# all 8 GEMM phases: tiles after the first skip the first two counted waits of their peeled first K-iteration (prefetches already landed behind the epilogue's full wait)
# baseline (speedup 1.0000x reference)
; #define PG8_STAGE(bufoff, gbase, voff) do { _Pragma("unroll") for (int _i = 0; _i < 2; ++_i) \
;         __builtin_amdgcn_global_load_lds((const unsigned*)((const char*)(gbase) + (voff)[_i]), (LAS unsigned*)(lds + (bufoff) + ldsw + _i * 8192), 16, 0, 0); } while (0)
; #define PG8_WAIT_V(n) asm volatile("s_waitcnt vmcnt(" #n ")" ::: "memory")
; #define PG8_BAR __builtin_amdgcn_s_barrier()
; template <class Epi, bool ALIGN_EPI>
; __device__ __forceinline__ void gemm_phase(LAS unsigned char* lds, const Gemm g, const StaticOrder& S, const Epi& E) {
;     ...
;     for (int i = 0; i < 2; ++i) { int R, C; stage_rc(tid * 16 + i * 8192, R, C); const int Rb = Epi::PERM ? ((R & ~31) + perm32(R & 31)) : R;
;         voffA[i] = (unsigned)(R * K + C) * 2u; voffB[i] = (unsigned)(Rb * K + C) * 2u; }
;     const size_t kstep = (size_t)(BK * 2);
;     const size_t hstep = (size_t)HALF * K * 2;
;     const size_t tstep = 2 * hstep;
;     const unsigned ldsw = (unsigned)wid * 1024u;
;     const int aoff = lds_byte(wr * 64 + fr, fq * 8), boff = lds_byte(wc * 32 + fr, fq * 8);
;     ...
;     const char* cA = (const char*)g.A + (size_t)cur.pm * tstep; const char* cB = (const char*)g.Bt + (size_t)cur.pn * tstep;
;     PG8_STAGE(PG8_SB(0, 0), cB, voffB); PG8_STAGE(PG8_SB(0, 1), cB + hstep, voffB); PG8_STAGE(PG8_SA(0, 0), cA, voffA); PG8_STAGE(PG8_SA(0, 1), cA + hstep, voffA);
;     if (wr == 1) PG8_BAR;
;     PG8_WAIT_V(2); PG8_BAR;
;     PG8_STAGE(PG8_SB(1, 0), cB + kstep, voffB); PG8_STAGE(PG8_SA(1, 0), cA + kstep, voffA); PG8_STAGE(PG8_SB(1, 1), cB + hstep + kstep, voffB);
;     PG8_WAIT_V(6); PG8_BAR;
;     for (;;) {
.LBB0_287:
	s_add_u32 s5, s28, 0x9a40000
	s_addc_u32 s90, s29, 0
	s_lshl_b32 s1, s1, 5
	s_mov_b64 s[62:63], 0x80
	s_and_b32 s1, s1, 0x60
	s_add_i32 m0, s76, 0x18000
	v_lshl_add_u64 v[8:9], v[8:9], 0, s[62:63]
	v_writelane_b32 v247, s5, 3
	s_ashr_i32 s91, s3, 31
	s_ashr_i32 s92, s2, 31
	s_lshl_b32 s5, s0, 13
	s_lshl_b32 s9, s1, 7
	s_waitcnt vmcnt(2)
	s_barrier
	global_load_lds_dwordx4 v[8:9], off
	v_lshl_add_u64 v[6:7], v[6:7], 0, s[62:63]
	s_add_i32 m0, s76, 0x1a000
	s_add_i32 s93, s76, 0x8000
	s_add_i32 s94, s76, 0xa000
	global_load_lds_dwordx4 v[6:7], off
	v_lshl_add_u64 v[2:3], v[2:3], 0, s[62:63]
	s_mov_b32 m0, s93
	s_add_u32 s64, s82, 0x40080
	global_load_lds_dwordx4 v[2:3], off
	v_lshl_add_u64 v[2:3], v[4:5], 0, s[62:63]
	s_mov_b32 m0, s94
	s_addc_u32 s65, s83, 0
	global_load_lds_dwordx4 v[2:3], off
	s_add_i32 m0, s76, 0x1c000
	v_lshl_add_u64 v[2:3], s[64:65], 0, v[132:133]
	global_load_lds_dwordx4 v[2:3], off
	v_lshl_add_u64 v[2:3], s[64:65], 0, v[136:137]
	s_add_i32 m0, s76, 0x1e000
	v_lshlrev_b32_e32 v4, 6, v1
	global_load_lds_dwordx4 v[2:3], off
	v_and_b32_e32 v2, 15, v1
	v_lshlrev_b32_e32 v3, 1, v13
	s_movk_i32 s50, 0x3c0
	v_and_or_b32 v4, v4, s50, v3
	v_and_b32_e32 v5, 32, v186
	v_lshl_or_b32 v188, s0, 6, v2
	v_lshl_or_b32 v2, v2, 6, v3
	v_lshlrev_b32_e32 v3, 8, v1
	v_bitop3_b32 v189, s9, v4, v5 bitop3:0xf6
	v_and_b32_e32 v3, 0x38000, v3
	v_lshlrev_b32_e32 v4, 11, v12
	v_or3_b32 v3, v10, v3, v4
	v_add_u32_e32 v140, v3, v11
	v_lshlrev_b32_e32 v3, 4, v14
	s_waitcnt vmcnt(6)
	s_cmpk_lt_u32 s8, 0x100
	v_and_b32_e32 v3, 0x78000, v3
	v_bitop3_b32 v2, v2, s5, v5 bitop3:0xde
	s_cselect_b64 s[64:65], -1, 0
	v_or_b32_e32 v190, s1, v13
	v_or3_b32 v3, v10, v3, v4
	s_add_i32 s95, 0, 0x10000
	s_add_i32 s96, 0, 0x14000
	v_or_b32_e32 v191, 0xfffff800, v190
	v_mov_b32_e32 v141, v139
	v_add_u32_e32 v142, v3, v11
	v_mov_b32_e32 v143, v139
	v_mov_b64_e32 v[144:145], 0x500
	v_mov_b64_e32 v[146:147], 0x4ff
	v_add_u32_e32 v192, s95, v189
	v_add_u32_e32 v193, s96, v189
	v_add_u32_e32 v194, 0, v2
	v_mov_b32_e32 v195, 0x358637bd
	s_mov_b32 s97, 0x800000
	s_barrier
	s_mov_b32 s98, 0
	s_branch .LBB0_290

; #define PG8_BAR __builtin_amdgcn_s_barrier()
; template <class Epi, bool ALIGN_EPI>
; __device__ __forceinline__ void gemm_phase(LAS unsigned char* lds, const Gemm g, const StaticOrder& S, const Epi& E) {
;     ...
;         if (!has_next) break;
; #pragma unroll
;         for (int a = 0; a < 2; ++a)
; #pragma unroll
;             for (int b = 0; b < 2; ++b)
; #pragma unroll
;                 for (int m = 0; m < 4; ++m)
; #pragma unroll
;                     for (int n = 0; n < 2; ++n) acc[a][b][m][n] = (f32x4){0.f, 0.f, 0.f, 0.f};
;         cur = nxt; cA = nA; cB = nB; ++ui;
;         if constexpr (ALIGN_EPI) { if (wr == 1) PG8_BAR; }
;     }
.LBB0_289:
	s_mov_b32 s98, 1
	s_andn2_b64 vcc, exec, s[0:1]
	s_mov_b32 s4, s66
	s_mov_b32 s78, s68
	s_mov_b64 s[82:83], s[72:73]
	s_mov_b64 s[80:81], s[70:71]
	s_cbranch_vccz .LBB0_335

; #define PG8_STAGE(bufoff, gbase, voff) do { _Pragma("unroll") for (int _i = 0; _i < 2; ++_i) \
;         __builtin_amdgcn_global_load_lds((const unsigned*)((const char*)(gbase) + (voff)[_i]), (LAS unsigned*)(lds + (bufoff) + ldsw + _i * 8192), 16, 0, 0); } while (0)
; #define PG8_LDA(dst, b, h) do { _Pragma("unroll") for (int m = 0; m < 4; ++m) _Pragma("unroll") for (int k = 0; k < 2; ++k) dst[m][k] = *(const LAS bf16x8*)(lds + PG8_SA(b, h) + aoff + m * 2048 + k * 1024); } while (0)
; #define PG8_LDB(dst, b, h) do { _Pragma("unroll") for (int n = 0; n < 2; ++n) _Pragma("unroll") for (int k = 0; k < 2; ++k) dst[n][k] = *(const LAS bf16x8*)(lds + PG8_SB(b, h) + boff + n * 2048 + k * 1024); } while (0)
; #define PG8_MMA(ai, bj, At, Bt) do { __builtin_amdgcn_s_setprio(3); _Pragma("unroll") for (int m = 0; m < 4; ++m) _Pragma("unroll") for (int n = 0; n < 2; ++n) _Pragma("unroll") for (int k = 0; k < 2; ++k) \
;         acc[ai][bj][m][n] = __builtin_amdgcn_mfma_f32_16x16x32_bf16(Bt[n][k], At[m][k], acc[ai][bj][m][n], 0, 0, 0); __builtin_amdgcn_s_setprio(0); } while (0)
; #define PG8_WAIT_V(n) asm volatile("s_waitcnt vmcnt(" #n ")" ::: "memory")
; #define PG8_WAIT_L(n) asm volatile("s_waitcnt lgkmcnt(" #n ")" ::: "memory")
; template <class Epi, bool ALIGN_EPI>
; __device__ __forceinline__ void gemm_phase(LAS unsigned char* lds, const Gemm g, const StaticOrder& S, const Epi& E) {
;     ...
;         const bool has_next = S.next(ui + 1, nxt);
;         const char* nA = has_next ? (const char*)g.A + (size_t)nxt.pm * tstep : cA; const char* nB = has_next ? (const char*)g.Bt + (size_t)nxt.pn * tstep : cB;
;         for (int t = 0; t < nt; t += 2) {
;             const bool last = (t == nt - 2);
;             const char* a1 = cA + (size_t)(t + 1) * kstep;
;             const char* a2 = last ? nA : cA + (size_t)(t + 2) * kstep; const char* b2 = last ? nB : cB + (size_t)(t + 2) * kstep;
;             const char* a3 = a2 + kstep; const char* b3 = b2 + kstep;
;             PG8_LDB(B0, 0, 0); PG8_LDB(B1, 0, 1); PG8_SCHED; PG8_LDA(At, 0, 0); PG8_STAGE(PG8_SA(1, 1), a1 + hstep, voffA);
;             PG8_WAIT_V(8); PG8_WAIT_L(0); PG8_BAR; PG8_MMA(0, 0, At, B0); PG8_MMA(0, 1, At, B1); PG8_BAR; PG8_SCHED;
;             PG8_LDA(At, 0, 1); PG8_STAGE(PG8_SB(0, 0), b2, voffB); PG8_STAGE(PG8_SB(0, 1), b2 + hstep, voffB); PG8_STAGE(PG8_SA(0, 0), a2, voffA);
.LBB0_292:
	s_ashr_i32 s69, s68, 31
	s_lshl_b64 s[8:9], s[68:69], 19
	s_add_u32 s70, s34, s8
	s_addc_u32 s71, s35, s9
	s_and_b64 s[8:9], s[0:1], exec
	s_cselect_b32 s5, s71, s81
	s_cselect_b32 s69, s70, s80
	s_ashr_i32 s67, s66, 31
	s_lshl_b64 s[8:9], s[66:67], 19
	s_add_u32 s72, s26, s8
	s_addc_u32 s73, s27, s9
	s_and_b64 s[8:9], s[0:1], exec
	s_cselect_b32 s67, s73, s83
	s_cselect_b32 s79, s72, s82
	s_add_u32 s80, s80, 0x40080
	s_addc_u32 s81, s81, 0
	s_add_u32 vcc_lo, s82, 0x100
	s_addc_u32 vcc_hi, s83, 0
	s_mov_b32 s8, -2
	ds_read_b128 v[148:151], v192
	ds_read_b128 v[152:155], v192 offset:1024
	ds_read_b128 v[156:159], v192 offset:2048
	ds_read_b128 v[160:163], v192 offset:3072
	ds_read_b128 v[164:167], v193
	ds_read_b128 v[168:171], v193 offset:1024
	ds_read_b128 v[172:175], v193 offset:2048
	ds_read_b128 v[176:179], v193 offset:3072
	s_add_u32 s9, s80, 0xfffc0080
	s_addc_u32 s50, s81, -1
	s_cmp_eq_u32 s8, 12
	s_cselect_b32 s85, s5, s50
	s_cselect_b32 s84, s69, s9
	s_cselect_b32 s83, s67, vcc_hi
	s_cselect_b32 s82, s79, vcc_lo
	v_lshl_add_u64 v[224:225], s[80:81], 0, v[140:141]
	s_add_i32 m0, s76, 0xc000
	ds_read_b128 v[180:183], v194
	ds_read_b128 v[196:199], v194 offset:1024
	ds_read_b128 v[200:203], v194 offset:2048
	ds_read_b128 v[204:207], v194 offset:3072
	ds_read_b128 v[208:211], v194 offset:4096
	ds_read_b128 v[212:215], v194 offset:5120
	ds_read_b128 v[216:219], v194 offset:6144
	ds_read_b128 v[220:223], v194 offset:7168
	global_load_lds_dwordx4 v[224:225], off
	v_lshl_add_u64 v[224:225], s[80:81], 0, v[142:143]
	s_add_i32 m0, s76, 0xe000
	s_nop 0
	global_load_lds_dwordx4 v[224:225], off
	s_cmp_lg_u32 s98, 0
	s_cbranch_scc1 .Lmy_rw_293_0
	s_waitcnt vmcnt(8)
.Lmy_rw_293_0:
	s_waitcnt lgkmcnt(0)
	s_barrier
	s_setprio 3
	s_waitcnt lgkmcnt(0)
	v_mfma_f32_16x16x32_bf16 v[118:121], v[148:151], v[180:183], 0
	v_mfma_f32_16x16x32_bf16 v[114:117], v[156:159], v[180:183], 0
	v_mfma_f32_16x16x32_bf16 v[102:105], v[148:151], v[200:203], 0
	v_mfma_f32_16x16x32_bf16 v[98:101], v[156:159], v[200:203], 0
	v_mfma_f32_16x16x32_bf16 v[86:89], v[148:151], v[208:211], 0
	v_mfma_f32_16x16x32_bf16 v[82:85], v[156:159], v[208:211], 0
	v_mfma_f32_16x16x32_bf16 v[70:73], v[148:151], v[216:219], 0
	v_mfma_f32_16x16x32_bf16 v[66:69], v[156:159], v[216:219], 0
	v_mfma_f32_16x16x32_bf16 v[118:121], v[152:155], v[196:199], v[118:121]
	v_mfma_f32_16x16x32_bf16 v[114:117], v[160:163], v[196:199], v[114:117]
	v_mfma_f32_16x16x32_bf16 v[102:105], v[152:155], v[204:207], v[102:105]
	v_mfma_f32_16x16x32_bf16 v[98:101], v[160:163], v[204:207], v[98:101]
	v_mfma_f32_16x16x32_bf16 v[86:89], v[152:155], v[212:215], v[86:89]
	v_mfma_f32_16x16x32_bf16 v[82:85], v[160:163], v[212:215], v[82:85]
	v_mfma_f32_16x16x32_bf16 v[70:73], v[152:155], v[220:223], v[70:73]
	v_mfma_f32_16x16x32_bf16 v[66:69], v[160:163], v[220:223], v[66:69]
	v_mfma_f32_16x16x32_bf16 v[126:129], v[164:167], v[180:183], 0
	v_mfma_f32_16x16x32_bf16 v[122:125], v[172:175], v[180:183], 0
	v_mfma_f32_16x16x32_bf16 v[110:113], v[164:167], v[200:203], 0
	v_mfma_f32_16x16x32_bf16 v[106:109], v[172:175], v[200:203], 0
	v_mfma_f32_16x16x32_bf16 v[94:97], v[164:167], v[208:211], 0
	v_mfma_f32_16x16x32_bf16 v[90:93], v[172:175], v[208:211], 0
	v_mfma_f32_16x16x32_bf16 v[78:81], v[164:167], v[216:219], 0
	v_mfma_f32_16x16x32_bf16 v[74:77], v[172:175], v[216:219], 0
	v_mfma_f32_16x16x32_bf16 v[126:129], v[168:171], v[196:199], v[126:129]
	v_mfma_f32_16x16x32_bf16 v[122:125], v[176:179], v[196:199], v[122:125]
	v_mfma_f32_16x16x32_bf16 v[110:113], v[168:171], v[204:207], v[110:113]
	v_mfma_f32_16x16x32_bf16 v[106:109], v[176:179], v[204:207], v[106:109]
	v_mfma_f32_16x16x32_bf16 v[94:97], v[168:171], v[212:215], v[94:97]
	v_mfma_f32_16x16x32_bf16 v[90:93], v[176:179], v[212:215], v[90:93]
	v_mfma_f32_16x16x32_bf16 v[78:81], v[168:171], v[220:223], v[78:81]
	v_mfma_f32_16x16x32_bf16 v[74:77], v[176:179], v[220:223], v[74:77]
	s_setprio 0
	s_barrier
	s_add_i32 s9, s95, s33
	v_lshl_add_u64 v[224:225], s[82:83], 0, v[132:133]
	s_mov_b32 m0, s9
	ds_read_b128 v[180:183], v194 offset:16384
	ds_read_b128 v[196:199], v194 offset:17408
	ds_read_b128 v[200:203], v194 offset:18432
	ds_read_b128 v[204:207], v194 offset:19456
	ds_read_b128 v[208:211], v194 offset:20480
	ds_read_b128 v[212:215], v194 offset:21504
	ds_read_b128 v[216:219], v194 offset:22528
	ds_read_b128 v[220:223], v194 offset:23552
	global_load_lds_dwordx4 v[224:225], off
	s_add_i32 m0, s9, 0x2000
	s_add_u32 s50, s82, 0x40000
	v_lshl_add_u64 v[226:227], s[82:83], 0, v[136:137]
	s_addc_u32 s51, s83, 0
	s_add_i32 s9, s96, s33
	global_load_lds_dwordx4 v[226:227], off
	v_lshl_add_u64 v[228:229], s[50:51], 0, v[132:133]
	s_mov_b32 m0, s9
	v_lshl_add_u64 v[230:231], s[84:85], 0, v[134:135]
	global_load_lds_dwordx4 v[228:229], off
	v_lshl_add_u64 v[228:229], s[50:51], 0, v[136:137]
	s_add_i32 m0, s9, 0x2000
	s_nop 0
	global_load_lds_dwordx4 v[228:229], off
	v_lshl_add_u64 v[228:229], s[84:85], 0, v[130:131]
	s_mov_b32 m0, s76
	s_nop 0
	global_load_lds_dwordx4 v[228:229], off
	s_mov_b32 m0, s77
	s_nop 0
	global_load_lds_dwordx4 v[230:231], off
	s_cmp_lg_u32 s98, 0
	s_cbranch_scc1 .Lmy_rw_293_1
	s_waitcnt vmcnt(8)
; #define PG8_STAGE(bufoff, gbase, voff) do { _Pragma("unroll") for (int _i = 0; _i < 2; ++_i) \
;         __builtin_amdgcn_global_load_lds((const unsigned*)((const char*)(gbase) + (voff)[_i]), (LAS unsigned*)(lds + (bufoff) + ldsw + _i * 8192), 16, 0, 0); } while (0)
; #define PG8_LDA(dst, b, h) do { _Pragma("unroll") for (int m = 0; m < 4; ++m) _Pragma("unroll") for (int k = 0; k < 2; ++k) dst[m][k] = *(const LAS bf16x8*)(lds + PG8_SA(b, h) + aoff + m * 2048 + k * 1024); } while (0)
; #define PG8_LDB(dst, b, h) do { _Pragma("unroll") for (int n = 0; n < 2; ++n) _Pragma("unroll") for (int k = 0; k < 2; ++k) dst[n][k] = *(const LAS bf16x8*)(lds + PG8_SB(b, h) + boff + n * 2048 + k * 1024); } while (0)
; #define PG8_MMA(ai, bj, At, Bt) do { __builtin_amdgcn_s_setprio(3); _Pragma("unroll") for (int m = 0; m < 4; ++m) _Pragma("unroll") for (int n = 0; n < 2; ++n) _Pragma("unroll") for (int k = 0; k < 2; ++k) \
;         acc[ai][bj][m][n] = __builtin_amdgcn_mfma_f32_16x16x32_bf16(Bt[n][k], At[m][k], acc[ai][bj][m][n], 0, 0, 0); __builtin_amdgcn_s_setprio(0); } while (0)
; #define PG8_WAIT_V(n) asm volatile("s_waitcnt vmcnt(" #n ")" ::: "memory")
; #define PG8_WAIT_L(n) asm volatile("s_waitcnt lgkmcnt(" #n ")" ::: "memory")
; #define PG8_BAR __builtin_amdgcn_s_barrier()
; #define PG8_SCHED __builtin_amdgcn_sched_barrier(0)
; template <class Epi, bool ALIGN_EPI>
; __device__ __forceinline__ void gemm_phase(LAS unsigned char* lds, const Gemm g, const StaticOrder& S, const Epi& E) {
;     ...
;             PG8_WAIT_V(8); PG8_WAIT_L(0); PG8_BAR; PG8_MMA(1, 0, At, B0); PG8_MMA(1, 1, At, B1); PG8_BAR; PG8_SCHED;
;             PG8_LDB(B0, 1, 0); PG8_LDB(B1, 1, 1); PG8_SCHED; PG8_LDA(At, 1, 0); PG8_STAGE(PG8_SA(0, 1), a2 + hstep, voffA);
;             PG8_WAIT_V(8); PG8_WAIT_L(0); PG8_BAR; PG8_MMA(0, 0, At, B0); PG8_MMA(0, 1, At, B1); PG8_BAR; PG8_SCHED;
.Lmy_rw_293_1:
	s_waitcnt lgkmcnt(0)
	s_barrier
	s_setprio 3
	s_waitcnt lgkmcnt(0)
	v_mfma_f32_16x16x32_bf16 v[54:57], v[148:151], v[180:183], 0
	v_mfma_f32_16x16x32_bf16 v[50:53], v[156:159], v[180:183], 0
	v_mfma_f32_16x16x32_bf16 v[38:41], v[148:151], v[200:203], 0
	v_mfma_f32_16x16x32_bf16 v[34:37], v[156:159], v[200:203], 0
	v_mfma_f32_16x16x32_bf16 v[22:25], v[148:151], v[208:211], 0
	v_mfma_f32_16x16x32_bf16 v[18:21], v[156:159], v[208:211], 0
	v_mfma_f32_16x16x32_bf16 v[6:9], v[148:151], v[216:219], 0
	v_mfma_f32_16x16x32_bf16 v[2:5], v[156:159], v[216:219], 0
	v_mfma_f32_16x16x32_bf16 v[54:57], v[152:155], v[196:199], v[54:57]
	v_mfma_f32_16x16x32_bf16 v[50:53], v[160:163], v[196:199], v[50:53]
	v_mfma_f32_16x16x32_bf16 v[38:41], v[152:155], v[204:207], v[38:41]
	v_mfma_f32_16x16x32_bf16 v[34:37], v[160:163], v[204:207], v[34:37]
	v_mfma_f32_16x16x32_bf16 v[22:25], v[152:155], v[212:215], v[22:25]
	v_mfma_f32_16x16x32_bf16 v[18:21], v[160:163], v[212:215], v[18:21]
	v_mfma_f32_16x16x32_bf16 v[6:9], v[152:155], v[220:223], v[6:9]
	v_mfma_f32_16x16x32_bf16 v[2:5], v[160:163], v[220:223], v[2:5]
	v_mfma_f32_16x16x32_bf16 v[62:65], v[164:167], v[180:183], 0
	v_mfma_f32_16x16x32_bf16 v[58:61], v[172:175], v[180:183], 0
	v_mfma_f32_16x16x32_bf16 v[46:49], v[164:167], v[200:203], 0
	v_mfma_f32_16x16x32_bf16 v[42:45], v[172:175], v[200:203], 0
	v_mfma_f32_16x16x32_bf16 v[30:33], v[164:167], v[208:211], 0
	v_mfma_f32_16x16x32_bf16 v[26:29], v[172:175], v[208:211], 0
	v_mfma_f32_16x16x32_bf16 v[14:17], v[164:167], v[216:219], 0
	v_mfma_f32_16x16x32_bf16 v[10:13], v[172:175], v[216:219], 0
	v_mfma_f32_16x16x32_bf16 v[62:65], v[168:171], v[196:199], v[62:65]
	v_mfma_f32_16x16x32_bf16 v[58:61], v[176:179], v[196:199], v[58:61]
	v_mfma_f32_16x16x32_bf16 v[46:49], v[168:171], v[204:207], v[46:49]
	v_mfma_f32_16x16x32_bf16 v[42:45], v[176:179], v[204:207], v[42:45]
	v_mfma_f32_16x16x32_bf16 v[30:33], v[168:171], v[212:215], v[30:33]
	v_mfma_f32_16x16x32_bf16 v[26:29], v[176:179], v[212:215], v[26:29]
	v_mfma_f32_16x16x32_bf16 v[14:17], v[168:171], v[220:223], v[14:17]
	v_mfma_f32_16x16x32_bf16 v[10:13], v[176:179], v[220:223], v[10:13]
	s_setprio 0
	s_barrier
	s_add_i32 s9, 0, 0x18000
	v_add_u32_e32 v138, s9, v189
	s_add_i32 s89, 0, 0x1c000
	ds_read_b128 v[148:151], v138
	ds_read_b128 v[152:155], v138 offset:1024
	ds_read_b128 v[156:159], v138 offset:2048
	ds_read_b128 v[160:163], v138 offset:3072
	v_add_u32_e32 v138, s89, v189
	ds_read_b128 v[164:167], v138
	ds_read_b128 v[168:171], v138 offset:1024
	ds_read_b128 v[172:175], v138 offset:2048
	ds_read_b128 v[176:179], v138 offset:3072
	s_add_u32 s50, s84, 0x40000
	s_addc_u32 s51, s85, 0
	s_mov_b32 m0, s86
	v_lshl_add_u64 v[232:233], s[50:51], 0, v[130:131]
	ds_read_b128 v[180:183], v194 offset:32768
	ds_read_b128 v[196:199], v194 offset:33792
	ds_read_b128 v[200:203], v194 offset:34816
	ds_read_b128 v[204:207], v194 offset:35840
	ds_read_b128 v[208:211], v194 offset:36864
	ds_read_b128 v[212:215], v194 offset:37888
	ds_read_b128 v[216:219], v194 offset:38912
	ds_read_b128 v[220:223], v194 offset:39936
	global_load_lds_dwordx4 v[232:233], off
	v_lshl_add_u64 v[232:233], s[50:51], 0, v[134:135]
	s_mov_b32 m0, s87
	s_nop 0
	global_load_lds_dwordx4 v[232:233], off
	s_waitcnt vmcnt(8)
	s_waitcnt lgkmcnt(0)
	s_barrier
	s_setprio 3
	s_waitcnt lgkmcnt(0)
	v_mfma_f32_16x16x32_bf16 v[118:121], v[148:151], v[180:183], v[118:121]
	v_mfma_f32_16x16x32_bf16 v[114:117], v[156:159], v[180:183], v[114:117]
	v_mfma_f32_16x16x32_bf16 v[102:105], v[148:151], v[200:203], v[102:105]
	v_mfma_f32_16x16x32_bf16 v[98:101], v[156:159], v[200:203], v[98:101]
	v_mfma_f32_16x16x32_bf16 v[86:89], v[148:151], v[208:211], v[86:89]
	v_mfma_f32_16x16x32_bf16 v[82:85], v[156:159], v[208:211], v[82:85]
	v_mfma_f32_16x16x32_bf16 v[70:73], v[148:151], v[216:219], v[70:73]
	v_mfma_f32_16x16x32_bf16 v[66:69], v[156:159], v[216:219], v[66:69]
	v_mfma_f32_16x16x32_bf16 v[118:121], v[152:155], v[196:199], v[118:121]
	v_mfma_f32_16x16x32_bf16 v[114:117], v[160:163], v[196:199], v[114:117]
	v_mfma_f32_16x16x32_bf16 v[102:105], v[152:155], v[204:207], v[102:105]
	v_mfma_f32_16x16x32_bf16 v[98:101], v[160:163], v[204:207], v[98:101]
	v_mfma_f32_16x16x32_bf16 v[86:89], v[152:155], v[212:215], v[86:89]
	v_mfma_f32_16x16x32_bf16 v[82:85], v[160:163], v[212:215], v[82:85]
	v_mfma_f32_16x16x32_bf16 v[70:73], v[152:155], v[220:223], v[70:73]
	v_mfma_f32_16x16x32_bf16 v[66:69], v[160:163], v[220:223], v[66:69]
	v_mfma_f32_16x16x32_bf16 v[126:129], v[164:167], v[180:183], v[126:129]
	v_mfma_f32_16x16x32_bf16 v[122:125], v[172:175], v[180:183], v[122:125]
	v_mfma_f32_16x16x32_bf16 v[110:113], v[164:167], v[200:203], v[110:113]
	v_mfma_f32_16x16x32_bf16 v[106:109], v[172:175], v[200:203], v[106:109]
	v_mfma_f32_16x16x32_bf16 v[94:97], v[164:167], v[208:211], v[94:97]
	v_mfma_f32_16x16x32_bf16 v[90:93], v[172:175], v[208:211], v[90:93]
	v_mfma_f32_16x16x32_bf16 v[78:81], v[164:167], v[216:219], v[78:81]
	v_mfma_f32_16x16x32_bf16 v[74:77], v[172:175], v[216:219], v[74:77]
	v_mfma_f32_16x16x32_bf16 v[126:129], v[168:171], v[196:199], v[126:129]
	v_mfma_f32_16x16x32_bf16 v[122:125], v[176:179], v[196:199], v[122:125]
	v_mfma_f32_16x16x32_bf16 v[110:113], v[168:171], v[204:207], v[110:113]
	v_mfma_f32_16x16x32_bf16 v[106:109], v[176:179], v[204:207], v[106:109]
	v_mfma_f32_16x16x32_bf16 v[94:97], v[168:171], v[212:215], v[94:97]
	v_mfma_f32_16x16x32_bf16 v[90:93], v[176:179], v[212:215], v[90:93]
	v_mfma_f32_16x16x32_bf16 v[78:81], v[168:171], v[220:223], v[78:81]
	v_mfma_f32_16x16x32_bf16 v[74:77], v[176:179], v[220:223], v[74:77]
	s_setprio 0
	s_barrier
; #define PG8_STAGE(bufoff, gbase, voff) do { _Pragma("unroll") for (int _i = 0; _i < 2; ++_i) \
;         __builtin_amdgcn_global_load_lds((const unsigned*)((const char*)(gbase) + (voff)[_i]), (LAS unsigned*)(lds + (bufoff) + ldsw + _i * 8192), 16, 0, 0); } while (0)
; #define PG8_LDA(dst, b, h) do { _Pragma("unroll") for (int m = 0; m < 4; ++m) _Pragma("unroll") for (int k = 0; k < 2; ++k) dst[m][k] = *(const LAS bf16x8*)(lds + PG8_SA(b, h) + aoff + m * 2048 + k * 1024); } while (0)
; #define PG8_MMA(ai, bj, At, Bt) do { __builtin_amdgcn_s_setprio(3); _Pragma("unroll") for (int m = 0; m < 4; ++m) _Pragma("unroll") for (int n = 0; n < 2; ++n) _Pragma("unroll") for (int k = 0; k < 2; ++k) \
;         acc[ai][bj][m][n] = __builtin_amdgcn_mfma_f32_16x16x32_bf16(Bt[n][k], At[m][k], acc[ai][bj][m][n], 0, 0, 0); __builtin_amdgcn_s_setprio(0); } while (0)
; #define PG8_WAIT_V(n) asm volatile("s_waitcnt vmcnt(" #n ")" ::: "memory")
; #define PG8_WAIT_L(n) asm volatile("s_waitcnt lgkmcnt(" #n ")" ::: "memory")
; #define PG8_BAR __builtin_amdgcn_s_barrier()
; #define PG8_SCHED __builtin_amdgcn_sched_barrier(0)
; template <class Epi, bool ALIGN_EPI>
; __device__ __forceinline__ void gemm_phase(LAS unsigned char* lds, const Gemm g, const StaticOrder& S, const Epi& E) {
;     ...
;             PG8_LDA(At, 1, 1); PG8_STAGE(PG8_SB(1, 0), b3, voffB); PG8_STAGE(PG8_SB(1, 1), b3 + hstep, voffB); PG8_STAGE(PG8_SA(1, 0), a3, voffA);
;             PG8_WAIT_V(8); PG8_WAIT_L(0); PG8_BAR; PG8_MMA(1, 0, At, B0); PG8_MMA(1, 1, At, B1); PG8_BAR; PG8_SCHED;
	s_add_i32 s9, s9, s33
	v_lshl_add_u64 v[224:225], v[224:225], 0, s[62:63]
	s_mov_b32 m0, s9
	ds_read_b128 v[180:183], v194 offset:49152
	ds_read_b128 v[196:199], v194 offset:50176
	ds_read_b128 v[200:203], v194 offset:51200
	ds_read_b128 v[204:207], v194 offset:52224
	ds_read_b128 v[208:211], v194 offset:53248
	ds_read_b128 v[212:215], v194 offset:54272
	ds_read_b128 v[216:219], v194 offset:55296
	ds_read_b128 v[220:223], v194 offset:56320
	global_load_lds_dwordx4 v[224:225], off
	s_add_i32 m0, s9, 0x2000
	s_add_u32 s50, s82, 0x40080
	v_lshl_add_u64 v[224:225], v[226:227], 0, s[62:63]
	s_addc_u32 s51, s83, 0
	s_add_i32 s9, s89, s33
	global_load_lds_dwordx4 v[224:225], off
	v_lshl_add_u64 v[224:225], s[50:51], 0, v[132:133]
	s_mov_b32 m0, s9
	s_nop 0
	global_load_lds_dwordx4 v[224:225], off
	v_lshl_add_u64 v[224:225], s[50:51], 0, v[136:137]
	s_add_i32 m0, s9, 0x2000
	s_nop 0
	global_load_lds_dwordx4 v[224:225], off
	v_lshl_add_u64 v[224:225], v[228:229], 0, s[62:63]
	s_mov_b32 m0, s93
	s_nop 0
	global_load_lds_dwordx4 v[224:225], off
	v_lshl_add_u64 v[224:225], v[230:231], 0, s[62:63]
	s_mov_b32 m0, s94
	s_nop 0
	global_load_lds_dwordx4 v[224:225], off
	s_waitcnt vmcnt(8)
	s_waitcnt lgkmcnt(0)
	s_barrier
	s_setprio 3
	s_waitcnt lgkmcnt(0)
	v_mfma_f32_16x16x32_bf16 v[54:57], v[148:151], v[180:183], v[54:57]
	v_mfma_f32_16x16x32_bf16 v[50:53], v[156:159], v[180:183], v[50:53]
	v_mfma_f32_16x16x32_bf16 v[38:41], v[148:151], v[200:203], v[38:41]
	v_mfma_f32_16x16x32_bf16 v[34:37], v[156:159], v[200:203], v[34:37]
	v_mfma_f32_16x16x32_bf16 v[22:25], v[148:151], v[208:211], v[22:25]
	v_mfma_f32_16x16x32_bf16 v[18:21], v[156:159], v[208:211], v[18:21]
	v_mfma_f32_16x16x32_bf16 v[6:9], v[148:151], v[216:219], v[6:9]
	v_mfma_f32_16x16x32_bf16 v[2:5], v[156:159], v[216:219], v[2:5]
	v_mfma_f32_16x16x32_bf16 v[54:57], v[152:155], v[196:199], v[54:57]
	v_mfma_f32_16x16x32_bf16 v[50:53], v[160:163], v[196:199], v[50:53]
	v_mfma_f32_16x16x32_bf16 v[38:41], v[152:155], v[204:207], v[38:41]
	v_mfma_f32_16x16x32_bf16 v[34:37], v[160:163], v[204:207], v[34:37]
	v_mfma_f32_16x16x32_bf16 v[22:25], v[152:155], v[212:215], v[22:25]
	v_mfma_f32_16x16x32_bf16 v[18:21], v[160:163], v[212:215], v[18:21]
	v_mfma_f32_16x16x32_bf16 v[6:9], v[152:155], v[220:223], v[6:9]
	v_mfma_f32_16x16x32_bf16 v[2:5], v[160:163], v[220:223], v[2:5]
	v_mfma_f32_16x16x32_bf16 v[62:65], v[164:167], v[180:183], v[62:65]
	v_mfma_f32_16x16x32_bf16 v[58:61], v[172:175], v[180:183], v[58:61]
	v_mfma_f32_16x16x32_bf16 v[46:49], v[164:167], v[200:203], v[46:49]
	v_mfma_f32_16x16x32_bf16 v[42:45], v[172:175], v[200:203], v[42:45]
	v_mfma_f32_16x16x32_bf16 v[30:33], v[164:167], v[208:211], v[30:33]
	v_mfma_f32_16x16x32_bf16 v[26:29], v[172:175], v[208:211], v[26:29]
	v_mfma_f32_16x16x32_bf16 v[14:17], v[164:167], v[216:219], v[14:17]
	v_mfma_f32_16x16x32_bf16 v[10:13], v[172:175], v[216:219], v[10:13]
	v_mfma_f32_16x16x32_bf16 v[62:65], v[168:171], v[196:199], v[62:65]
	v_mfma_f32_16x16x32_bf16 v[58:61], v[176:179], v[196:199], v[58:61]
	v_mfma_f32_16x16x32_bf16 v[46:49], v[168:171], v[204:207], v[46:49]
	v_mfma_f32_16x16x32_bf16 v[42:45], v[176:179], v[204:207], v[42:45]
	v_mfma_f32_16x16x32_bf16 v[30:33], v[168:171], v[212:215], v[30:33]
	v_mfma_f32_16x16x32_bf16 v[26:29], v[176:179], v[212:215], v[26:29]
	v_mfma_f32_16x16x32_bf16 v[14:17], v[168:171], v[220:223], v[14:17]
	v_mfma_f32_16x16x32_bf16 v[10:13], v[176:179], v[220:223], v[10:13]
	s_setprio 0
	s_barrier
	s_add_i32 s8, s8, 2
	s_add_u32 s80, s80, 0x100
	s_addc_u32 s81, s81, 0
	s_add_u32 vcc_lo, vcc_lo, 0x100
	s_addc_u32 vcc_hi, vcc_hi, 0

; #define PG8_STAGE(bufoff, gbase, voff) do { _Pragma("unroll") for (int _i = 0; _i < 2; ++_i) \
;         __builtin_amdgcn_global_load_lds((const unsigned*)((const char*)(gbase) + (voff)[_i]), (LAS unsigned*)(lds + (bufoff) + ldsw + _i * 8192), 16, 0, 0); } while (0)
; #define PG8_WAIT_V(n) asm volatile("s_waitcnt vmcnt(" #n ")" ::: "memory")
; #define PG8_BAR __builtin_amdgcn_s_barrier()
; template <class Epi, bool ALIGN_EPI>
; __device__ __forceinline__ void gemm_phase(LAS unsigned char* lds, const Gemm g, const StaticOrder& S, const Epi& E) {
;     ...
;     const int aoff = lds_byte(wr * 64 + fr, fq * 8), boff = lds_byte(wc * 32 + fr, fq * 8);
;     ...
;     Unit cur, nxt; int ui = 0;
;     if (!S.next(0, cur)) return;
;     f32x4 acc[2][2][4][2];
; #pragma unroll
;     for (int a = 0; a < 2; ++a)
; #pragma unroll
;         for (int b = 0; b < 2; ++b)
; #pragma unroll
;             for (int m = 0; m < 4; ++m)
; #pragma unroll
;                 for (int n = 0; n < 2; ++n) acc[a][b][m][n] = (f32x4){0.f, 0.f, 0.f, 0.f};
;     bf16x8 At[4][2], B0[2][2], B1[2][2];
;     const char* cA = (const char*)g.A + (size_t)cur.pm * tstep; const char* cB = (const char*)g.Bt + (size_t)cur.pn * tstep;
;     PG8_STAGE(PG8_SB(0, 0), cB, voffB); PG8_STAGE(PG8_SB(0, 1), cB + hstep, voffB); PG8_STAGE(PG8_SA(0, 0), cA, voffA); PG8_STAGE(PG8_SA(0, 1), cA + hstep, voffA);
;     if (wr == 1) PG8_BAR;
;     PG8_WAIT_V(2); PG8_BAR;
;     PG8_STAGE(PG8_SB(1, 0), cB + kstep, voffB); PG8_STAGE(PG8_SA(1, 0), cA + kstep, voffA); PG8_STAGE(PG8_SB(1, 1), cB + hstep + kstep, voffB);
;     PG8_WAIT_V(6); PG8_BAR;
;     for (;;) {
;         const bool has_next = S.next(ui + 1, nxt);
.LBB0_510:
	s_lshl_b32 s0, s0, 5
	s_mov_b64 s[18:19], 0x80
	s_and_b32 s52, s0, 0x60
	s_add_i32 m0, s63, 0x18000
	v_lshl_add_u64 v[8:9], v[8:9], 0, s[18:19]
	s_ashr_i32 s76, s3, 31
	s_ashr_i32 s77, s2, 31
	s_lshl_b32 s50, s5, 13
	s_lshl_b32 s51, s52, 7
	s_waitcnt vmcnt(2)
	s_barrier
	global_load_lds_dwordx4 v[8:9], off
	v_lshl_add_u64 v[6:7], v[6:7], 0, s[18:19]
	s_add_i32 m0, s63, 0x1a000
	s_add_i32 s78, s63, 0x8000
	s_add_i32 s79, s63, 0xa000
	global_load_lds_dwordx4 v[6:7], off
	v_lshl_add_u64 v[2:3], v[2:3], 0, s[18:19]
	s_mov_b32 m0, s78
	s_add_u32 s0, s66, 0x40080
	global_load_lds_dwordx4 v[2:3], off
	v_lshl_add_u64 v[2:3], v[4:5], 0, s[18:19]
	s_mov_b32 m0, s79
	s_addc_u32 s1, s67, 0
	global_load_lds_dwordx4 v[2:3], off
	s_add_i32 m0, s63, 0x1c000
	v_lshl_add_u64 v[2:3], s[0:1], 0, v[180:181]
	global_load_lds_dwordx4 v[2:3], off
	v_lshl_add_u64 v[2:3], s[0:1], 0, v[184:185]
	s_add_i32 m0, s63, 0x1e000
	v_lshlrev_b32_e32 v4, 6, v206
	global_load_lds_dwordx4 v[2:3], off
	v_and_b32_e32 v2, 3, v1
	v_lshlrev_b32_e32 v3, 4, v2
	s_movk_i32 s0, 0x3c0
	v_and_or_b32 v4, v4, s0, v3
	v_and_b32_e32 v5, 32, v209
	v_cmp_eq_u32_e64 s[0:1], 0, v2
	v_lshl_or_b32 v213, v2, 3, s52
	v_lshlrev_b32_e32 v2, 8, v206
	v_bitop3_b32 v212, s51, v4, v5 bitop3:0xf6
	v_and_b32_e32 v2, 0x38000, v2
	v_lshlrev_b32_e32 v4, 11, v12
	v_or3_b32 v2, v10, v2, v4
	v_add_u32_e32 v186, v2, v11
	v_lshlrev_b32_e32 v2, 4, v13
	v_lshlrev_b32_e32 v6, 2, v208
	v_and_b32_e32 v2, 0x78000, v2
	v_lshl_or_b32 v3, v208, 6, v3
	v_and_b32_e32 v6, 32, v6
	s_waitcnt vmcnt(6)
	s_cmpk_lt_u32 s4, 0x100
	v_or3_b32 v2, v10, v2, v4
	v_bitop3_b32 v3, v3, s50, v6 bitop3:0xde
	s_cselect_b64 s[50:51], -1, 0
	v_add_u32_e32 v188, v2, v11
	s_add_i32 s80, 0, 0x10000
	s_add_i32 s81, 0, 0x14000
	v_mbcnt_lo_u32_b32 v2, -1, 0
	v_lshl_or_b32 v211, s5, 6, v208
	v_mov_b32_e32 v187, v181
	v_mov_b32_e32 v189, v181
	v_mov_b64_e32 v[190:191], 0x200
	v_mov_b64_e32 v[192:193], 0x1ff
	v_add_u32_e32 v214, s80, v212
	v_add_u32_e32 v215, s81, v212
	v_add_u32_e32 v216, 0, v3
	v_mbcnt_hi_u32_b32 v217, -1, v2
	s_barrier
	s_mov_b32 s98, 0
	s_branch .LBB0_513

; #define PG8_BAR __builtin_amdgcn_s_barrier()
; template <class Epi, bool ALIGN_EPI>
; __device__ __forceinline__ void gemm_phase(LAS unsigned char* lds, const Gemm g, const StaticOrder& S, const Epi& E) {
;     ...
;         if (!has_next) break;
; #pragma unroll
;         for (int a = 0; a < 2; ++a)
; #pragma unroll
;             for (int b = 0; b < 2; ++b)
; #pragma unroll
;                 for (int m = 0; m < 4; ++m)
; #pragma unroll
;                     for (int n = 0; n < 2; ++n) acc[a][b][m][n] = (f32x4){0.f, 0.f, 0.f, 0.f};
;         cur = nxt; cA = nA; cB = nB; ++ui;
;         if constexpr (ALIGN_EPI) { if (wr == 1) PG8_BAR; }
;     }
.LBB0_512:
	s_mov_b32 s98, 1
	s_andn2_b64 vcc, exec, s[4:5]
	s_mov_b32 s62, s52
	s_mov_b32 s60, s54
	s_mov_b64 s[66:67], s[58:59]
	s_mov_b64 s[64:65], s[56:57]
	s_cbranch_vccz .LBB0_542

; #define PG8_STAGE(bufoff, gbase, voff) do { _Pragma("unroll") for (int _i = 0; _i < 2; ++_i) \
;         __builtin_amdgcn_global_load_lds((const unsigned*)((const char*)(gbase) + (voff)[_i]), (LAS unsigned*)(lds + (bufoff) + ldsw + _i * 8192), 16, 0, 0); } while (0)
; #define PG8_LDA(dst, b, h) do { _Pragma("unroll") for (int m = 0; m < 4; ++m) _Pragma("unroll") for (int k = 0; k < 2; ++k) dst[m][k] = *(const LAS bf16x8*)(lds + PG8_SA(b, h) + aoff + m * 2048 + k * 1024); } while (0)
; #define PG8_LDB(dst, b, h) do { _Pragma("unroll") for (int n = 0; n < 2; ++n) _Pragma("unroll") for (int k = 0; k < 2; ++k) dst[n][k] = *(const LAS bf16x8*)(lds + PG8_SB(b, h) + boff + n * 2048 + k * 1024); } while (0)
; #define PG8_MMA(ai, bj, At, Bt) do { __builtin_amdgcn_s_setprio(3); _Pragma("unroll") for (int m = 0; m < 4; ++m) _Pragma("unroll") for (int n = 0; n < 2; ++n) _Pragma("unroll") for (int k = 0; k < 2; ++k) \
;         acc[ai][bj][m][n] = __builtin_amdgcn_mfma_f32_16x16x32_bf16(Bt[n][k], At[m][k], acc[ai][bj][m][n], 0, 0, 0); __builtin_amdgcn_s_setprio(0); } while (0)
; #define PG8_WAIT_V(n) asm volatile("s_waitcnt vmcnt(" #n ")" ::: "memory")
; #define PG8_WAIT_L(n) asm volatile("s_waitcnt lgkmcnt(" #n ")" ::: "memory")
; template <class Epi, bool ALIGN_EPI>
; __device__ __forceinline__ void gemm_phase(LAS unsigned char* lds, const Gemm g, const StaticOrder& S, const Epi& E) {
;     ...
;         const bool has_next = S.next(ui + 1, nxt);
;         const char* nA = has_next ? (const char*)g.A + (size_t)nxt.pm * tstep : cA; const char* nB = has_next ? (const char*)g.Bt + (size_t)nxt.pn * tstep : cB;
;         for (int t = 0; t < nt; t += 2) {
;             const bool last = (t == nt - 2);
;             const char* a1 = cA + (size_t)(t + 1) * kstep;
;             const char* a2 = last ? nA : cA + (size_t)(t + 2) * kstep; const char* b2 = last ? nB : cB + (size_t)(t + 2) * kstep;
;             const char* a3 = a2 + kstep; const char* b3 = b2 + kstep;
;             PG8_LDB(B0, 0, 0); PG8_LDB(B1, 0, 1); PG8_SCHED; PG8_LDA(At, 0, 0); PG8_STAGE(PG8_SA(1, 1), a1 + hstep, voffA);
;             PG8_WAIT_V(8); PG8_WAIT_L(0); PG8_BAR; PG8_MMA(0, 0, At, B0); PG8_MMA(0, 1, At, B1); PG8_BAR; PG8_SCHED;
;             PG8_LDA(At, 0, 1); PG8_STAGE(PG8_SB(0, 0), b2, voffB); PG8_STAGE(PG8_SB(0, 1), b2 + hstep, voffB); PG8_STAGE(PG8_SA(0, 0), a2, voffA);
.LBB0_519:
	s_ashr_i32 s55, s54, 31
	s_lshl_b64 s[56:57], s[54:55], 19
	s_add_u32 s56, s26, s56
	s_addc_u32 s57, s27, s57
	s_and_b64 s[58:59], s[4:5], exec
	s_cselect_b32 s55, s57, s65
	s_cselect_b32 s61, s56, s64
	s_ashr_i32 s53, s52, 31
	s_lshl_b64 s[58:59], s[52:53], 19
	s_add_u32 s58, s10, s58
	s_addc_u32 s59, s11, s59
	s_and_b64 s[68:69], s[4:5], exec
	s_cselect_b32 s53, s59, s67
	s_cselect_b32 s82, s58, s66
	s_add_u32 s64, s64, 0x40080
	s_addc_u32 s65, s65, 0
	s_add_u32 s83, s66, 0x100
	s_addc_u32 s84, s67, 0
	s_mov_b32 s85, -2
	s_waitcnt lgkmcnt(0)
	ds_read_b128 v[130:133], v214
	ds_read_b128 v[134:137], v214 offset:1024
	ds_read_b128 v[138:141], v214 offset:2048
	ds_read_b128 v[142:145], v214 offset:3072
	ds_read_b128 v[146:149], v215
	ds_read_b128 v[150:153], v215 offset:1024
	ds_read_b128 v[154:157], v215 offset:2048
	ds_read_b128 v[158:161], v215 offset:3072
	s_add_u32 s66, s64, 0xfffc0080
	s_addc_u32 s67, s65, -1
	s_cmp_eq_u32 s85, 12
	s_cselect_b32 s69, s55, s67
	s_cselect_b32 s68, s61, s66
	s_cselect_b32 s67, s53, s84
	s_cselect_b32 s66, s82, s83
	v_lshl_add_u64 v[222:223], s[64:65], 0, v[186:187]
	s_add_i32 m0, s63, 0xc000
	ds_read_b128 v[162:165], v216
	ds_read_b128 v[166:169], v216 offset:1024
	ds_read_b128 v[170:173], v216 offset:2048
	ds_read_b128 v[174:177], v216 offset:3072
	ds_read_b128 v[194:197], v216 offset:4096
	ds_read_b128 v[198:201], v216 offset:5120
	ds_read_b128 v[202:205], v216 offset:6144
	ds_read_b128 v[218:221], v216 offset:7168
	global_load_lds_dwordx4 v[222:223], off
	v_lshl_add_u64 v[222:223], s[64:65], 0, v[188:189]
	s_add_i32 m0, s63, 0xe000
	s_nop 0
	global_load_lds_dwordx4 v[222:223], off
	s_cmp_lg_u32 s98, 0
	s_cbranch_scc1 .Lmy_rw_520_0
	s_waitcnt vmcnt(8)
.Lmy_rw_520_0:
	s_waitcnt lgkmcnt(0)
	s_barrier
	s_setprio 3
	s_waitcnt lgkmcnt(0)
	v_mfma_f32_16x16x32_bf16 v[126:129], v[130:133], v[162:165], 0
	v_mfma_f32_16x16x32_bf16 v[122:125], v[138:141], v[162:165], 0
	v_mfma_f32_16x16x32_bf16 v[110:113], v[130:133], v[170:173], 0
	v_mfma_f32_16x16x32_bf16 v[106:109], v[138:141], v[170:173], 0
	v_mfma_f32_16x16x32_bf16 v[94:97], v[130:133], v[194:197], 0
	v_mfma_f32_16x16x32_bf16 v[90:93], v[138:141], v[194:197], 0
	v_mfma_f32_16x16x32_bf16 v[78:81], v[130:133], v[202:205], 0
	v_mfma_f32_16x16x32_bf16 v[74:77], v[138:141], v[202:205], 0
	v_mfma_f32_16x16x32_bf16 v[126:129], v[134:137], v[166:169], v[126:129]
	v_mfma_f32_16x16x32_bf16 v[122:125], v[142:145], v[166:169], v[122:125]
	v_mfma_f32_16x16x32_bf16 v[110:113], v[134:137], v[174:177], v[110:113]
	v_mfma_f32_16x16x32_bf16 v[106:109], v[142:145], v[174:177], v[106:109]
	v_mfma_f32_16x16x32_bf16 v[94:97], v[134:137], v[198:201], v[94:97]
	v_mfma_f32_16x16x32_bf16 v[90:93], v[142:145], v[198:201], v[90:93]
	v_mfma_f32_16x16x32_bf16 v[78:81], v[134:137], v[218:221], v[78:81]
	v_mfma_f32_16x16x32_bf16 v[74:77], v[142:145], v[218:221], v[74:77]
	v_mfma_f32_16x16x32_bf16 v[118:121], v[146:149], v[162:165], 0
	v_mfma_f32_16x16x32_bf16 v[114:117], v[154:157], v[162:165], 0
	v_mfma_f32_16x16x32_bf16 v[102:105], v[146:149], v[170:173], 0
	v_mfma_f32_16x16x32_bf16 v[98:101], v[154:157], v[170:173], 0
	v_mfma_f32_16x16x32_bf16 v[86:89], v[146:149], v[194:197], 0
	v_mfma_f32_16x16x32_bf16 v[82:85], v[154:157], v[194:197], 0
	v_mfma_f32_16x16x32_bf16 v[70:73], v[146:149], v[202:205], 0
	v_mfma_f32_16x16x32_bf16 v[66:69], v[154:157], v[202:205], 0
	v_mfma_f32_16x16x32_bf16 v[118:121], v[150:153], v[166:169], v[118:121]
	v_mfma_f32_16x16x32_bf16 v[114:117], v[158:161], v[166:169], v[114:117]
	v_mfma_f32_16x16x32_bf16 v[102:105], v[150:153], v[174:177], v[102:105]
	v_mfma_f32_16x16x32_bf16 v[98:101], v[158:161], v[174:177], v[98:101]
	v_mfma_f32_16x16x32_bf16 v[86:89], v[150:153], v[198:201], v[86:89]
	v_mfma_f32_16x16x32_bf16 v[82:85], v[158:161], v[198:201], v[82:85]
	v_mfma_f32_16x16x32_bf16 v[70:73], v[150:153], v[218:221], v[70:73]
	v_mfma_f32_16x16x32_bf16 v[66:69], v[158:161], v[218:221], v[66:69]
	s_setprio 0
	s_barrier
	s_add_i32 s86, s80, s33
	v_lshl_add_u64 v[222:223], s[66:67], 0, v[180:181]
	s_mov_b32 m0, s86
	ds_read_b128 v[162:165], v216 offset:16384
	ds_read_b128 v[166:169], v216 offset:17408
	ds_read_b128 v[170:173], v216 offset:18432
	ds_read_b128 v[174:177], v216 offset:19456
	ds_read_b128 v[194:197], v216 offset:20480
	ds_read_b128 v[198:201], v216 offset:21504
	ds_read_b128 v[202:205], v216 offset:22528
	ds_read_b128 v[218:221], v216 offset:23552
	global_load_lds_dwordx4 v[222:223], off
	s_add_i32 m0, s86, 0x2000
	s_add_u32 s86, s66, 0x40000
	v_lshl_add_u64 v[224:225], s[66:67], 0, v[184:185]
	s_addc_u32 s87, s67, 0
	s_add_i32 s88, s81, s33
	global_load_lds_dwordx4 v[224:225], off
	v_lshl_add_u64 v[226:227], s[86:87], 0, v[180:181]
	s_mov_b32 m0, s88
	v_lshl_add_u64 v[228:229], s[68:69], 0, v[182:183]
	global_load_lds_dwordx4 v[226:227], off
	v_lshl_add_u64 v[226:227], s[86:87], 0, v[184:185]
	s_add_i32 m0, s88, 0x2000
	s_nop 0
	global_load_lds_dwordx4 v[226:227], off
	v_lshl_add_u64 v[226:227], s[68:69], 0, v[178:179]
	s_mov_b32 m0, s63
	s_nop 0
	global_load_lds_dwordx4 v[226:227], off
	s_mov_b32 m0, s70
	s_nop 0
	global_load_lds_dwordx4 v[228:229], off
	s_cmp_lg_u32 s98, 0
	s_cbranch_scc1 .Lmy_rw_520_1
	s_waitcnt vmcnt(8)
; #define PG8_STAGE(bufoff, gbase, voff) do { _Pragma("unroll") for (int _i = 0; _i < 2; ++_i) \
;         __builtin_amdgcn_global_load_lds((const unsigned*)((const char*)(gbase) + (voff)[_i]), (LAS unsigned*)(lds + (bufoff) + ldsw + _i * 8192), 16, 0, 0); } while (0)
; #define PG8_LDA(dst, b, h) do { _Pragma("unroll") for (int m = 0; m < 4; ++m) _Pragma("unroll") for (int k = 0; k < 2; ++k) dst[m][k] = *(const LAS bf16x8*)(lds + PG8_SA(b, h) + aoff + m * 2048 + k * 1024); } while (0)
; #define PG8_LDB(dst, b, h) do { _Pragma("unroll") for (int n = 0; n < 2; ++n) _Pragma("unroll") for (int k = 0; k < 2; ++k) dst[n][k] = *(const LAS bf16x8*)(lds + PG8_SB(b, h) + boff + n * 2048 + k * 1024); } while (0)
; #define PG8_MMA(ai, bj, At, Bt) do { __builtin_amdgcn_s_setprio(3); _Pragma("unroll") for (int m = 0; m < 4; ++m) _Pragma("unroll") for (int n = 0; n < 2; ++n) _Pragma("unroll") for (int k = 0; k < 2; ++k) \
;         acc[ai][bj][m][n] = __builtin_amdgcn_mfma_f32_16x16x32_bf16(Bt[n][k], At[m][k], acc[ai][bj][m][n], 0, 0, 0); __builtin_amdgcn_s_setprio(0); } while (0)
; #define PG8_WAIT_V(n) asm volatile("s_waitcnt vmcnt(" #n ")" ::: "memory")
; #define PG8_WAIT_L(n) asm volatile("s_waitcnt lgkmcnt(" #n ")" ::: "memory")
; #define PG8_BAR __builtin_amdgcn_s_barrier()
; #define PG8_SCHED __builtin_amdgcn_sched_barrier(0)
; template <class Epi, bool ALIGN_EPI>
; __device__ __forceinline__ void gemm_phase(LAS unsigned char* lds, const Gemm g, const StaticOrder& S, const Epi& E) {
;     ...
;             PG8_WAIT_V(8); PG8_WAIT_L(0); PG8_BAR; PG8_MMA(1, 0, At, B0); PG8_MMA(1, 1, At, B1); PG8_BAR; PG8_SCHED;
;             PG8_LDB(B0, 1, 0); PG8_LDB(B1, 1, 1); PG8_SCHED; PG8_LDA(At, 1, 0); PG8_STAGE(PG8_SA(0, 1), a2 + hstep, voffA);
;             PG8_WAIT_V(8); PG8_WAIT_L(0); PG8_BAR; PG8_MMA(0, 0, At, B0); PG8_MMA(0, 1, At, B1); PG8_BAR; PG8_SCHED;
.Lmy_rw_520_1:
	s_waitcnt lgkmcnt(0)
	s_barrier
	s_setprio 3
	s_waitcnt lgkmcnt(0)
	v_mfma_f32_16x16x32_bf16 v[62:65], v[130:133], v[162:165], 0
	v_mfma_f32_16x16x32_bf16 v[58:61], v[138:141], v[162:165], 0
	v_mfma_f32_16x16x32_bf16 v[46:49], v[130:133], v[170:173], 0
	v_mfma_f32_16x16x32_bf16 v[42:45], v[138:141], v[170:173], 0
	v_mfma_f32_16x16x32_bf16 v[30:33], v[130:133], v[194:197], 0
	v_mfma_f32_16x16x32_bf16 v[26:29], v[138:141], v[194:197], 0
	v_mfma_f32_16x16x32_bf16 v[14:17], v[130:133], v[202:205], 0
	v_mfma_f32_16x16x32_bf16 v[10:13], v[138:141], v[202:205], 0
	v_mfma_f32_16x16x32_bf16 v[62:65], v[134:137], v[166:169], v[62:65]
	v_mfma_f32_16x16x32_bf16 v[58:61], v[142:145], v[166:169], v[58:61]
	v_mfma_f32_16x16x32_bf16 v[46:49], v[134:137], v[174:177], v[46:49]
	v_mfma_f32_16x16x32_bf16 v[42:45], v[142:145], v[174:177], v[42:45]
	v_mfma_f32_16x16x32_bf16 v[30:33], v[134:137], v[198:201], v[30:33]
	v_mfma_f32_16x16x32_bf16 v[26:29], v[142:145], v[198:201], v[26:29]
	v_mfma_f32_16x16x32_bf16 v[14:17], v[134:137], v[218:221], v[14:17]
	v_mfma_f32_16x16x32_bf16 v[10:13], v[142:145], v[218:221], v[10:13]
	v_mfma_f32_16x16x32_bf16 v[54:57], v[146:149], v[162:165], 0
	v_mfma_f32_16x16x32_bf16 v[50:53], v[154:157], v[162:165], 0
	v_mfma_f32_16x16x32_bf16 v[38:41], v[146:149], v[170:173], 0
	v_mfma_f32_16x16x32_bf16 v[34:37], v[154:157], v[170:173], 0
	v_mfma_f32_16x16x32_bf16 v[22:25], v[146:149], v[194:197], 0
	v_mfma_f32_16x16x32_bf16 v[18:21], v[154:157], v[194:197], 0
	v_mfma_f32_16x16x32_bf16 v[6:9], v[146:149], v[202:205], 0
	v_mfma_f32_16x16x32_bf16 v[2:5], v[154:157], v[202:205], 0
	v_mfma_f32_16x16x32_bf16 v[54:57], v[150:153], v[166:169], v[54:57]
	v_mfma_f32_16x16x32_bf16 v[50:53], v[158:161], v[166:169], v[50:53]
	v_mfma_f32_16x16x32_bf16 v[38:41], v[150:153], v[174:177], v[38:41]
	v_mfma_f32_16x16x32_bf16 v[34:37], v[158:161], v[174:177], v[34:37]
	v_mfma_f32_16x16x32_bf16 v[22:25], v[150:153], v[198:201], v[22:25]
	v_mfma_f32_16x16x32_bf16 v[18:21], v[158:161], v[198:201], v[18:21]
	v_mfma_f32_16x16x32_bf16 v[6:9], v[150:153], v[218:221], v[6:9]
	v_mfma_f32_16x16x32_bf16 v[2:5], v[158:161], v[218:221], v[2:5]
	s_setprio 0
	s_barrier
	s_add_i32 s86, 0, 0x18000
	s_add_i32 s87, 0, 0x1c000
	v_add_u32_e32 v142, s86, v212
	v_add_u32_e32 v158, s87, v212
	ds_read_b128 v[130:133], v142
	ds_read_b128 v[134:137], v142 offset:1024
	ds_read_b128 v[138:141], v142 offset:2048
	ds_read_b128 v[142:145], v142 offset:3072
	ds_read_b128 v[146:149], v158
	ds_read_b128 v[150:153], v158 offset:1024
	ds_read_b128 v[154:157], v158 offset:2048
	ds_read_b128 v[158:161], v158 offset:3072
	s_add_u32 s68, s68, 0x40000
	s_addc_u32 s69, s69, 0
	s_mov_b32 m0, s71
	v_lshl_add_u64 v[230:231], s[68:69], 0, v[178:179]
	ds_read_b128 v[162:165], v216 offset:32768
	ds_read_b128 v[166:169], v216 offset:33792
	ds_read_b128 v[170:173], v216 offset:34816
	ds_read_b128 v[174:177], v216 offset:35840
	ds_read_b128 v[194:197], v216 offset:36864
	ds_read_b128 v[198:201], v216 offset:37888
	ds_read_b128 v[202:205], v216 offset:38912
	ds_read_b128 v[218:221], v216 offset:39936
	global_load_lds_dwordx4 v[230:231], off
	v_lshl_add_u64 v[230:231], s[68:69], 0, v[182:183]
	s_mov_b32 m0, s72
	s_nop 0
	global_load_lds_dwordx4 v[230:231], off
	s_waitcnt vmcnt(8)
	s_waitcnt lgkmcnt(0)
	s_barrier
	s_setprio 3
	s_waitcnt lgkmcnt(0)
	v_mfma_f32_16x16x32_bf16 v[126:129], v[130:133], v[162:165], v[126:129]
	v_mfma_f32_16x16x32_bf16 v[122:125], v[138:141], v[162:165], v[122:125]
	v_mfma_f32_16x16x32_bf16 v[110:113], v[130:133], v[170:173], v[110:113]
	v_mfma_f32_16x16x32_bf16 v[106:109], v[138:141], v[170:173], v[106:109]
	v_mfma_f32_16x16x32_bf16 v[94:97], v[130:133], v[194:197], v[94:97]
	v_mfma_f32_16x16x32_bf16 v[90:93], v[138:141], v[194:197], v[90:93]
	v_mfma_f32_16x16x32_bf16 v[78:81], v[130:133], v[202:205], v[78:81]
	v_mfma_f32_16x16x32_bf16 v[74:77], v[138:141], v[202:205], v[74:77]
	v_mfma_f32_16x16x32_bf16 v[126:129], v[134:137], v[166:169], v[126:129]
	v_mfma_f32_16x16x32_bf16 v[122:125], v[142:145], v[166:169], v[122:125]
	v_mfma_f32_16x16x32_bf16 v[110:113], v[134:137], v[174:177], v[110:113]
	v_mfma_f32_16x16x32_bf16 v[106:109], v[142:145], v[174:177], v[106:109]
	v_mfma_f32_16x16x32_bf16 v[94:97], v[134:137], v[198:201], v[94:97]
	v_mfma_f32_16x16x32_bf16 v[90:93], v[142:145], v[198:201], v[90:93]
	v_mfma_f32_16x16x32_bf16 v[78:81], v[134:137], v[218:221], v[78:81]
	v_mfma_f32_16x16x32_bf16 v[74:77], v[142:145], v[218:221], v[74:77]
	v_mfma_f32_16x16x32_bf16 v[118:121], v[146:149], v[162:165], v[118:121]
	v_mfma_f32_16x16x32_bf16 v[114:117], v[154:157], v[162:165], v[114:117]
	v_mfma_f32_16x16x32_bf16 v[102:105], v[146:149], v[170:173], v[102:105]
	v_mfma_f32_16x16x32_bf16 v[98:101], v[154:157], v[170:173], v[98:101]
	v_mfma_f32_16x16x32_bf16 v[86:89], v[146:149], v[194:197], v[86:89]
	v_mfma_f32_16x16x32_bf16 v[82:85], v[154:157], v[194:197], v[82:85]
	v_mfma_f32_16x16x32_bf16 v[70:73], v[146:149], v[202:205], v[70:73]
	v_mfma_f32_16x16x32_bf16 v[66:69], v[154:157], v[202:205], v[66:69]
	v_mfma_f32_16x16x32_bf16 v[118:121], v[150:153], v[166:169], v[118:121]
	v_mfma_f32_16x16x32_bf16 v[114:117], v[158:161], v[166:169], v[114:117]
	v_mfma_f32_16x16x32_bf16 v[102:105], v[150:153], v[174:177], v[102:105]
	v_mfma_f32_16x16x32_bf16 v[98:101], v[158:161], v[174:177], v[98:101]
	v_mfma_f32_16x16x32_bf16 v[86:89], v[150:153], v[198:201], v[86:89]
	v_mfma_f32_16x16x32_bf16 v[82:85], v[158:161], v[198:201], v[82:85]
	v_mfma_f32_16x16x32_bf16 v[70:73], v[150:153], v[218:221], v[70:73]
	v_mfma_f32_16x16x32_bf16 v[66:69], v[158:161], v[218:221], v[66:69]
	s_setprio 0
	s_barrier
; #define PG8_STAGE(bufoff, gbase, voff) do { _Pragma("unroll") for (int _i = 0; _i < 2; ++_i) \
;         __builtin_amdgcn_global_load_lds((const unsigned*)((const char*)(gbase) + (voff)[_i]), (LAS unsigned*)(lds + (bufoff) + ldsw + _i * 8192), 16, 0, 0); } while (0)
; #define PG8_LDA(dst, b, h) do { _Pragma("unroll") for (int m = 0; m < 4; ++m) _Pragma("unroll") for (int k = 0; k < 2; ++k) dst[m][k] = *(const LAS bf16x8*)(lds + PG8_SA(b, h) + aoff + m * 2048 + k * 1024); } while (0)
; #define PG8_MMA(ai, bj, At, Bt) do { __builtin_amdgcn_s_setprio(3); _Pragma("unroll") for (int m = 0; m < 4; ++m) _Pragma("unroll") for (int n = 0; n < 2; ++n) _Pragma("unroll") for (int k = 0; k < 2; ++k) \
;         acc[ai][bj][m][n] = __builtin_amdgcn_mfma_f32_16x16x32_bf16(Bt[n][k], At[m][k], acc[ai][bj][m][n], 0, 0, 0); __builtin_amdgcn_s_setprio(0); } while (0)
; #define PG8_WAIT_V(n) asm volatile("s_waitcnt vmcnt(" #n ")" ::: "memory")
; #define PG8_WAIT_L(n) asm volatile("s_waitcnt lgkmcnt(" #n ")" ::: "memory")
; #define PG8_BAR __builtin_amdgcn_s_barrier()
; #define PG8_SCHED __builtin_amdgcn_sched_barrier(0)
; template <class Epi, bool ALIGN_EPI>
; __device__ __forceinline__ void gemm_phase(LAS unsigned char* lds, const Gemm g, const StaticOrder& S, const Epi& E) {
;     ...
;             PG8_LDA(At, 1, 1); PG8_STAGE(PG8_SB(1, 0), b3, voffB); PG8_STAGE(PG8_SB(1, 1), b3 + hstep, voffB); PG8_STAGE(PG8_SA(1, 0), a3, voffA);
;             PG8_WAIT_V(8); PG8_WAIT_L(0); PG8_BAR; PG8_MMA(1, 0, At, B0); PG8_MMA(1, 1, At, B1); PG8_BAR; PG8_SCHED;
	s_add_i32 s68, s86, s33
	v_lshl_add_u64 v[222:223], v[222:223], 0, s[18:19]
	s_mov_b32 m0, s68
	ds_read_b128 v[162:165], v216 offset:49152
	ds_read_b128 v[166:169], v216 offset:50176
	ds_read_b128 v[170:173], v216 offset:51200
	ds_read_b128 v[174:177], v216 offset:52224
	ds_read_b128 v[194:197], v216 offset:53248
	ds_read_b128 v[198:201], v216 offset:54272
	ds_read_b128 v[202:205], v216 offset:55296
	ds_read_b128 v[218:221], v216 offset:56320
	global_load_lds_dwordx4 v[222:223], off
	s_add_i32 m0, s68, 0x2000
	s_add_u32 s66, s66, 0x40080
	v_lshl_add_u64 v[222:223], v[224:225], 0, s[18:19]
	s_addc_u32 s67, s67, 0
	s_add_i32 s68, s87, s33
	global_load_lds_dwordx4 v[222:223], off
	v_lshl_add_u64 v[222:223], s[66:67], 0, v[180:181]
	s_mov_b32 m0, s68
	s_nop 0
	global_load_lds_dwordx4 v[222:223], off
	v_lshl_add_u64 v[222:223], s[66:67], 0, v[184:185]
	s_add_i32 m0, s68, 0x2000
	s_nop 0
	global_load_lds_dwordx4 v[222:223], off
	v_lshl_add_u64 v[222:223], v[226:227], 0, s[18:19]
	s_mov_b32 m0, s78
	s_nop 0
	global_load_lds_dwordx4 v[222:223], off
	v_lshl_add_u64 v[222:223], v[228:229], 0, s[18:19]
	s_mov_b32 m0, s79
	s_nop 0
	global_load_lds_dwordx4 v[222:223], off
	s_waitcnt vmcnt(8)
	s_waitcnt lgkmcnt(0)
	s_barrier
	s_setprio 3
	s_waitcnt lgkmcnt(0)
	v_mfma_f32_16x16x32_bf16 v[62:65], v[130:133], v[162:165], v[62:65]
	v_mfma_f32_16x16x32_bf16 v[58:61], v[138:141], v[162:165], v[58:61]
	v_mfma_f32_16x16x32_bf16 v[46:49], v[130:133], v[170:173], v[46:49]
	v_mfma_f32_16x16x32_bf16 v[42:45], v[138:141], v[170:173], v[42:45]
	v_mfma_f32_16x16x32_bf16 v[30:33], v[130:133], v[194:197], v[30:33]
	v_mfma_f32_16x16x32_bf16 v[26:29], v[138:141], v[194:197], v[26:29]
	v_mfma_f32_16x16x32_bf16 v[14:17], v[130:133], v[202:205], v[14:17]
	v_mfma_f32_16x16x32_bf16 v[10:13], v[138:141], v[202:205], v[10:13]
	v_mfma_f32_16x16x32_bf16 v[62:65], v[134:137], v[166:169], v[62:65]
	v_mfma_f32_16x16x32_bf16 v[58:61], v[142:145], v[166:169], v[58:61]
	v_mfma_f32_16x16x32_bf16 v[46:49], v[134:137], v[174:177], v[46:49]
	v_mfma_f32_16x16x32_bf16 v[42:45], v[142:145], v[174:177], v[42:45]
	v_mfma_f32_16x16x32_bf16 v[30:33], v[134:137], v[198:201], v[30:33]
	v_mfma_f32_16x16x32_bf16 v[26:29], v[142:145], v[198:201], v[26:29]
	v_mfma_f32_16x16x32_bf16 v[14:17], v[134:137], v[218:221], v[14:17]
	v_mfma_f32_16x16x32_bf16 v[10:13], v[142:145], v[218:221], v[10:13]
	v_mfma_f32_16x16x32_bf16 v[54:57], v[146:149], v[162:165], v[54:57]
	v_mfma_f32_16x16x32_bf16 v[50:53], v[154:157], v[162:165], v[50:53]
	v_mfma_f32_16x16x32_bf16 v[38:41], v[146:149], v[170:173], v[38:41]
	v_mfma_f32_16x16x32_bf16 v[34:37], v[154:157], v[170:173], v[34:37]
	v_mfma_f32_16x16x32_bf16 v[22:25], v[146:149], v[194:197], v[22:25]
	v_mfma_f32_16x16x32_bf16 v[18:21], v[154:157], v[194:197], v[18:21]
	v_mfma_f32_16x16x32_bf16 v[6:9], v[146:149], v[202:205], v[6:9]
	v_mfma_f32_16x16x32_bf16 v[2:5], v[154:157], v[202:205], v[2:5]
	v_mfma_f32_16x16x32_bf16 v[54:57], v[150:153], v[166:169], v[54:57]
	v_mfma_f32_16x16x32_bf16 v[50:53], v[158:161], v[166:169], v[50:53]
	v_mfma_f32_16x16x32_bf16 v[38:41], v[150:153], v[174:177], v[38:41]
	v_mfma_f32_16x16x32_bf16 v[34:37], v[158:161], v[174:177], v[34:37]
	v_mfma_f32_16x16x32_bf16 v[22:25], v[150:153], v[198:201], v[22:25]
	v_mfma_f32_16x16x32_bf16 v[18:21], v[158:161], v[198:201], v[18:21]
	v_mfma_f32_16x16x32_bf16 v[6:9], v[150:153], v[218:221], v[6:9]
	v_mfma_f32_16x16x32_bf16 v[2:5], v[158:161], v[218:221], v[2:5]
	s_setprio 0
	s_barrier
	s_add_i32 s85, s85, 2
	s_add_u32 s64, s64, 0x100
	s_addc_u32 s65, s65, 0
	s_add_u32 s83, s83, 0x100
	s_addc_u32 s84, s84, 0

; #define PG8_STAGE(bufoff, gbase, voff) do { _Pragma("unroll") for (int _i = 0; _i < 2; ++_i) \
;         __builtin_amdgcn_global_load_lds((const unsigned*)((const char*)(gbase) + (voff)[_i]), (LAS unsigned*)(lds + (bufoff) + ldsw + _i * 8192), 16, 0, 0); } while (0)
; #define PG8_LDA(dst, b, h) do { _Pragma("unroll") for (int m = 0; m < 4; ++m) _Pragma("unroll") for (int k = 0; k < 2; ++k) dst[m][k] = *(const LAS bf16x8*)(lds + PG8_SA(b, h) + aoff + m * 2048 + k * 1024); } while (0)
; #define PG8_LDB(dst, b, h) do { _Pragma("unroll") for (int n = 0; n < 2; ++n) _Pragma("unroll") for (int k = 0; k < 2; ++k) dst[n][k] = *(const LAS bf16x8*)(lds + PG8_SB(b, h) + boff + n * 2048 + k * 1024); } while (0)
; #define PG8_MMA(ai, bj, At, Bt) do { __builtin_amdgcn_s_setprio(3); _Pragma("unroll") for (int m = 0; m < 4; ++m) _Pragma("unroll") for (int n = 0; n < 2; ++n) _Pragma("unroll") for (int k = 0; k < 2; ++k) \
;         acc[ai][bj][m][n] = __builtin_amdgcn_mfma_f32_16x16x32_bf16(Bt[n][k], At[m][k], acc[ai][bj][m][n], 0, 0, 0); __builtin_amdgcn_s_setprio(0); } while (0)
; #define PG8_WAIT_V(n) asm volatile("s_waitcnt vmcnt(" #n ")" ::: "memory")
; #define PG8_WAIT_L(n) asm volatile("s_waitcnt lgkmcnt(" #n ")" ::: "memory")
; template <class Epi, bool ALIGN_EPI>
; __device__ __forceinline__ void gemm_phase(LAS unsigned char* lds, const Gemm g, const StaticOrder& S, const Epi& E) {
;     ...
;         const bool has_next = S.next(ui + 1, nxt);
;         const char* nA = has_next ? (const char*)g.A + (size_t)nxt.pm * tstep : cA; const char* nB = has_next ? (const char*)g.Bt + (size_t)nxt.pn * tstep : cB;
;         for (int t = 0; t < nt; t += 2) {
;             const bool last = (t == nt - 2);
;             const char* a1 = cA + (size_t)(t + 1) * kstep;
;             const char* a2 = last ? nA : cA + (size_t)(t + 2) * kstep; const char* b2 = last ? nB : cB + (size_t)(t + 2) * kstep;
;             const char* a3 = a2 + kstep; const char* b3 = b2 + kstep;
;             PG8_LDB(B0, 0, 0); PG8_LDB(B1, 0, 1); PG8_SCHED; PG8_LDA(At, 0, 0); PG8_STAGE(PG8_SA(1, 1), a1 + hstep, voffA);
;             PG8_WAIT_V(8); PG8_WAIT_L(0); PG8_BAR; PG8_MMA(0, 0, At, B0); PG8_MMA(0, 1, At, B1); PG8_BAR; PG8_SCHED;
;             PG8_LDA(At, 0, 1); PG8_STAGE(PG8_SB(0, 0), b2, voffB); PG8_STAGE(PG8_SB(0, 1), b2 + hstep, voffB); PG8_STAGE(PG8_SA(0, 0), a2, voffA);
.LBB0_608:
	s_ashr_i32 s63, s62, 31
	s_lshl_b64 s[10:11], s[62:63], 19
	s_add_u32 s64, s34, s10
	s_addc_u32 s65, s35, s11
	s_and_b64 s[10:11], s[0:1], exec
	s_cselect_b32 s12, s65, s7
	s_cselect_b32 s13, s64, s6
	s_ashr_i32 s61, s60, 31
	s_lshl_b64 s[10:11], s[60:61], 19
	s_add_u32 s66, s52, s10
	s_addc_u32 s67, s53, s11
	s_and_b64 s[10:11], s[0:1], exec
	s_cselect_b32 s14, s67, s9
	s_cselect_b32 s15, s66, s8
	s_add_u32 s6, s6, 0x40080
	s_addc_u32 s7, s7, 0
	s_add_u32 s16, s8, 0x100
	s_addc_u32 s17, s9, 0
	s_mov_b32 s61, -2
	ds_read_b128 v[146:149], v168
	ds_read_b128 v[150:153], v168 offset:1024
	ds_read_b128 v[154:157], v168 offset:2048
	ds_read_b128 v[158:161], v168 offset:3072
	ds_read_b128 v[172:175], v169
	ds_read_b128 v[176:179], v169 offset:1024
	ds_read_b128 v[180:183], v169 offset:2048
	ds_read_b128 v[184:187], v169 offset:3072
	s_add_u32 s8, s6, 0xfffc0080
	s_addc_u32 s9, s7, -1
	s_cmp_eq_u32 s61, 12
	s_cselect_b32 s11, s12, s9
	s_cselect_b32 s10, s13, s8
	s_cselect_b32 s9, s14, s17
	s_cselect_b32 s8, s15, s16
	v_lshl_add_u64 v[220:221], s[6:7], 0, v[138:139]
	s_add_i32 m0, s70, 0xc000
	ds_read_b128 v[188:191], v170
	ds_read_b128 v[192:195], v170 offset:1024
	ds_read_b128 v[196:199], v170 offset:2048
	ds_read_b128 v[200:203], v170 offset:3072
	ds_read_b128 v[204:207], v170 offset:4096
	ds_read_b128 v[208:211], v170 offset:5120
	ds_read_b128 v[212:215], v170 offset:6144
	ds_read_b128 v[216:219], v170 offset:7168
	global_load_lds_dwordx4 v[220:221], off
	v_lshl_add_u64 v[220:221], s[6:7], 0, v[140:141]
	s_add_i32 m0, s70, 0xe000
	s_nop 0
	global_load_lds_dwordx4 v[220:221], off
	s_cmp_lg_u32 s98, 0
	s_cbranch_scc1 .Lmy_rw_609_0
	s_waitcnt vmcnt(8)
.Lmy_rw_609_0:
	s_waitcnt lgkmcnt(0)
	s_barrier
	s_setprio 3
	s_waitcnt lgkmcnt(0)
	v_mfma_f32_16x16x32_bf16 v[126:129], v[146:149], v[188:191], 0
	v_mfma_f32_16x16x32_bf16 v[118:121], v[154:157], v[188:191], 0
	v_mfma_f32_16x16x32_bf16 v[110:113], v[146:149], v[196:199], 0
	v_mfma_f32_16x16x32_bf16 v[102:105], v[154:157], v[196:199], 0
	v_mfma_f32_16x16x32_bf16 v[94:97], v[146:149], v[204:207], 0
	v_mfma_f32_16x16x32_bf16 v[86:89], v[154:157], v[204:207], 0
	v_mfma_f32_16x16x32_bf16 v[78:81], v[146:149], v[212:215], 0
	v_mfma_f32_16x16x32_bf16 v[70:73], v[154:157], v[212:215], 0
	v_mfma_f32_16x16x32_bf16 v[126:129], v[150:153], v[192:195], v[126:129]
	v_mfma_f32_16x16x32_bf16 v[118:121], v[158:161], v[192:195], v[118:121]
	v_mfma_f32_16x16x32_bf16 v[110:113], v[150:153], v[200:203], v[110:113]
	v_mfma_f32_16x16x32_bf16 v[102:105], v[158:161], v[200:203], v[102:105]
	v_mfma_f32_16x16x32_bf16 v[94:97], v[150:153], v[208:211], v[94:97]
	v_mfma_f32_16x16x32_bf16 v[86:89], v[158:161], v[208:211], v[86:89]
	v_mfma_f32_16x16x32_bf16 v[78:81], v[150:153], v[216:219], v[78:81]
	v_mfma_f32_16x16x32_bf16 v[70:73], v[158:161], v[216:219], v[70:73]
	v_mfma_f32_16x16x32_bf16 v[122:125], v[172:175], v[188:191], 0
	v_mfma_f32_16x16x32_bf16 v[114:117], v[180:183], v[188:191], 0
	v_mfma_f32_16x16x32_bf16 v[106:109], v[172:175], v[196:199], 0
	v_mfma_f32_16x16x32_bf16 v[98:101], v[180:183], v[196:199], 0
	v_mfma_f32_16x16x32_bf16 v[90:93], v[172:175], v[204:207], 0
	v_mfma_f32_16x16x32_bf16 v[82:85], v[180:183], v[204:207], 0
	v_mfma_f32_16x16x32_bf16 v[74:77], v[172:175], v[212:215], 0
	v_mfma_f32_16x16x32_bf16 v[66:69], v[180:183], v[212:215], 0
	v_mfma_f32_16x16x32_bf16 v[122:125], v[176:179], v[192:195], v[122:125]
	v_mfma_f32_16x16x32_bf16 v[114:117], v[184:187], v[192:195], v[114:117]
	v_mfma_f32_16x16x32_bf16 v[106:109], v[176:179], v[200:203], v[106:109]
	v_mfma_f32_16x16x32_bf16 v[98:101], v[184:187], v[200:203], v[98:101]
	v_mfma_f32_16x16x32_bf16 v[90:93], v[176:179], v[208:211], v[90:93]
	v_mfma_f32_16x16x32_bf16 v[82:85], v[184:187], v[208:211], v[82:85]
	v_mfma_f32_16x16x32_bf16 v[74:77], v[176:179], v[216:219], v[74:77]
	v_mfma_f32_16x16x32_bf16 v[66:69], v[184:187], v[216:219], v[66:69]
	s_setprio 0
	s_barrier
	s_add_i32 s63, s80, s33
	v_lshl_add_u64 v[220:221], s[8:9], 0, v[132:133]
	s_mov_b32 m0, s63
	ds_read_b128 v[188:191], v170 offset:16384
	ds_read_b128 v[192:195], v170 offset:17408
	ds_read_b128 v[196:199], v170 offset:18432
	ds_read_b128 v[200:203], v170 offset:19456
	ds_read_b128 v[204:207], v170 offset:20480
	ds_read_b128 v[208:211], v170 offset:21504
	ds_read_b128 v[212:215], v170 offset:22528
	ds_read_b128 v[216:219], v170 offset:23552
	global_load_lds_dwordx4 v[220:221], off
	s_add_i32 m0, s63, 0x2000
	s_add_u32 s84, s8, 0x40000
	v_lshl_add_u64 v[222:223], s[8:9], 0, v[136:137]
	s_addc_u32 s85, s9, 0
	s_add_i32 s63, s81, s33
	global_load_lds_dwordx4 v[222:223], off
	v_lshl_add_u64 v[224:225], s[84:85], 0, v[132:133]
	s_mov_b32 m0, s63
	v_lshl_add_u64 v[226:227], s[10:11], 0, v[134:135]
	global_load_lds_dwordx4 v[224:225], off
	v_lshl_add_u64 v[224:225], s[84:85], 0, v[136:137]
	s_add_i32 m0, s63, 0x2000
	s_nop 0
	global_load_lds_dwordx4 v[224:225], off
	v_lshl_add_u64 v[224:225], s[10:11], 0, v[130:131]
	s_mov_b32 m0, s70
	s_nop 0
	global_load_lds_dwordx4 v[224:225], off
	s_mov_b32 m0, s71
	s_nop 0
	global_load_lds_dwordx4 v[226:227], off
	s_cmp_lg_u32 s98, 0
	s_cbranch_scc1 .Lmy_rw_609_1
	s_waitcnt vmcnt(8)
; #define PG8_STAGE(bufoff, gbase, voff) do { _Pragma("unroll") for (int _i = 0; _i < 2; ++_i) \
;         __builtin_amdgcn_global_load_lds((const unsigned*)((const char*)(gbase) + (voff)[_i]), (LAS unsigned*)(lds + (bufoff) + ldsw + _i * 8192), 16, 0, 0); } while (0)
; #define PG8_LDA(dst, b, h) do { _Pragma("unroll") for (int m = 0; m < 4; ++m) _Pragma("unroll") for (int k = 0; k < 2; ++k) dst[m][k] = *(const LAS bf16x8*)(lds + PG8_SA(b, h) + aoff + m * 2048 + k * 1024); } while (0)
; #define PG8_LDB(dst, b, h) do { _Pragma("unroll") for (int n = 0; n < 2; ++n) _Pragma("unroll") for (int k = 0; k < 2; ++k) dst[n][k] = *(const LAS bf16x8*)(lds + PG8_SB(b, h) + boff + n * 2048 + k * 1024); } while (0)
; #define PG8_MMA(ai, bj, At, Bt) do { __builtin_amdgcn_s_setprio(3); _Pragma("unroll") for (int m = 0; m < 4; ++m) _Pragma("unroll") for (int n = 0; n < 2; ++n) _Pragma("unroll") for (int k = 0; k < 2; ++k) \
;         acc[ai][bj][m][n] = __builtin_amdgcn_mfma_f32_16x16x32_bf16(Bt[n][k], At[m][k], acc[ai][bj][m][n], 0, 0, 0); __builtin_amdgcn_s_setprio(0); } while (0)
; #define PG8_WAIT_V(n) asm volatile("s_waitcnt vmcnt(" #n ")" ::: "memory")
; #define PG8_WAIT_L(n) asm volatile("s_waitcnt lgkmcnt(" #n ")" ::: "memory")
; #define PG8_BAR __builtin_amdgcn_s_barrier()
; #define PG8_SCHED __builtin_amdgcn_sched_barrier(0)
; template <class Epi, bool ALIGN_EPI>
; __device__ __forceinline__ void gemm_phase(LAS unsigned char* lds, const Gemm g, const StaticOrder& S, const Epi& E) {
;     ...
;             PG8_WAIT_V(8); PG8_WAIT_L(0); PG8_BAR; PG8_MMA(1, 0, At, B0); PG8_MMA(1, 1, At, B1); PG8_BAR; PG8_SCHED;
;             PG8_LDB(B0, 1, 0); PG8_LDB(B1, 1, 1); PG8_SCHED; PG8_LDA(At, 1, 0); PG8_STAGE(PG8_SA(0, 1), a2 + hstep, voffA);
;             PG8_WAIT_V(8); PG8_WAIT_L(0); PG8_BAR; PG8_MMA(0, 0, At, B0); PG8_MMA(0, 1, At, B1); PG8_BAR; PG8_SCHED;
.Lmy_rw_609_1:
	s_waitcnt lgkmcnt(0)
	s_barrier
	s_setprio 3
	s_waitcnt lgkmcnt(0)
	v_mfma_f32_16x16x32_bf16 v[62:65], v[146:149], v[188:191], 0
	v_mfma_f32_16x16x32_bf16 v[54:57], v[154:157], v[188:191], 0
	v_mfma_f32_16x16x32_bf16 v[46:49], v[146:149], v[196:199], 0
	v_mfma_f32_16x16x32_bf16 v[38:41], v[154:157], v[196:199], 0
	v_mfma_f32_16x16x32_bf16 v[30:33], v[146:149], v[204:207], 0
	v_mfma_f32_16x16x32_bf16 v[22:25], v[154:157], v[204:207], 0
	v_mfma_f32_16x16x32_bf16 v[14:17], v[146:149], v[212:215], 0
	v_mfma_f32_16x16x32_bf16 v[6:9], v[154:157], v[212:215], 0
	v_mfma_f32_16x16x32_bf16 v[62:65], v[150:153], v[192:195], v[62:65]
	v_mfma_f32_16x16x32_bf16 v[54:57], v[158:161], v[192:195], v[54:57]
	v_mfma_f32_16x16x32_bf16 v[46:49], v[150:153], v[200:203], v[46:49]
	v_mfma_f32_16x16x32_bf16 v[38:41], v[158:161], v[200:203], v[38:41]
	v_mfma_f32_16x16x32_bf16 v[30:33], v[150:153], v[208:211], v[30:33]
	v_mfma_f32_16x16x32_bf16 v[22:25], v[158:161], v[208:211], v[22:25]
	v_mfma_f32_16x16x32_bf16 v[14:17], v[150:153], v[216:219], v[14:17]
	v_mfma_f32_16x16x32_bf16 v[6:9], v[158:161], v[216:219], v[6:9]
	v_mfma_f32_16x16x32_bf16 v[58:61], v[172:175], v[188:191], 0
	v_mfma_f32_16x16x32_bf16 v[50:53], v[180:183], v[188:191], 0
	v_mfma_f32_16x16x32_bf16 v[42:45], v[172:175], v[196:199], 0
	v_mfma_f32_16x16x32_bf16 v[34:37], v[180:183], v[196:199], 0
	v_mfma_f32_16x16x32_bf16 v[26:29], v[172:175], v[204:207], 0
	v_mfma_f32_16x16x32_bf16 v[18:21], v[180:183], v[204:207], 0
	v_mfma_f32_16x16x32_bf16 v[10:13], v[172:175], v[212:215], 0
	v_mfma_f32_16x16x32_bf16 v[2:5], v[180:183], v[212:215], 0
	v_mfma_f32_16x16x32_bf16 v[58:61], v[176:179], v[192:195], v[58:61]
	v_mfma_f32_16x16x32_bf16 v[50:53], v[184:187], v[192:195], v[50:53]
	v_mfma_f32_16x16x32_bf16 v[42:45], v[176:179], v[200:203], v[42:45]
	v_mfma_f32_16x16x32_bf16 v[34:37], v[184:187], v[200:203], v[34:37]
	v_mfma_f32_16x16x32_bf16 v[26:29], v[176:179], v[208:211], v[26:29]
	v_mfma_f32_16x16x32_bf16 v[18:21], v[184:187], v[208:211], v[18:21]
	v_mfma_f32_16x16x32_bf16 v[10:13], v[176:179], v[216:219], v[10:13]
	v_mfma_f32_16x16x32_bf16 v[2:5], v[184:187], v[216:219], v[2:5]
	s_setprio 0
	s_barrier
	s_add_i32 s63, 0, 0x18000
	s_add_i32 s84, 0, 0x1c000
	v_add_u32_e32 v158, s63, v166
	v_add_u32_e32 v184, s84, v166
	ds_read_b128 v[146:149], v158
	ds_read_b128 v[150:153], v158 offset:1024
	ds_read_b128 v[154:157], v158 offset:2048
	ds_read_b128 v[158:161], v158 offset:3072
	ds_read_b128 v[172:175], v184
	ds_read_b128 v[176:179], v184 offset:1024
	ds_read_b128 v[180:183], v184 offset:2048
	ds_read_b128 v[184:187], v184 offset:3072
	s_add_u32 s10, s10, 0x40000
	s_addc_u32 s11, s11, 0
	s_mov_b32 m0, s72
	v_lshl_add_u64 v[228:229], s[10:11], 0, v[130:131]
	ds_read_b128 v[188:191], v170 offset:32768
	ds_read_b128 v[192:195], v170 offset:33792
	ds_read_b128 v[196:199], v170 offset:34816
	ds_read_b128 v[200:203], v170 offset:35840
	ds_read_b128 v[204:207], v170 offset:36864
	ds_read_b128 v[208:211], v170 offset:37888
	ds_read_b128 v[212:215], v170 offset:38912
	ds_read_b128 v[216:219], v170 offset:39936
	global_load_lds_dwordx4 v[228:229], off
	v_lshl_add_u64 v[228:229], s[10:11], 0, v[134:135]
	s_mov_b32 m0, s73
	s_nop 0
	global_load_lds_dwordx4 v[228:229], off
	s_waitcnt vmcnt(8)
	s_waitcnt lgkmcnt(0)
	s_barrier
	s_setprio 3
	s_waitcnt lgkmcnt(0)
	v_mfma_f32_16x16x32_bf16 v[126:129], v[146:149], v[188:191], v[126:129]
	v_mfma_f32_16x16x32_bf16 v[118:121], v[154:157], v[188:191], v[118:121]
	v_mfma_f32_16x16x32_bf16 v[110:113], v[146:149], v[196:199], v[110:113]
	v_mfma_f32_16x16x32_bf16 v[102:105], v[154:157], v[196:199], v[102:105]
	v_mfma_f32_16x16x32_bf16 v[94:97], v[146:149], v[204:207], v[94:97]
	v_mfma_f32_16x16x32_bf16 v[86:89], v[154:157], v[204:207], v[86:89]
	v_mfma_f32_16x16x32_bf16 v[78:81], v[146:149], v[212:215], v[78:81]
	v_mfma_f32_16x16x32_bf16 v[70:73], v[154:157], v[212:215], v[70:73]
	v_mfma_f32_16x16x32_bf16 v[126:129], v[150:153], v[192:195], v[126:129]
	v_mfma_f32_16x16x32_bf16 v[118:121], v[158:161], v[192:195], v[118:121]
	v_mfma_f32_16x16x32_bf16 v[110:113], v[150:153], v[200:203], v[110:113]
	v_mfma_f32_16x16x32_bf16 v[102:105], v[158:161], v[200:203], v[102:105]
	v_mfma_f32_16x16x32_bf16 v[94:97], v[150:153], v[208:211], v[94:97]
	v_mfma_f32_16x16x32_bf16 v[86:89], v[158:161], v[208:211], v[86:89]
	v_mfma_f32_16x16x32_bf16 v[78:81], v[150:153], v[216:219], v[78:81]
	v_mfma_f32_16x16x32_bf16 v[70:73], v[158:161], v[216:219], v[70:73]
	v_mfma_f32_16x16x32_bf16 v[122:125], v[172:175], v[188:191], v[122:125]
	v_mfma_f32_16x16x32_bf16 v[114:117], v[180:183], v[188:191], v[114:117]
	v_mfma_f32_16x16x32_bf16 v[106:109], v[172:175], v[196:199], v[106:109]
	v_mfma_f32_16x16x32_bf16 v[98:101], v[180:183], v[196:199], v[98:101]
	v_mfma_f32_16x16x32_bf16 v[90:93], v[172:175], v[204:207], v[90:93]
	v_mfma_f32_16x16x32_bf16 v[82:85], v[180:183], v[204:207], v[82:85]
	v_mfma_f32_16x16x32_bf16 v[74:77], v[172:175], v[212:215], v[74:77]
	v_mfma_f32_16x16x32_bf16 v[66:69], v[180:183], v[212:215], v[66:69]
	v_mfma_f32_16x16x32_bf16 v[122:125], v[176:179], v[192:195], v[122:125]
	v_mfma_f32_16x16x32_bf16 v[114:117], v[184:187], v[192:195], v[114:117]
	v_mfma_f32_16x16x32_bf16 v[106:109], v[176:179], v[200:203], v[106:109]
	v_mfma_f32_16x16x32_bf16 v[98:101], v[184:187], v[200:203], v[98:101]
	v_mfma_f32_16x16x32_bf16 v[90:93], v[176:179], v[208:211], v[90:93]
	v_mfma_f32_16x16x32_bf16 v[82:85], v[184:187], v[208:211], v[82:85]
	v_mfma_f32_16x16x32_bf16 v[74:77], v[176:179], v[216:219], v[74:77]
	v_mfma_f32_16x16x32_bf16 v[66:69], v[184:187], v[216:219], v[66:69]
	s_setprio 0
	s_barrier
; #define PG8_STAGE(bufoff, gbase, voff) do { _Pragma("unroll") for (int _i = 0; _i < 2; ++_i) \
;         __builtin_amdgcn_global_load_lds((const unsigned*)((const char*)(gbase) + (voff)[_i]), (LAS unsigned*)(lds + (bufoff) + ldsw + _i * 8192), 16, 0, 0); } while (0)
; #define PG8_LDA(dst, b, h) do { _Pragma("unroll") for (int m = 0; m < 4; ++m) _Pragma("unroll") for (int k = 0; k < 2; ++k) dst[m][k] = *(const LAS bf16x8*)(lds + PG8_SA(b, h) + aoff + m * 2048 + k * 1024); } while (0)
; #define PG8_MMA(ai, bj, At, Bt) do { __builtin_amdgcn_s_setprio(3); _Pragma("unroll") for (int m = 0; m < 4; ++m) _Pragma("unroll") for (int n = 0; n < 2; ++n) _Pragma("unroll") for (int k = 0; k < 2; ++k) \
;         acc[ai][bj][m][n] = __builtin_amdgcn_mfma_f32_16x16x32_bf16(Bt[n][k], At[m][k], acc[ai][bj][m][n], 0, 0, 0); __builtin_amdgcn_s_setprio(0); } while (0)
; #define PG8_WAIT_V(n) asm volatile("s_waitcnt vmcnt(" #n ")" ::: "memory")
; #define PG8_WAIT_L(n) asm volatile("s_waitcnt lgkmcnt(" #n ")" ::: "memory")
; #define PG8_BAR __builtin_amdgcn_s_barrier()
; #define PG8_SCHED __builtin_amdgcn_sched_barrier(0)
; template <class Epi, bool ALIGN_EPI>
; __device__ __forceinline__ void gemm_phase(LAS unsigned char* lds, const Gemm g, const StaticOrder& S, const Epi& E) {
;     ...
;             PG8_LDA(At, 1, 1); PG8_STAGE(PG8_SB(1, 0), b3, voffB); PG8_STAGE(PG8_SB(1, 1), b3 + hstep, voffB); PG8_STAGE(PG8_SA(1, 0), a3, voffA);
;             PG8_WAIT_V(8); PG8_WAIT_L(0); PG8_BAR; PG8_MMA(1, 0, At, B0); PG8_MMA(1, 1, At, B1); PG8_BAR; PG8_SCHED;
	s_add_i32 s10, s63, s33
	v_lshl_add_u64 v[220:221], v[220:221], 0, s[56:57]
	s_mov_b32 m0, s10
	ds_read_b128 v[188:191], v170 offset:49152
	ds_read_b128 v[192:195], v170 offset:50176
	ds_read_b128 v[196:199], v170 offset:51200
	ds_read_b128 v[200:203], v170 offset:52224
	ds_read_b128 v[204:207], v170 offset:53248
	ds_read_b128 v[208:211], v170 offset:54272
	ds_read_b128 v[212:215], v170 offset:55296
	ds_read_b128 v[216:219], v170 offset:56320
	global_load_lds_dwordx4 v[220:221], off
	s_add_i32 m0, s10, 0x2000
	s_add_u32 s8, s8, 0x40080
	v_lshl_add_u64 v[220:221], v[222:223], 0, s[56:57]
	s_addc_u32 s9, s9, 0
	s_add_i32 s10, s84, s33
	global_load_lds_dwordx4 v[220:221], off
	v_lshl_add_u64 v[220:221], s[8:9], 0, v[132:133]
	s_mov_b32 m0, s10
	s_nop 0
	global_load_lds_dwordx4 v[220:221], off
	v_lshl_add_u64 v[220:221], s[8:9], 0, v[136:137]
	s_add_i32 m0, s10, 0x2000
	s_nop 0
	global_load_lds_dwordx4 v[220:221], off
	v_lshl_add_u64 v[220:221], v[224:225], 0, s[56:57]
	s_mov_b32 m0, s78
	s_nop 0
	global_load_lds_dwordx4 v[220:221], off
	v_lshl_add_u64 v[220:221], v[226:227], 0, s[56:57]
	s_mov_b32 m0, s79
	s_nop 0
	global_load_lds_dwordx4 v[220:221], off
	s_waitcnt vmcnt(8)
	s_waitcnt lgkmcnt(0)
	s_barrier
	s_setprio 3
	s_waitcnt lgkmcnt(0)
	v_mfma_f32_16x16x32_bf16 v[62:65], v[146:149], v[188:191], v[62:65]
	v_mfma_f32_16x16x32_bf16 v[54:57], v[154:157], v[188:191], v[54:57]
	v_mfma_f32_16x16x32_bf16 v[46:49], v[146:149], v[196:199], v[46:49]
	v_mfma_f32_16x16x32_bf16 v[38:41], v[154:157], v[196:199], v[38:41]
	v_mfma_f32_16x16x32_bf16 v[30:33], v[146:149], v[204:207], v[30:33]
	v_mfma_f32_16x16x32_bf16 v[22:25], v[154:157], v[204:207], v[22:25]
	v_mfma_f32_16x16x32_bf16 v[14:17], v[146:149], v[212:215], v[14:17]
	v_mfma_f32_16x16x32_bf16 v[6:9], v[154:157], v[212:215], v[6:9]
	v_mfma_f32_16x16x32_bf16 v[62:65], v[150:153], v[192:195], v[62:65]
	v_mfma_f32_16x16x32_bf16 v[54:57], v[158:161], v[192:195], v[54:57]
	v_mfma_f32_16x16x32_bf16 v[46:49], v[150:153], v[200:203], v[46:49]
	v_mfma_f32_16x16x32_bf16 v[38:41], v[158:161], v[200:203], v[38:41]
	v_mfma_f32_16x16x32_bf16 v[30:33], v[150:153], v[208:211], v[30:33]
	v_mfma_f32_16x16x32_bf16 v[22:25], v[158:161], v[208:211], v[22:25]
	v_mfma_f32_16x16x32_bf16 v[14:17], v[150:153], v[216:219], v[14:17]
	v_mfma_f32_16x16x32_bf16 v[6:9], v[158:161], v[216:219], v[6:9]
	v_mfma_f32_16x16x32_bf16 v[58:61], v[172:175], v[188:191], v[58:61]
	v_mfma_f32_16x16x32_bf16 v[50:53], v[180:183], v[188:191], v[50:53]
	v_mfma_f32_16x16x32_bf16 v[42:45], v[172:175], v[196:199], v[42:45]
	v_mfma_f32_16x16x32_bf16 v[34:37], v[180:183], v[196:199], v[34:37]
	v_mfma_f32_16x16x32_bf16 v[26:29], v[172:175], v[204:207], v[26:29]
	v_mfma_f32_16x16x32_bf16 v[18:21], v[180:183], v[204:207], v[18:21]
	v_mfma_f32_16x16x32_bf16 v[10:13], v[172:175], v[212:215], v[10:13]
	v_mfma_f32_16x16x32_bf16 v[2:5], v[180:183], v[212:215], v[2:5]
	v_mfma_f32_16x16x32_bf16 v[58:61], v[176:179], v[192:195], v[58:61]
	v_mfma_f32_16x16x32_bf16 v[50:53], v[184:187], v[192:195], v[50:53]
	v_mfma_f32_16x16x32_bf16 v[42:45], v[176:179], v[200:203], v[42:45]
	v_mfma_f32_16x16x32_bf16 v[34:37], v[184:187], v[200:203], v[34:37]
	v_mfma_f32_16x16x32_bf16 v[26:29], v[176:179], v[208:211], v[26:29]
	v_mfma_f32_16x16x32_bf16 v[18:21], v[184:187], v[208:211], v[18:21]
	v_mfma_f32_16x16x32_bf16 v[10:13], v[176:179], v[216:219], v[10:13]
	v_mfma_f32_16x16x32_bf16 v[2:5], v[184:187], v[216:219], v[2:5]
	s_setprio 0
	s_barrier
	s_add_i32 s61, s61, 2
	s_add_u32 s6, s6, 0x100
	s_addc_u32 s7, s7, 0
	s_add_u32 s16, s16, 0x100
	s_addc_u32 s17, s17, 0

; #define PG8_STAGE(bufoff, gbase, voff) do { _Pragma("unroll") for (int _i = 0; _i < 2; ++_i) \
;         __builtin_amdgcn_global_load_lds((const unsigned*)((const char*)(gbase) + (voff)[_i]), (LAS unsigned*)(lds + (bufoff) + ldsw + _i * 8192), 16, 0, 0); } while (0)
; #define PG8_WAIT_V(n) asm volatile("s_waitcnt vmcnt(" #n ")" ::: "memory")
; #define PG8_BAR __builtin_amdgcn_s_barrier()
; template <class Epi, bool ALIGN_EPI>
; __device__ __forceinline__ void gemm_phase(LAS unsigned char* lds, const Gemm g, const StaticOrder& S, const Epi& E) {
;     ...
;     const int aoff = lds_byte(wr * 64 + fr, fq * 8), boff = lds_byte(wc * 32 + fr, fq * 8);
;     ...
;     Unit cur, nxt; int ui = 0;
;     if (!S.next(0, cur)) return;
;     f32x4 acc[2][2][4][2];
; #pragma unroll
;     for (int a = 0; a < 2; ++a)
; #pragma unroll
;         for (int b = 0; b < 2; ++b)
; #pragma unroll
;             for (int m = 0; m < 4; ++m)
; #pragma unroll
;                 for (int n = 0; n < 2; ++n) acc[a][b][m][n] = (f32x4){0.f, 0.f, 0.f, 0.f};
;     bf16x8 At[4][2], B0[2][2], B1[2][2];
;     const char* cA = (const char*)g.A + (size_t)cur.pm * tstep; const char* cB = (const char*)g.Bt + (size_t)cur.pn * tstep;
;     PG8_STAGE(PG8_SB(0, 0), cB, voffB); PG8_STAGE(PG8_SB(0, 1), cB + hstep, voffB); PG8_STAGE(PG8_SA(0, 0), cA, voffA); PG8_STAGE(PG8_SA(0, 1), cA + hstep, voffA);
;     if (wr == 1) PG8_BAR;
;     PG8_WAIT_V(2); PG8_BAR;
;     PG8_STAGE(PG8_SB(1, 0), cB + kstep, voffB); PG8_STAGE(PG8_SA(1, 0), cA + kstep, voffA); PG8_STAGE(PG8_SB(1, 1), cB + hstep + kstep, voffB);
;     PG8_WAIT_V(6); PG8_BAR;
;     for (;;) {
;         const bool has_next = S.next(ui + 1, nxt);
.LBB0_682:
	s_lshl_b32 s1, s1, 5
	s_mov_b64 s[14:15], 0x80
	s_and_b32 s18, s1, 0x60
	s_add_i32 m0, s58, 0x18000
	v_lshl_add_u64 v[8:9], v[8:9], 0, s[14:15]
	s_lshl_b32 s7, s0, 13
	s_lshl_b32 s1, s18, 7
	s_waitcnt vmcnt(2)
	s_barrier
	global_load_lds_dwordx4 v[8:9], off
	v_lshl_add_u64 v[6:7], v[6:7], 0, s[14:15]
	s_add_i32 m0, s58, 0x1a000
	s_add_i32 s63, s58, 0x8000
	s_add_i32 s64, s58, 0xa000
	global_load_lds_dwordx4 v[6:7], off
	v_lshl_add_u64 v[2:3], v[2:3], 0, s[14:15]
	s_mov_b32 m0, s63
	s_add_u32 s4, s52, 0xb0080
	global_load_lds_dwordx4 v[2:3], off
	v_lshl_add_u64 v[2:3], v[4:5], 0, s[14:15]
	s_mov_b32 m0, s64
	s_addc_u32 s5, s53, 0
	global_load_lds_dwordx4 v[2:3], off
	s_add_i32 m0, s58, 0x1c000
	v_lshl_add_u64 v[2:3], s[4:5], 0, v[156:157]
	global_load_lds_dwordx4 v[2:3], off
	v_lshl_add_u64 v[2:3], s[4:5], 0, v[160:161]
	s_add_i32 m0, s58, 0x1e000
	v_lshlrev_b32_e32 v5, 2, v190
	global_load_lds_dwordx4 v[2:3], off
	v_and_b32_e32 v2, 3, v188
	v_lshlrev_b32_e32 v3, 4, v2
	v_lshl_or_b32 v4, v190, 6, v3
	v_and_b32_e32 v5, 32, v5
	v_lshl_or_b32 v193, s0, 6, v190
	v_bitop3_b32 v4, v4, s7, v5 bitop3:0xde
	v_lshlrev_b32_e32 v5, 6, v189
	s_movk_i32 s0, 0x3c0
	v_and_or_b32 v3, v5, s0, v3
	v_and_b32_e32 v5, 32, v192
	v_bitop3_b32 v194, s1, v3, v5 bitop3:0xf6
	v_cmp_eq_u32_e64 s[0:1], 0, v2
	v_lshl_or_b32 v195, v2, 3, s18
	v_add_u16_e32 v2, v10, v11
	s_waitcnt vmcnt(6)
	s_cmpk_lt_u32 s6, 0x100
	v_lshrrev_b16_e32 v2, 1, v2
	s_cselect_b64 s[16:17], -1, 0
	v_add_lshl_u32 v162, v12, v2, 1
	v_add_lshl_u32 v164, v13, v2, 1
	s_add_i32 s67, 0, 0x10000
	s_add_i32 s68, 0, 0x14000
	v_mbcnt_lo_u32_b32 v2, -1, 0
	s_ashr_i32 s65, s3, 31
	s_ashr_i32 s66, s2, 31
	v_mov_b32_e32 v163, v157
	v_mov_b32_e32 v165, v157
	v_mov_b64_e32 v[166:167], 0x200
	v_mov_b64_e32 v[168:169], 0x1ff
	v_add_u32_e32 v196, s67, v194
	v_add_u32_e32 v197, s68, v194
	v_add_u32_e32 v198, 0, v4
	v_mbcnt_hi_u32_b32 v199, -1, v2
	s_barrier
	s_mov_b32 s98, 0
	s_branch .LBB0_685

; #define PG8_BAR __builtin_amdgcn_s_barrier()
; template <class Epi, bool ALIGN_EPI>
; __device__ __forceinline__ void gemm_phase(LAS unsigned char* lds, const Gemm g, const StaticOrder& S, const Epi& E) {
;     ...
;         if (!has_next) break;
; #pragma unroll
;         for (int a = 0; a < 2; ++a)
; #pragma unroll
;             for (int b = 0; b < 2; ++b)
; #pragma unroll
;                 for (int m = 0; m < 4; ++m)
; #pragma unroll
;                     for (int n = 0; n < 2; ++n) acc[a][b][m][n] = (f32x4){0.f, 0.f, 0.f, 0.f};
;         cur = nxt; cA = nA; cB = nB; ++ui;
;         if constexpr (ALIGN_EPI) { if (wr == 1) PG8_BAR; }
;     }
.LBB0_684:
	s_mov_b32 s98, 1
	s_andn2_b64 vcc, exec, s[6:7]
	s_mov_b32 s72, s69
	s_mov_b32 s71, s70
	s_mov_b64 s[52:53], s[18:19]
	s_mov_b64 s[50:51], s[4:5]
	s_cbranch_vccz .LBB0_718

; #define PG8_STAGE(bufoff, gbase, voff) do { _Pragma("unroll") for (int _i = 0; _i < 2; ++_i) \
;         __builtin_amdgcn_global_load_lds((const unsigned*)((const char*)(gbase) + (voff)[_i]), (LAS unsigned*)(lds + (bufoff) + ldsw + _i * 8192), 16, 0, 0); } while (0)
; #define PG8_LDA(dst, b, h) do { _Pragma("unroll") for (int m = 0; m < 4; ++m) _Pragma("unroll") for (int k = 0; k < 2; ++k) dst[m][k] = *(const LAS bf16x8*)(lds + PG8_SA(b, h) + aoff + m * 2048 + k * 1024); } while (0)
; #define PG8_LDB(dst, b, h) do { _Pragma("unroll") for (int n = 0; n < 2; ++n) _Pragma("unroll") for (int k = 0; k < 2; ++k) dst[n][k] = *(const LAS bf16x8*)(lds + PG8_SB(b, h) + boff + n * 2048 + k * 1024); } while (0)
; #define PG8_MMA(ai, bj, At, Bt) do { __builtin_amdgcn_s_setprio(3); _Pragma("unroll") for (int m = 0; m < 4; ++m) _Pragma("unroll") for (int n = 0; n < 2; ++n) _Pragma("unroll") for (int k = 0; k < 2; ++k) \
;         acc[ai][bj][m][n] = __builtin_amdgcn_mfma_f32_16x16x32_bf16(Bt[n][k], At[m][k], acc[ai][bj][m][n], 0, 0, 0); __builtin_amdgcn_s_setprio(0); } while (0)
; #define PG8_WAIT_V(n) asm volatile("s_waitcnt vmcnt(" #n ")" ::: "memory")
; #define PG8_WAIT_L(n) asm volatile("s_waitcnt lgkmcnt(" #n ")" ::: "memory")
; template <class Epi, bool ALIGN_EPI>
; __device__ __forceinline__ void gemm_phase(LAS unsigned char* lds, const Gemm g, const StaticOrder& S, const Epi& E) {
;     ...
;         const bool has_next = S.next(ui + 1, nxt);
;         const char* nA = has_next ? (const char*)g.A + (size_t)nxt.pm * tstep : cA; const char* nB = has_next ? (const char*)g.Bt + (size_t)nxt.pn * tstep : cB;
;         for (int t = 0; t < nt; t += 2) {
;             const bool last = (t == nt - 2);
;             const char* a1 = cA + (size_t)(t + 1) * kstep;
;             const char* a2 = last ? nA : cA + (size_t)(t + 2) * kstep; const char* b2 = last ? nB : cB + (size_t)(t + 2) * kstep;
;             const char* a3 = a2 + kstep; const char* b3 = b2 + kstep;
;             PG8_LDB(B0, 0, 0); PG8_LDB(B1, 0, 1); PG8_SCHED; PG8_LDA(At, 0, 0); PG8_STAGE(PG8_SA(1, 1), a1 + hstep, voffA);
;             PG8_WAIT_V(8); PG8_WAIT_L(0); PG8_BAR; PG8_MMA(0, 0, At, B0); PG8_MMA(0, 1, At, B1); PG8_BAR; PG8_SCHED;
;             PG8_LDA(At, 0, 1); PG8_STAGE(PG8_SB(0, 0), b2, voffB); PG8_STAGE(PG8_SB(0, 1), b2 + hstep, voffB); PG8_STAGE(PG8_SA(0, 0), a2, voffA);
.LBB0_695:
	s_add_u32 s50, s50, 0xb0080
	s_addc_u32 s51, s51, 0
	s_add_u32 s73, s52, 0x100
	s_addc_u32 s76, s53, 0
	s_mov_b32 s77, -2
	s_waitcnt lgkmcnt(0)
	ds_read_b128 v[130:133], v196
	ds_read_b128 v[134:137], v196 offset:1024
	ds_read_b128 v[138:141], v196 offset:2048
	ds_read_b128 v[142:145], v196 offset:3072
	ds_read_b128 v[146:149], v197
	ds_read_b128 v[150:153], v197 offset:1024
	ds_read_b128 v[170:173], v197 offset:2048
	ds_read_b128 v[174:177], v197 offset:3072
	s_add_u32 s52, s50, 0xfff50080
	s_addc_u32 s53, s51, -1
	s_cmp_eq_u32 s77, 40
	s_cselect_b32 s55, s5, s53
	s_cselect_b32 s54, s4, s52
	s_cselect_b32 s53, s19, s76
	s_cselect_b32 s52, s18, s73
	v_lshl_add_u64 v[186:187], s[50:51], 0, v[162:163]
	s_add_i32 m0, s58, 0xc000
	ds_read_b128 v[178:181], v198
	ds_read_b128 v[182:185], v198 offset:1024
	ds_read_b128 v[200:203], v198 offset:2048
	ds_read_b128 v[204:207], v198 offset:3072
	ds_read_b128 v[208:211], v198 offset:4096
	ds_read_b128 v[212:215], v198 offset:5120
	ds_read_b128 v[216:219], v198 offset:6144
	ds_read_b128 v[220:223], v198 offset:7168
	global_load_lds_dwordx4 v[186:187], off
	v_lshl_add_u64 v[186:187], s[50:51], 0, v[164:165]
	s_add_i32 m0, s58, 0xe000
	s_nop 0
	global_load_lds_dwordx4 v[186:187], off
	s_cmp_lg_u32 s98, 0
	s_cbranch_scc1 .Lmy_rw_696_0
	s_waitcnt vmcnt(8)
.Lmy_rw_696_0:
	s_waitcnt lgkmcnt(0)
	s_barrier
	s_setprio 3
	s_waitcnt lgkmcnt(0)
	v_mfma_f32_16x16x32_bf16 v[126:129], v[130:133], v[178:181], 0
	v_mfma_f32_16x16x32_bf16 v[122:125], v[138:141], v[178:181], 0
	v_mfma_f32_16x16x32_bf16 v[110:113], v[130:133], v[200:203], 0
	v_mfma_f32_16x16x32_bf16 v[106:109], v[138:141], v[200:203], 0
	v_mfma_f32_16x16x32_bf16 v[94:97], v[130:133], v[208:211], 0
	v_mfma_f32_16x16x32_bf16 v[90:93], v[138:141], v[208:211], 0
	v_mfma_f32_16x16x32_bf16 v[78:81], v[130:133], v[216:219], 0
	v_mfma_f32_16x16x32_bf16 v[74:77], v[138:141], v[216:219], 0
	v_mfma_f32_16x16x32_bf16 v[126:129], v[134:137], v[182:185], v[126:129]
	v_mfma_f32_16x16x32_bf16 v[122:125], v[142:145], v[182:185], v[122:125]
	v_mfma_f32_16x16x32_bf16 v[110:113], v[134:137], v[204:207], v[110:113]
	v_mfma_f32_16x16x32_bf16 v[106:109], v[142:145], v[204:207], v[106:109]
	v_mfma_f32_16x16x32_bf16 v[94:97], v[134:137], v[212:215], v[94:97]
	v_mfma_f32_16x16x32_bf16 v[90:93], v[142:145], v[212:215], v[90:93]
	v_mfma_f32_16x16x32_bf16 v[78:81], v[134:137], v[220:223], v[78:81]
	v_mfma_f32_16x16x32_bf16 v[74:77], v[142:145], v[220:223], v[74:77]
	v_mfma_f32_16x16x32_bf16 v[118:121], v[146:149], v[178:181], 0
	v_mfma_f32_16x16x32_bf16 v[114:117], v[170:173], v[178:181], 0
	v_mfma_f32_16x16x32_bf16 v[102:105], v[146:149], v[200:203], 0
	v_mfma_f32_16x16x32_bf16 v[98:101], v[170:173], v[200:203], 0
	v_mfma_f32_16x16x32_bf16 v[86:89], v[146:149], v[208:211], 0
	v_mfma_f32_16x16x32_bf16 v[82:85], v[170:173], v[208:211], 0
	v_mfma_f32_16x16x32_bf16 v[70:73], v[146:149], v[216:219], 0
	v_mfma_f32_16x16x32_bf16 v[66:69], v[170:173], v[216:219], 0
	v_mfma_f32_16x16x32_bf16 v[118:121], v[150:153], v[182:185], v[118:121]
	v_mfma_f32_16x16x32_bf16 v[114:117], v[174:177], v[182:185], v[114:117]
	v_mfma_f32_16x16x32_bf16 v[102:105], v[150:153], v[204:207], v[102:105]
	v_mfma_f32_16x16x32_bf16 v[98:101], v[174:177], v[204:207], v[98:101]
	v_mfma_f32_16x16x32_bf16 v[86:89], v[150:153], v[212:215], v[86:89]
	v_mfma_f32_16x16x32_bf16 v[82:85], v[174:177], v[212:215], v[82:85]
	v_mfma_f32_16x16x32_bf16 v[70:73], v[150:153], v[220:223], v[70:73]
	v_mfma_f32_16x16x32_bf16 v[66:69], v[174:177], v[220:223], v[66:69]
	s_setprio 0
	s_barrier
	s_add_i32 s78, s67, s57
	v_lshl_add_u64 v[186:187], s[52:53], 0, v[156:157]
	s_mov_b32 m0, s78
	ds_read_b128 v[178:181], v198 offset:16384
	ds_read_b128 v[182:185], v198 offset:17408
	ds_read_b128 v[200:203], v198 offset:18432
	ds_read_b128 v[204:207], v198 offset:19456
	ds_read_b128 v[208:211], v198 offset:20480
	ds_read_b128 v[212:215], v198 offset:21504
	ds_read_b128 v[216:219], v198 offset:22528
	ds_read_b128 v[220:223], v198 offset:23552
	global_load_lds_dwordx4 v[186:187], off
	s_add_i32 m0, s78, 0x2000
	s_add_u32 s78, s52, 0xb0000
	v_lshl_add_u64 v[224:225], s[52:53], 0, v[160:161]
	s_addc_u32 s79, s53, 0
	s_add_i32 s80, s68, s57
	global_load_lds_dwordx4 v[224:225], off
	v_lshl_add_u64 v[226:227], s[78:79], 0, v[156:157]
	s_mov_b32 m0, s80
	v_lshl_add_u64 v[228:229], s[54:55], 0, v[158:159]
	global_load_lds_dwordx4 v[226:227], off
	v_lshl_add_u64 v[226:227], s[78:79], 0, v[160:161]
	s_add_i32 m0, s80, 0x2000
	s_nop 0
	global_load_lds_dwordx4 v[226:227], off
	v_lshl_add_u64 v[226:227], s[54:55], 0, v[154:155]
	s_mov_b32 m0, s58
	s_nop 0
	global_load_lds_dwordx4 v[226:227], off
	s_mov_b32 m0, s59
	s_nop 0
	global_load_lds_dwordx4 v[228:229], off
	s_cmp_lg_u32 s98, 0
	s_cbranch_scc1 .Lmy_rw_696_1
	s_waitcnt vmcnt(8)
; #define PG8_STAGE(bufoff, gbase, voff) do { _Pragma("unroll") for (int _i = 0; _i < 2; ++_i) \
;         __builtin_amdgcn_global_load_lds((const unsigned*)((const char*)(gbase) + (voff)[_i]), (LAS unsigned*)(lds + (bufoff) + ldsw + _i * 8192), 16, 0, 0); } while (0)
; #define PG8_LDA(dst, b, h) do { _Pragma("unroll") for (int m = 0; m < 4; ++m) _Pragma("unroll") for (int k = 0; k < 2; ++k) dst[m][k] = *(const LAS bf16x8*)(lds + PG8_SA(b, h) + aoff + m * 2048 + k * 1024); } while (0)
; #define PG8_LDB(dst, b, h) do { _Pragma("unroll") for (int n = 0; n < 2; ++n) _Pragma("unroll") for (int k = 0; k < 2; ++k) dst[n][k] = *(const LAS bf16x8*)(lds + PG8_SB(b, h) + boff + n * 2048 + k * 1024); } while (0)
; #define PG8_MMA(ai, bj, At, Bt) do { __builtin_amdgcn_s_setprio(3); _Pragma("unroll") for (int m = 0; m < 4; ++m) _Pragma("unroll") for (int n = 0; n < 2; ++n) _Pragma("unroll") for (int k = 0; k < 2; ++k) \
;         acc[ai][bj][m][n] = __builtin_amdgcn_mfma_f32_16x16x32_bf16(Bt[n][k], At[m][k], acc[ai][bj][m][n], 0, 0, 0); __builtin_amdgcn_s_setprio(0); } while (0)
; #define PG8_WAIT_V(n) asm volatile("s_waitcnt vmcnt(" #n ")" ::: "memory")
; #define PG8_WAIT_L(n) asm volatile("s_waitcnt lgkmcnt(" #n ")" ::: "memory")
; #define PG8_BAR __builtin_amdgcn_s_barrier()
; #define PG8_SCHED __builtin_amdgcn_sched_barrier(0)
; template <class Epi, bool ALIGN_EPI>
; __device__ __forceinline__ void gemm_phase(LAS unsigned char* lds, const Gemm g, const StaticOrder& S, const Epi& E) {
;     ...
;             PG8_WAIT_V(8); PG8_WAIT_L(0); PG8_BAR; PG8_MMA(1, 0, At, B0); PG8_MMA(1, 1, At, B1); PG8_BAR; PG8_SCHED;
;             PG8_LDB(B0, 1, 0); PG8_LDB(B1, 1, 1); PG8_SCHED; PG8_LDA(At, 1, 0); PG8_STAGE(PG8_SA(0, 1), a2 + hstep, voffA);
;             PG8_WAIT_V(8); PG8_WAIT_L(0); PG8_BAR; PG8_MMA(0, 0, At, B0); PG8_MMA(0, 1, At, B1); PG8_BAR; PG8_SCHED;
.Lmy_rw_696_1:
	s_waitcnt lgkmcnt(0)
	s_barrier
	s_setprio 3
	s_waitcnt lgkmcnt(0)
	v_mfma_f32_16x16x32_bf16 v[62:65], v[130:133], v[178:181], 0
	v_mfma_f32_16x16x32_bf16 v[58:61], v[138:141], v[178:181], 0
	v_mfma_f32_16x16x32_bf16 v[46:49], v[130:133], v[200:203], 0
	v_mfma_f32_16x16x32_bf16 v[42:45], v[138:141], v[200:203], 0
	v_mfma_f32_16x16x32_bf16 v[30:33], v[130:133], v[208:211], 0
	v_mfma_f32_16x16x32_bf16 v[26:29], v[138:141], v[208:211], 0
	v_mfma_f32_16x16x32_bf16 v[14:17], v[130:133], v[216:219], 0
	v_mfma_f32_16x16x32_bf16 v[10:13], v[138:141], v[216:219], 0
	v_mfma_f32_16x16x32_bf16 v[62:65], v[134:137], v[182:185], v[62:65]
	v_mfma_f32_16x16x32_bf16 v[58:61], v[142:145], v[182:185], v[58:61]
	v_mfma_f32_16x16x32_bf16 v[46:49], v[134:137], v[204:207], v[46:49]
	v_mfma_f32_16x16x32_bf16 v[42:45], v[142:145], v[204:207], v[42:45]
	v_mfma_f32_16x16x32_bf16 v[30:33], v[134:137], v[212:215], v[30:33]
	v_mfma_f32_16x16x32_bf16 v[26:29], v[142:145], v[212:215], v[26:29]
	v_mfma_f32_16x16x32_bf16 v[14:17], v[134:137], v[220:223], v[14:17]
	v_mfma_f32_16x16x32_bf16 v[10:13], v[142:145], v[220:223], v[10:13]
	v_mfma_f32_16x16x32_bf16 v[54:57], v[146:149], v[178:181], 0
	v_mfma_f32_16x16x32_bf16 v[50:53], v[170:173], v[178:181], 0
	v_mfma_f32_16x16x32_bf16 v[38:41], v[146:149], v[200:203], 0
	v_mfma_f32_16x16x32_bf16 v[34:37], v[170:173], v[200:203], 0
	v_mfma_f32_16x16x32_bf16 v[22:25], v[146:149], v[208:211], 0
	v_mfma_f32_16x16x32_bf16 v[18:21], v[170:173], v[208:211], 0
	v_mfma_f32_16x16x32_bf16 v[6:9], v[146:149], v[216:219], 0
	v_mfma_f32_16x16x32_bf16 v[2:5], v[170:173], v[216:219], 0
	v_mfma_f32_16x16x32_bf16 v[54:57], v[150:153], v[182:185], v[54:57]
	v_mfma_f32_16x16x32_bf16 v[50:53], v[174:177], v[182:185], v[50:53]
	v_mfma_f32_16x16x32_bf16 v[38:41], v[150:153], v[204:207], v[38:41]
	v_mfma_f32_16x16x32_bf16 v[34:37], v[174:177], v[204:207], v[34:37]
	v_mfma_f32_16x16x32_bf16 v[22:25], v[150:153], v[212:215], v[22:25]
	v_mfma_f32_16x16x32_bf16 v[18:21], v[174:177], v[212:215], v[18:21]
	v_mfma_f32_16x16x32_bf16 v[6:9], v[150:153], v[220:223], v[6:9]
	v_mfma_f32_16x16x32_bf16 v[2:5], v[174:177], v[220:223], v[2:5]
	s_setprio 0
	s_barrier
	s_add_i32 s78, 0, 0x18000
	s_add_i32 s79, 0, 0x1c000
	v_add_u32_e32 v142, s78, v194
	v_add_u32_e32 v174, s79, v194
	ds_read_b128 v[130:133], v142
	ds_read_b128 v[134:137], v142 offset:1024
	ds_read_b128 v[138:141], v142 offset:2048
	ds_read_b128 v[142:145], v142 offset:3072
	ds_read_b128 v[146:149], v174
	ds_read_b128 v[150:153], v174 offset:1024
	ds_read_b128 v[170:173], v174 offset:2048
	ds_read_b128 v[174:177], v174 offset:3072
	s_add_u32 s54, s54, 0xb0000
	s_addc_u32 s55, s55, 0
	s_mov_b32 m0, s60
	v_lshl_add_u64 v[230:231], s[54:55], 0, v[154:155]
	ds_read_b128 v[178:181], v198 offset:32768
	ds_read_b128 v[182:185], v198 offset:33792
	ds_read_b128 v[200:203], v198 offset:34816
	ds_read_b128 v[204:207], v198 offset:35840
	ds_read_b128 v[208:211], v198 offset:36864
	ds_read_b128 v[212:215], v198 offset:37888
	ds_read_b128 v[216:219], v198 offset:38912
	ds_read_b128 v[220:223], v198 offset:39936
	global_load_lds_dwordx4 v[230:231], off
	v_lshl_add_u64 v[230:231], s[54:55], 0, v[158:159]
	s_mov_b32 m0, s61
	s_nop 0
	global_load_lds_dwordx4 v[230:231], off
	s_waitcnt vmcnt(8)
	s_waitcnt lgkmcnt(0)
	s_barrier
	s_setprio 3
	s_waitcnt lgkmcnt(0)
	v_mfma_f32_16x16x32_bf16 v[126:129], v[130:133], v[178:181], v[126:129]
	v_mfma_f32_16x16x32_bf16 v[122:125], v[138:141], v[178:181], v[122:125]
	v_mfma_f32_16x16x32_bf16 v[110:113], v[130:133], v[200:203], v[110:113]
	v_mfma_f32_16x16x32_bf16 v[106:109], v[138:141], v[200:203], v[106:109]
	v_mfma_f32_16x16x32_bf16 v[94:97], v[130:133], v[208:211], v[94:97]
	v_mfma_f32_16x16x32_bf16 v[90:93], v[138:141], v[208:211], v[90:93]
	v_mfma_f32_16x16x32_bf16 v[78:81], v[130:133], v[216:219], v[78:81]
	v_mfma_f32_16x16x32_bf16 v[74:77], v[138:141], v[216:219], v[74:77]
	v_mfma_f32_16x16x32_bf16 v[126:129], v[134:137], v[182:185], v[126:129]
	v_mfma_f32_16x16x32_bf16 v[122:125], v[142:145], v[182:185], v[122:125]
	v_mfma_f32_16x16x32_bf16 v[110:113], v[134:137], v[204:207], v[110:113]
	v_mfma_f32_16x16x32_bf16 v[106:109], v[142:145], v[204:207], v[106:109]
	v_mfma_f32_16x16x32_bf16 v[94:97], v[134:137], v[212:215], v[94:97]
	v_mfma_f32_16x16x32_bf16 v[90:93], v[142:145], v[212:215], v[90:93]
	v_mfma_f32_16x16x32_bf16 v[78:81], v[134:137], v[220:223], v[78:81]
	v_mfma_f32_16x16x32_bf16 v[74:77], v[142:145], v[220:223], v[74:77]
	v_mfma_f32_16x16x32_bf16 v[118:121], v[146:149], v[178:181], v[118:121]
	v_mfma_f32_16x16x32_bf16 v[114:117], v[170:173], v[178:181], v[114:117]
	v_mfma_f32_16x16x32_bf16 v[102:105], v[146:149], v[200:203], v[102:105]
	v_mfma_f32_16x16x32_bf16 v[98:101], v[170:173], v[200:203], v[98:101]
	v_mfma_f32_16x16x32_bf16 v[86:89], v[146:149], v[208:211], v[86:89]
	v_mfma_f32_16x16x32_bf16 v[82:85], v[170:173], v[208:211], v[82:85]
	v_mfma_f32_16x16x32_bf16 v[70:73], v[146:149], v[216:219], v[70:73]
	v_mfma_f32_16x16x32_bf16 v[66:69], v[170:173], v[216:219], v[66:69]
	v_mfma_f32_16x16x32_bf16 v[118:121], v[150:153], v[182:185], v[118:121]
	v_mfma_f32_16x16x32_bf16 v[114:117], v[174:177], v[182:185], v[114:117]
	v_mfma_f32_16x16x32_bf16 v[102:105], v[150:153], v[204:207], v[102:105]
	v_mfma_f32_16x16x32_bf16 v[98:101], v[174:177], v[204:207], v[98:101]
	v_mfma_f32_16x16x32_bf16 v[86:89], v[150:153], v[212:215], v[86:89]
	v_mfma_f32_16x16x32_bf16 v[82:85], v[174:177], v[212:215], v[82:85]
	v_mfma_f32_16x16x32_bf16 v[70:73], v[150:153], v[220:223], v[70:73]
	v_mfma_f32_16x16x32_bf16 v[66:69], v[174:177], v[220:223], v[66:69]
	s_setprio 0
	s_barrier
; #define PG8_STAGE(bufoff, gbase, voff) do { _Pragma("unroll") for (int _i = 0; _i < 2; ++_i) \
;         __builtin_amdgcn_global_load_lds((const unsigned*)((const char*)(gbase) + (voff)[_i]), (LAS unsigned*)(lds + (bufoff) + ldsw + _i * 8192), 16, 0, 0); } while (0)
; #define PG8_LDA(dst, b, h) do { _Pragma("unroll") for (int m = 0; m < 4; ++m) _Pragma("unroll") for (int k = 0; k < 2; ++k) dst[m][k] = *(const LAS bf16x8*)(lds + PG8_SA(b, h) + aoff + m * 2048 + k * 1024); } while (0)
; #define PG8_MMA(ai, bj, At, Bt) do { __builtin_amdgcn_s_setprio(3); _Pragma("unroll") for (int m = 0; m < 4; ++m) _Pragma("unroll") for (int n = 0; n < 2; ++n) _Pragma("unroll") for (int k = 0; k < 2; ++k) \
;         acc[ai][bj][m][n] = __builtin_amdgcn_mfma_f32_16x16x32_bf16(Bt[n][k], At[m][k], acc[ai][bj][m][n], 0, 0, 0); __builtin_amdgcn_s_setprio(0); } while (0)
; #define PG8_WAIT_V(n) asm volatile("s_waitcnt vmcnt(" #n ")" ::: "memory")
; #define PG8_WAIT_L(n) asm volatile("s_waitcnt lgkmcnt(" #n ")" ::: "memory")
; #define PG8_BAR __builtin_amdgcn_s_barrier()
; #define PG8_SCHED __builtin_amdgcn_sched_barrier(0)
; template <class Epi, bool ALIGN_EPI>
; __device__ __forceinline__ void gemm_phase(LAS unsigned char* lds, const Gemm g, const StaticOrder& S, const Epi& E) {
;     ...
;             PG8_LDA(At, 1, 1); PG8_STAGE(PG8_SB(1, 0), b3, voffB); PG8_STAGE(PG8_SB(1, 1), b3 + hstep, voffB); PG8_STAGE(PG8_SA(1, 0), a3, voffA);
;             PG8_WAIT_V(8); PG8_WAIT_L(0); PG8_BAR; PG8_MMA(1, 0, At, B0); PG8_MMA(1, 1, At, B1); PG8_BAR; PG8_SCHED;
	s_add_i32 s54, s78, s57
	v_lshl_add_u64 v[186:187], v[186:187], 0, s[14:15]
	s_mov_b32 m0, s54
	ds_read_b128 v[178:181], v198 offset:49152
	ds_read_b128 v[182:185], v198 offset:50176
	ds_read_b128 v[200:203], v198 offset:51200
	ds_read_b128 v[204:207], v198 offset:52224
	ds_read_b128 v[208:211], v198 offset:53248
	ds_read_b128 v[212:215], v198 offset:54272
	ds_read_b128 v[216:219], v198 offset:55296
	ds_read_b128 v[220:223], v198 offset:56320
	global_load_lds_dwordx4 v[186:187], off
	s_add_i32 m0, s54, 0x2000
	s_add_u32 s52, s52, 0xb0080
	v_lshl_add_u64 v[186:187], v[224:225], 0, s[14:15]
	s_addc_u32 s53, s53, 0
	s_add_i32 s54, s79, s57
	global_load_lds_dwordx4 v[186:187], off
	v_lshl_add_u64 v[186:187], s[52:53], 0, v[156:157]
	s_mov_b32 m0, s54
	s_nop 0
	global_load_lds_dwordx4 v[186:187], off
	v_lshl_add_u64 v[186:187], s[52:53], 0, v[160:161]
	s_add_i32 m0, s54, 0x2000
	s_nop 0
	global_load_lds_dwordx4 v[186:187], off
	v_lshl_add_u64 v[186:187], v[226:227], 0, s[14:15]
	s_mov_b32 m0, s63
	s_nop 0
	global_load_lds_dwordx4 v[186:187], off
	v_lshl_add_u64 v[186:187], v[228:229], 0, s[14:15]
	s_mov_b32 m0, s64
	s_nop 0
	global_load_lds_dwordx4 v[186:187], off
	s_waitcnt vmcnt(8)
	s_waitcnt lgkmcnt(0)
	s_barrier
	s_setprio 3
	s_waitcnt lgkmcnt(0)
	v_mfma_f32_16x16x32_bf16 v[62:65], v[130:133], v[178:181], v[62:65]
	v_mfma_f32_16x16x32_bf16 v[58:61], v[138:141], v[178:181], v[58:61]
	v_mfma_f32_16x16x32_bf16 v[46:49], v[130:133], v[200:203], v[46:49]
	v_mfma_f32_16x16x32_bf16 v[42:45], v[138:141], v[200:203], v[42:45]
	v_mfma_f32_16x16x32_bf16 v[30:33], v[130:133], v[208:211], v[30:33]
	v_mfma_f32_16x16x32_bf16 v[26:29], v[138:141], v[208:211], v[26:29]
	v_mfma_f32_16x16x32_bf16 v[14:17], v[130:133], v[216:219], v[14:17]
	v_mfma_f32_16x16x32_bf16 v[10:13], v[138:141], v[216:219], v[10:13]
	v_mfma_f32_16x16x32_bf16 v[62:65], v[134:137], v[182:185], v[62:65]
	v_mfma_f32_16x16x32_bf16 v[58:61], v[142:145], v[182:185], v[58:61]
	v_mfma_f32_16x16x32_bf16 v[46:49], v[134:137], v[204:207], v[46:49]
	v_mfma_f32_16x16x32_bf16 v[42:45], v[142:145], v[204:207], v[42:45]
	v_mfma_f32_16x16x32_bf16 v[30:33], v[134:137], v[212:215], v[30:33]
	v_mfma_f32_16x16x32_bf16 v[26:29], v[142:145], v[212:215], v[26:29]
	v_mfma_f32_16x16x32_bf16 v[14:17], v[134:137], v[220:223], v[14:17]
	v_mfma_f32_16x16x32_bf16 v[10:13], v[142:145], v[220:223], v[10:13]
	v_mfma_f32_16x16x32_bf16 v[54:57], v[146:149], v[178:181], v[54:57]
	v_mfma_f32_16x16x32_bf16 v[50:53], v[170:173], v[178:181], v[50:53]
	v_mfma_f32_16x16x32_bf16 v[38:41], v[146:149], v[200:203], v[38:41]
	v_mfma_f32_16x16x32_bf16 v[34:37], v[170:173], v[200:203], v[34:37]
	v_mfma_f32_16x16x32_bf16 v[22:25], v[146:149], v[208:211], v[22:25]
	v_mfma_f32_16x16x32_bf16 v[18:21], v[170:173], v[208:211], v[18:21]
	v_mfma_f32_16x16x32_bf16 v[6:9], v[146:149], v[216:219], v[6:9]
	v_mfma_f32_16x16x32_bf16 v[2:5], v[170:173], v[216:219], v[2:5]
	v_mfma_f32_16x16x32_bf16 v[54:57], v[150:153], v[182:185], v[54:57]
	v_mfma_f32_16x16x32_bf16 v[50:53], v[174:177], v[182:185], v[50:53]
	v_mfma_f32_16x16x32_bf16 v[38:41], v[150:153], v[204:207], v[38:41]
	v_mfma_f32_16x16x32_bf16 v[34:37], v[174:177], v[204:207], v[34:37]
	v_mfma_f32_16x16x32_bf16 v[22:25], v[150:153], v[212:215], v[22:25]
	v_mfma_f32_16x16x32_bf16 v[18:21], v[174:177], v[212:215], v[18:21]
	v_mfma_f32_16x16x32_bf16 v[6:9], v[150:153], v[220:223], v[6:9]
	v_mfma_f32_16x16x32_bf16 v[2:5], v[174:177], v[220:223], v[2:5]
	s_setprio 0
	s_barrier
	s_add_i32 s77, s77, 2
	s_add_u32 s50, s50, 0x100
	s_addc_u32 s51, s51, 0
	s_add_u32 s73, s73, 0x100
	s_addc_u32 s76, s76, 0

; #define PG8_STAGE(bufoff, gbase, voff) do { _Pragma("unroll") for (int _i = 0; _i < 2; ++_i) \
;         __builtin_amdgcn_global_load_lds((const unsigned*)((const char*)(gbase) + (voff)[_i]), (LAS unsigned*)(lds + (bufoff) + ldsw + _i * 8192), 16, 0, 0); } while (0)
; #define PG8_WAIT_V(n) asm volatile("s_waitcnt vmcnt(" #n ")" ::: "memory")
; #define PG8_BAR __builtin_amdgcn_s_barrier()
; template <class Epi, bool ALIGN_EPI>
; __device__ __forceinline__ void gemm_phase(LAS unsigned char* lds, const Gemm g, const StaticOrder& S, const Epi& E) {
;     ...
;     const int aoff = lds_byte(wr * 64 + fr, fq * 8), boff = lds_byte(wc * 32 + fr, fq * 8);
;     ...
;     Unit cur, nxt; int ui = 0;
;     if (!S.next(0, cur)) return;
;     f32x4 acc[2][2][4][2];
; #pragma unroll
;     for (int a = 0; a < 2; ++a)
; #pragma unroll
;         for (int b = 0; b < 2; ++b)
; #pragma unroll
;             for (int m = 0; m < 4; ++m)
; #pragma unroll
;                 for (int n = 0; n < 2; ++n) acc[a][b][m][n] = (f32x4){0.f, 0.f, 0.f, 0.f};
;     bf16x8 At[4][2], B0[2][2], B1[2][2];
;     const char* cA = (const char*)g.A + (size_t)cur.pm * tstep; const char* cB = (const char*)g.Bt + (size_t)cur.pn * tstep;
;     PG8_STAGE(PG8_SB(0, 0), cB, voffB); PG8_STAGE(PG8_SB(0, 1), cB + hstep, voffB); PG8_STAGE(PG8_SA(0, 0), cA, voffA); PG8_STAGE(PG8_SA(0, 1), cA + hstep, voffA);
;     if (wr == 1) PG8_BAR;
;     PG8_WAIT_V(2); PG8_BAR;
;     PG8_STAGE(PG8_SB(1, 0), cB + kstep, voffB); PG8_STAGE(PG8_SA(1, 0), cA + kstep, voffA); PG8_STAGE(PG8_SB(1, 1), cB + hstep + kstep, voffB);
;     PG8_WAIT_V(6); PG8_BAR;
;     for (;;) {
;         const bool has_next = S.next(ui + 1, nxt);
.LBB0_781:
	s_ashr_i32 s15, s3, 31
	s_ashr_i32 s12, s2, 31
	s_add_u32 s13, s74, 0x8900000
	s_addc_u32 s52, s75, 0
	s_add_u32 s56, s74, 0x91c0000
	s_addc_u32 s57, s75, 0
	s_add_u32 s53, s74, 0x8100000
	s_addc_u32 s64, s75, 0
	s_add_u32 s58, s74, 0x9180000
	s_mov_b64 s[60:61], 0x80
	s_addc_u32 s59, s75, 0
	s_and_b32 s10, s0, 3
	s_add_i32 m0, s77, 0x18000
	v_lshl_add_u64 v[8:9], v[8:9], 0, s[60:61]
	s_lshl_b32 s11, s9, 13
	s_lshl_b32 s50, s10, 12
	s_waitcnt vmcnt(2)
	s_barrier
	global_load_lds_dwordx4 v[8:9], off
	v_lshl_add_u64 v[4:5], v[4:5], 0, s[60:61]
	s_add_i32 m0, s77, 0x1a000
	s_add_i32 s65, s77, 0x8000
	s_add_i32 s66, s77, 0xa000
	global_load_lds_dwordx4 v[4:5], off
	v_lshl_add_u64 v[2:3], v[2:3], 0, s[60:61]
	s_mov_b32 m0, s65
	s_add_u32 s0, s6, 0x40080
	global_load_lds_dwordx4 v[2:3], off
	v_lshl_add_u64 v[2:3], v[6:7], 0, s[60:61]
	s_mov_b32 m0, s66
	s_addc_u32 s1, s7, 0
	global_load_lds_dwordx4 v[2:3], off
	s_add_i32 m0, s77, 0x1c000
	v_lshl_add_u64 v[2:3], s[0:1], 0, v[148:149]
	global_load_lds_dwordx4 v[2:3], off
	v_lshl_add_u64 v[2:3], s[0:1], 0, v[152:153]
	s_add_i32 m0, s77, 0x1e000
	v_lshlrev_b32_e32 v4, 6, v210
	global_load_lds_dwordx4 v[2:3], off
	v_and_b32_e32 v2, 3, v157
	v_lshlrev_b32_e32 v3, 4, v2
	s_movk_i32 s0, 0x3c0
	v_lshlrev_b32_e32 v156, 3, v2
	v_and_or_b32 v4, v4, s0, v3
	v_cmp_eq_u32_e64 s[0:1], 0, v2
	v_lshl_or_b32 v2, v211, 6, v3
	v_lshlrev_b32_e32 v3, 2, v211
	v_and_b32_e32 v3, 32, v3
	v_and_b32_e32 v5, 32, v214
	v_bitop3_b32 v2, v2, s11, v3 bitop3:0xde
	v_lshlrev_b32_e32 v3, 8, v210
	v_bitop3_b32 v217, s50, v4, v5 bitop3:0xf6
	v_and_b32_e32 v3, 0x38000, v3
	v_lshlrev_b32_e32 v4, 11, v12
	v_or3_b32 v3, v10, v3, v4
	v_add_u32_e32 v158, v3, v11
	v_lshlrev_b32_e32 v3, 4, v13
	s_waitcnt vmcnt(6)
	s_cmpk_lt_u32 s8, 0x100
	v_and_b32_e32 v3, 0x78000, v3
	v_lshl_or_b32 v216, s9, 6, v211
	s_cselect_b64 s[62:63], -1, 0
	v_or3_b32 v3, v10, v3, v4
	s_add_i32 s69, 0, 0x10000
	s_add_i32 s70, 0, 0x14000
	v_add_u32_e32 v222, 0, v2
	v_mbcnt_lo_u32_b32 v2, -1, 0
	v_add_u32_e32 v218, 0xfffff200, v216
	s_lshl_b32 s67, s10, 3
	s_lshl_b32 s68, s10, 6
	v_lshl_or_b32 v219, s10, 5, v156
	v_mov_b32_e32 v159, v155
	v_add_u32_e32 v160, v3, v11
	v_mov_b32_e32 v161, v155
	v_mov_b64_e32 v[162:163], 0x500
	v_mov_b64_e32 v[164:165], 0x4ff
	v_add_u32_e32 v220, s69, v217
	v_add_u32_e32 v221, s70, v217
	v_mov_b32_e32 v223, 0x358637bd
	s_mov_b32 s71, 0x800000
	s_mov_b64 s[96:97], 0x58000
	v_mbcnt_hi_u32_b32 v224, -1, v2
	v_mov_b32_e32 v225, 0x3e38aa3b
	s_mov_b32 s54, 0
	s_barrier
	s_mov_b32 s98, 0
	s_branch .LBB0_784

; #define PG8_BAR __builtin_amdgcn_s_barrier()
; template <class Epi, bool ALIGN_EPI>
; __device__ __forceinline__ void gemm_phase(LAS unsigned char* lds, const Gemm g, const StaticOrder& S, const Epi& E) {
;     ...
;         if (!has_next) break;
; #pragma unroll
;         for (int a = 0; a < 2; ++a)
; #pragma unroll
;             for (int b = 0; b < 2; ++b)
; #pragma unroll
;                 for (int m = 0; m < 4; ++m)
; #pragma unroll
;                     for (int n = 0; n < 2; ++n) acc[a][b][m][n] = (f32x4){0.f, 0.f, 0.f, 0.f};
;         cur = nxt; cA = nA; cB = nB; ++ui;
;         if constexpr (ALIGN_EPI) { if (wr == 1) PG8_BAR; }
;     }
.LBB0_783:
	s_mov_b32 s98, 1
	s_andn2_b64 vcc, exec, s[4:5]
	s_mov_b32 s86, s72
	s_mov_b32 s84, s78
	s_mov_b64 s[6:7], s[82:83]
	s_mov_b64 s[4:5], s[80:81]
	s_cbranch_vccz .LBB0_931

; #define PG8_STAGE(bufoff, gbase, voff) do { _Pragma("unroll") for (int _i = 0; _i < 2; ++_i) \
;         __builtin_amdgcn_global_load_lds((const unsigned*)((const char*)(gbase) + (voff)[_i]), (LAS unsigned*)(lds + (bufoff) + ldsw + _i * 8192), 16, 0, 0); } while (0)
; #define PG8_LDA(dst, b, h) do { _Pragma("unroll") for (int m = 0; m < 4; ++m) _Pragma("unroll") for (int k = 0; k < 2; ++k) dst[m][k] = *(const LAS bf16x8*)(lds + PG8_SA(b, h) + aoff + m * 2048 + k * 1024); } while (0)
; #define PG8_LDB(dst, b, h) do { _Pragma("unroll") for (int n = 0; n < 2; ++n) _Pragma("unroll") for (int k = 0; k < 2; ++k) dst[n][k] = *(const LAS bf16x8*)(lds + PG8_SB(b, h) + boff + n * 2048 + k * 1024); } while (0)
; #define PG8_MMA(ai, bj, At, Bt) do { __builtin_amdgcn_s_setprio(3); _Pragma("unroll") for (int m = 0; m < 4; ++m) _Pragma("unroll") for (int n = 0; n < 2; ++n) _Pragma("unroll") for (int k = 0; k < 2; ++k) \
;         acc[ai][bj][m][n] = __builtin_amdgcn_mfma_f32_16x16x32_bf16(Bt[n][k], At[m][k], acc[ai][bj][m][n], 0, 0, 0); __builtin_amdgcn_s_setprio(0); } while (0)
; #define PG8_WAIT_V(n) asm volatile("s_waitcnt vmcnt(" #n ")" ::: "memory")
; #define PG8_WAIT_L(n) asm volatile("s_waitcnt lgkmcnt(" #n ")" ::: "memory")
; template <class Epi, bool ALIGN_EPI>
; __device__ __forceinline__ void gemm_phase(LAS unsigned char* lds, const Gemm g, const StaticOrder& S, const Epi& E) {
;     ...
;         const bool has_next = S.next(ui + 1, nxt);
;         const char* nA = has_next ? (const char*)g.A + (size_t)nxt.pm * tstep : cA; const char* nB = has_next ? (const char*)g.Bt + (size_t)nxt.pn * tstep : cB;
;         for (int t = 0; t < nt; t += 2) {
;             const bool last = (t == nt - 2);
;             const char* a1 = cA + (size_t)(t + 1) * kstep;
;             const char* a2 = last ? nA : cA + (size_t)(t + 2) * kstep; const char* b2 = last ? nB : cB + (size_t)(t + 2) * kstep;
;             const char* a3 = a2 + kstep; const char* b3 = b2 + kstep;
;             PG8_LDB(B0, 0, 0); PG8_LDB(B1, 0, 1); PG8_SCHED; PG8_LDA(At, 0, 0); PG8_STAGE(PG8_SA(1, 1), a1 + hstep, voffA);
;             PG8_WAIT_V(8); PG8_WAIT_L(0); PG8_BAR; PG8_MMA(0, 0, At, B0); PG8_MMA(0, 1, At, B1); PG8_BAR; PG8_SCHED;
;             PG8_LDA(At, 0, 1); PG8_STAGE(PG8_SB(0, 0), b2, voffB); PG8_STAGE(PG8_SB(0, 1), b2 + hstep, voffB); PG8_STAGE(PG8_SA(0, 0), a2, voffA);
.LBB0_786:
	s_ashr_i32 s79, s78, 31
	s_lshl_b64 s[8:9], s[78:79], 19
	s_add_u32 s80, s34, s8
	s_addc_u32 s81, s35, s9
	s_and_b64 s[8:9], s[10:11], exec
	s_cselect_b32 s50, s81, s5
	s_cselect_b32 s55, s80, s4
	s_ashr_i32 s73, s72, 31
	s_lshl_b64 s[8:9], s[72:73], 19
	s_add_u32 s82, s18, s8
	s_addc_u32 s83, s19, s9
	s_and_b64 s[8:9], s[10:11], exec
	s_cselect_b32 s73, s83, s7
	s_cselect_b32 s79, s82, s6
	s_add_u32 s4, s4, 0x40080
	s_addc_u32 s5, s5, 0
	s_add_u32 s85, s6, 0x100
	s_addc_u32 s88, s7, 0
	s_mov_b32 s89, -2
	s_waitcnt lgkmcnt(0)
	ds_read_b128 v[130:133], v220
	ds_read_b128 v[134:137], v220 offset:1024
	ds_read_b128 v[138:141], v220 offset:2048
	ds_read_b128 v[142:145], v220 offset:3072
	ds_read_b128 v[166:169], v221
	ds_read_b128 v[170:173], v221 offset:1024
	ds_read_b128 v[174:177], v221 offset:2048
	ds_read_b128 v[178:181], v221 offset:3072
	s_add_u32 s6, s4, 0xfffc0080
	s_addc_u32 s7, s5, -1
	s_cmp_eq_u32 s89, 12
	s_cselect_b32 s9, s50, s7
	s_cselect_b32 s8, s55, s6
	s_cselect_b32 s7, s73, s88
	s_cselect_b32 s6, s79, s85
	v_lshl_add_u64 v[230:231], s[4:5], 0, v[158:159]
	s_add_i32 m0, s77, 0xc000
	ds_read_b128 v[182:185], v222
	ds_read_b128 v[186:189], v222 offset:1024
	ds_read_b128 v[190:193], v222 offset:2048
	ds_read_b128 v[194:197], v222 offset:3072
	ds_read_b128 v[198:201], v222 offset:4096
	ds_read_b128 v[202:205], v222 offset:5120
	ds_read_b128 v[206:209], v222 offset:6144
	ds_read_b128 v[226:229], v222 offset:7168
	global_load_lds_dwordx4 v[230:231], off
	v_lshl_add_u64 v[230:231], s[4:5], 0, v[160:161]
	s_add_i32 m0, s77, 0xe000
	s_nop 0
	global_load_lds_dwordx4 v[230:231], off
	s_cmp_lg_u32 s98, 0
	s_cbranch_scc1 .Lmy_rw_787_0
	s_waitcnt vmcnt(8)
.Lmy_rw_787_0:
	s_waitcnt lgkmcnt(0)
	s_barrier
	s_setprio 3
	s_waitcnt lgkmcnt(0)
	v_mfma_f32_16x16x32_bf16 v[126:129], v[130:133], v[182:185], 0
	v_mfma_f32_16x16x32_bf16 v[122:125], v[138:141], v[182:185], 0
	v_mfma_f32_16x16x32_bf16 v[110:113], v[130:133], v[190:193], 0
	v_mfma_f32_16x16x32_bf16 v[106:109], v[138:141], v[190:193], 0
	v_mfma_f32_16x16x32_bf16 v[94:97], v[130:133], v[198:201], 0
	v_mfma_f32_16x16x32_bf16 v[90:93], v[138:141], v[198:201], 0
	v_mfma_f32_16x16x32_bf16 v[78:81], v[130:133], v[206:209], 0
	v_mfma_f32_16x16x32_bf16 v[74:77], v[138:141], v[206:209], 0
	v_mfma_f32_16x16x32_bf16 v[126:129], v[134:137], v[186:189], v[126:129]
	v_mfma_f32_16x16x32_bf16 v[122:125], v[142:145], v[186:189], v[122:125]
	v_mfma_f32_16x16x32_bf16 v[110:113], v[134:137], v[194:197], v[110:113]
	v_mfma_f32_16x16x32_bf16 v[106:109], v[142:145], v[194:197], v[106:109]
	v_mfma_f32_16x16x32_bf16 v[94:97], v[134:137], v[202:205], v[94:97]
	v_mfma_f32_16x16x32_bf16 v[90:93], v[142:145], v[202:205], v[90:93]
	v_mfma_f32_16x16x32_bf16 v[78:81], v[134:137], v[226:229], v[78:81]
	v_mfma_f32_16x16x32_bf16 v[74:77], v[142:145], v[226:229], v[74:77]
	v_mfma_f32_16x16x32_bf16 v[118:121], v[166:169], v[182:185], 0
	v_mfma_f32_16x16x32_bf16 v[114:117], v[174:177], v[182:185], 0
	v_mfma_f32_16x16x32_bf16 v[102:105], v[166:169], v[190:193], 0
	v_mfma_f32_16x16x32_bf16 v[98:101], v[174:177], v[190:193], 0
	v_mfma_f32_16x16x32_bf16 v[86:89], v[166:169], v[198:201], 0
	v_mfma_f32_16x16x32_bf16 v[82:85], v[174:177], v[198:201], 0
	v_mfma_f32_16x16x32_bf16 v[70:73], v[166:169], v[206:209], 0
	v_mfma_f32_16x16x32_bf16 v[66:69], v[174:177], v[206:209], 0
	v_mfma_f32_16x16x32_bf16 v[118:121], v[170:173], v[186:189], v[118:121]
	v_mfma_f32_16x16x32_bf16 v[114:117], v[178:181], v[186:189], v[114:117]
	v_mfma_f32_16x16x32_bf16 v[102:105], v[170:173], v[194:197], v[102:105]
	v_mfma_f32_16x16x32_bf16 v[98:101], v[178:181], v[194:197], v[98:101]
	v_mfma_f32_16x16x32_bf16 v[86:89], v[170:173], v[202:205], v[86:89]
	v_mfma_f32_16x16x32_bf16 v[82:85], v[178:181], v[202:205], v[82:85]
	v_mfma_f32_16x16x32_bf16 v[70:73], v[170:173], v[226:229], v[70:73]
	v_mfma_f32_16x16x32_bf16 v[66:69], v[178:181], v[226:229], v[66:69]
	s_setprio 0
	s_barrier
	s_add_i32 s90, s69, s76
	v_lshl_add_u64 v[230:231], s[6:7], 0, v[148:149]
	s_mov_b32 m0, s90
	ds_read_b128 v[182:185], v222 offset:16384
	ds_read_b128 v[186:189], v222 offset:17408
	ds_read_b128 v[190:193], v222 offset:18432
	ds_read_b128 v[194:197], v222 offset:19456
	ds_read_b128 v[198:201], v222 offset:20480
	ds_read_b128 v[202:205], v222 offset:21504
	ds_read_b128 v[206:209], v222 offset:22528
	ds_read_b128 v[226:229], v222 offset:23552
	global_load_lds_dwordx4 v[230:231], off
	s_add_i32 m0, s90, 0x2000
	s_add_u32 s90, s6, 0x40000
	v_lshl_add_u64 v[232:233], s[6:7], 0, v[152:153]
	s_addc_u32 s91, s7, 0
	s_add_i32 s92, s70, s76
	global_load_lds_dwordx4 v[232:233], off
	v_lshl_add_u64 v[234:235], s[90:91], 0, v[148:149]
	s_mov_b32 m0, s92
	v_lshl_add_u64 v[236:237], s[8:9], 0, v[150:151]
	global_load_lds_dwordx4 v[234:235], off
	v_lshl_add_u64 v[234:235], s[90:91], 0, v[152:153]
	s_add_i32 m0, s92, 0x2000
	s_nop 0
	global_load_lds_dwordx4 v[234:235], off
	v_lshl_add_u64 v[234:235], s[8:9], 0, v[146:147]
	s_mov_b32 m0, s77
	s_nop 0
	global_load_lds_dwordx4 v[234:235], off
	s_mov_b32 m0, s87
	s_nop 0
	global_load_lds_dwordx4 v[236:237], off
	s_cmp_lg_u32 s98, 0
	s_cbranch_scc1 .Lmy_rw_787_1
	s_waitcnt vmcnt(8)
; #define PG8_STAGE(bufoff, gbase, voff) do { _Pragma("unroll") for (int _i = 0; _i < 2; ++_i) \
;         __builtin_amdgcn_global_load_lds((const unsigned*)((const char*)(gbase) + (voff)[_i]), (LAS unsigned*)(lds + (bufoff) + ldsw + _i * 8192), 16, 0, 0); } while (0)
; #define PG8_LDA(dst, b, h) do { _Pragma("unroll") for (int m = 0; m < 4; ++m) _Pragma("unroll") for (int k = 0; k < 2; ++k) dst[m][k] = *(const LAS bf16x8*)(lds + PG8_SA(b, h) + aoff + m * 2048 + k * 1024); } while (0)
; #define PG8_LDB(dst, b, h) do { _Pragma("unroll") for (int n = 0; n < 2; ++n) _Pragma("unroll") for (int k = 0; k < 2; ++k) dst[n][k] = *(const LAS bf16x8*)(lds + PG8_SB(b, h) + boff + n * 2048 + k * 1024); } while (0)
; #define PG8_MMA(ai, bj, At, Bt) do { __builtin_amdgcn_s_setprio(3); _Pragma("unroll") for (int m = 0; m < 4; ++m) _Pragma("unroll") for (int n = 0; n < 2; ++n) _Pragma("unroll") for (int k = 0; k < 2; ++k) \
;         acc[ai][bj][m][n] = __builtin_amdgcn_mfma_f32_16x16x32_bf16(Bt[n][k], At[m][k], acc[ai][bj][m][n], 0, 0, 0); __builtin_amdgcn_s_setprio(0); } while (0)
; #define PG8_WAIT_V(n) asm volatile("s_waitcnt vmcnt(" #n ")" ::: "memory")
; #define PG8_WAIT_L(n) asm volatile("s_waitcnt lgkmcnt(" #n ")" ::: "memory")
; #define PG8_BAR __builtin_amdgcn_s_barrier()
; #define PG8_SCHED __builtin_amdgcn_sched_barrier(0)
; template <class Epi, bool ALIGN_EPI>
; __device__ __forceinline__ void gemm_phase(LAS unsigned char* lds, const Gemm g, const StaticOrder& S, const Epi& E) {
;     ...
;             PG8_WAIT_V(8); PG8_WAIT_L(0); PG8_BAR; PG8_MMA(1, 0, At, B0); PG8_MMA(1, 1, At, B1); PG8_BAR; PG8_SCHED;
;             PG8_LDB(B0, 1, 0); PG8_LDB(B1, 1, 1); PG8_SCHED; PG8_LDA(At, 1, 0); PG8_STAGE(PG8_SA(0, 1), a2 + hstep, voffA);
;             PG8_WAIT_V(8); PG8_WAIT_L(0); PG8_BAR; PG8_MMA(0, 0, At, B0); PG8_MMA(0, 1, At, B1); PG8_BAR; PG8_SCHED;
.Lmy_rw_787_1:
	s_waitcnt lgkmcnt(0)
	s_barrier
	s_setprio 3
	s_waitcnt lgkmcnt(0)
	v_mfma_f32_16x16x32_bf16 v[62:65], v[130:133], v[182:185], 0
	v_mfma_f32_16x16x32_bf16 v[58:61], v[138:141], v[182:185], 0
	v_mfma_f32_16x16x32_bf16 v[46:49], v[130:133], v[190:193], 0
	v_mfma_f32_16x16x32_bf16 v[42:45], v[138:141], v[190:193], 0
	v_mfma_f32_16x16x32_bf16 v[30:33], v[130:133], v[198:201], 0
	v_mfma_f32_16x16x32_bf16 v[26:29], v[138:141], v[198:201], 0
	v_mfma_f32_16x16x32_bf16 v[14:17], v[130:133], v[206:209], 0
	v_mfma_f32_16x16x32_bf16 v[10:13], v[138:141], v[206:209], 0
	v_mfma_f32_16x16x32_bf16 v[62:65], v[134:137], v[186:189], v[62:65]
	v_mfma_f32_16x16x32_bf16 v[58:61], v[142:145], v[186:189], v[58:61]
	v_mfma_f32_16x16x32_bf16 v[46:49], v[134:137], v[194:197], v[46:49]
	v_mfma_f32_16x16x32_bf16 v[42:45], v[142:145], v[194:197], v[42:45]
	v_mfma_f32_16x16x32_bf16 v[30:33], v[134:137], v[202:205], v[30:33]
	v_mfma_f32_16x16x32_bf16 v[26:29], v[142:145], v[202:205], v[26:29]
	v_mfma_f32_16x16x32_bf16 v[14:17], v[134:137], v[226:229], v[14:17]
	v_mfma_f32_16x16x32_bf16 v[10:13], v[142:145], v[226:229], v[10:13]
	v_mfma_f32_16x16x32_bf16 v[54:57], v[166:169], v[182:185], 0
	v_mfma_f32_16x16x32_bf16 v[50:53], v[174:177], v[182:185], 0
	v_mfma_f32_16x16x32_bf16 v[38:41], v[166:169], v[190:193], 0
	v_mfma_f32_16x16x32_bf16 v[34:37], v[174:177], v[190:193], 0
	v_mfma_f32_16x16x32_bf16 v[22:25], v[166:169], v[198:201], 0
	v_mfma_f32_16x16x32_bf16 v[18:21], v[174:177], v[198:201], 0
	v_mfma_f32_16x16x32_bf16 v[6:9], v[166:169], v[206:209], 0
	v_mfma_f32_16x16x32_bf16 v[2:5], v[174:177], v[206:209], 0
	v_mfma_f32_16x16x32_bf16 v[54:57], v[170:173], v[186:189], v[54:57]
	v_mfma_f32_16x16x32_bf16 v[50:53], v[178:181], v[186:189], v[50:53]
	v_mfma_f32_16x16x32_bf16 v[38:41], v[170:173], v[194:197], v[38:41]
	v_mfma_f32_16x16x32_bf16 v[34:37], v[178:181], v[194:197], v[34:37]
	v_mfma_f32_16x16x32_bf16 v[22:25], v[170:173], v[202:205], v[22:25]
	v_mfma_f32_16x16x32_bf16 v[18:21], v[178:181], v[202:205], v[18:21]
	v_mfma_f32_16x16x32_bf16 v[6:9], v[170:173], v[226:229], v[6:9]
	v_mfma_f32_16x16x32_bf16 v[2:5], v[178:181], v[226:229], v[2:5]
	s_setprio 0
	s_barrier
	s_add_i32 s90, 0, 0x18000
	s_add_i32 s91, 0, 0x1c000
	v_add_u32_e32 v142, s90, v217
	v_add_u32_e32 v154, s91, v217
	ds_read_b128 v[130:133], v142
	ds_read_b128 v[134:137], v142 offset:1024
	ds_read_b128 v[138:141], v142 offset:2048
	ds_read_b128 v[142:145], v142 offset:3072
	ds_read_b128 v[166:169], v154
	ds_read_b128 v[170:173], v154 offset:1024
	ds_read_b128 v[174:177], v154 offset:2048
	ds_read_b128 v[178:181], v154 offset:3072
	s_add_u32 s8, s8, 0x40000
	s_addc_u32 s9, s9, 0
	s_mov_b32 m0, s33
	v_lshl_add_u64 v[238:239], s[8:9], 0, v[146:147]
	ds_read_b128 v[182:185], v222 offset:32768
	ds_read_b128 v[186:189], v222 offset:33792
	ds_read_b128 v[190:193], v222 offset:34816
	ds_read_b128 v[194:197], v222 offset:35840
	ds_read_b128 v[198:201], v222 offset:36864
	ds_read_b128 v[202:205], v222 offset:37888
	ds_read_b128 v[206:209], v222 offset:38912
	ds_read_b128 v[226:229], v222 offset:39936
	global_load_lds_dwordx4 v[238:239], off
	v_lshl_add_u64 v[238:239], s[8:9], 0, v[150:151]
	s_mov_b32 m0, s14
	s_nop 0
	global_load_lds_dwordx4 v[238:239], off
	s_waitcnt vmcnt(8)
	s_waitcnt lgkmcnt(0)
	s_barrier
	s_setprio 3
	s_waitcnt lgkmcnt(0)
	v_mfma_f32_16x16x32_bf16 v[126:129], v[130:133], v[182:185], v[126:129]
	v_mfma_f32_16x16x32_bf16 v[122:125], v[138:141], v[182:185], v[122:125]
	v_mfma_f32_16x16x32_bf16 v[110:113], v[130:133], v[190:193], v[110:113]
	v_mfma_f32_16x16x32_bf16 v[106:109], v[138:141], v[190:193], v[106:109]
	v_mfma_f32_16x16x32_bf16 v[94:97], v[130:133], v[198:201], v[94:97]
	v_mfma_f32_16x16x32_bf16 v[90:93], v[138:141], v[198:201], v[90:93]
	v_mfma_f32_16x16x32_bf16 v[78:81], v[130:133], v[206:209], v[78:81]
	v_mfma_f32_16x16x32_bf16 v[74:77], v[138:141], v[206:209], v[74:77]
	v_mfma_f32_16x16x32_bf16 v[126:129], v[134:137], v[186:189], v[126:129]
	v_mfma_f32_16x16x32_bf16 v[122:125], v[142:145], v[186:189], v[122:125]
	v_mfma_f32_16x16x32_bf16 v[110:113], v[134:137], v[194:197], v[110:113]
	v_mfma_f32_16x16x32_bf16 v[106:109], v[142:145], v[194:197], v[106:109]
	v_mfma_f32_16x16x32_bf16 v[94:97], v[134:137], v[202:205], v[94:97]
	v_mfma_f32_16x16x32_bf16 v[90:93], v[142:145], v[202:205], v[90:93]
	v_mfma_f32_16x16x32_bf16 v[78:81], v[134:137], v[226:229], v[78:81]
	v_mfma_f32_16x16x32_bf16 v[74:77], v[142:145], v[226:229], v[74:77]
	v_mfma_f32_16x16x32_bf16 v[118:121], v[166:169], v[182:185], v[118:121]
	v_mfma_f32_16x16x32_bf16 v[114:117], v[174:177], v[182:185], v[114:117]
	v_mfma_f32_16x16x32_bf16 v[102:105], v[166:169], v[190:193], v[102:105]
	v_mfma_f32_16x16x32_bf16 v[98:101], v[174:177], v[190:193], v[98:101]
	v_mfma_f32_16x16x32_bf16 v[86:89], v[166:169], v[198:201], v[86:89]
	v_mfma_f32_16x16x32_bf16 v[82:85], v[174:177], v[198:201], v[82:85]
	v_mfma_f32_16x16x32_bf16 v[70:73], v[166:169], v[206:209], v[70:73]
	v_mfma_f32_16x16x32_bf16 v[66:69], v[174:177], v[206:209], v[66:69]
	v_mfma_f32_16x16x32_bf16 v[118:121], v[170:173], v[186:189], v[118:121]
	v_mfma_f32_16x16x32_bf16 v[114:117], v[178:181], v[186:189], v[114:117]
	v_mfma_f32_16x16x32_bf16 v[102:105], v[170:173], v[194:197], v[102:105]
	v_mfma_f32_16x16x32_bf16 v[98:101], v[178:181], v[194:197], v[98:101]
	v_mfma_f32_16x16x32_bf16 v[86:89], v[170:173], v[202:205], v[86:89]
	v_mfma_f32_16x16x32_bf16 v[82:85], v[178:181], v[202:205], v[82:85]
	v_mfma_f32_16x16x32_bf16 v[70:73], v[170:173], v[226:229], v[70:73]
	v_mfma_f32_16x16x32_bf16 v[66:69], v[178:181], v[226:229], v[66:69]
	s_setprio 0
	s_barrier
; #define PG8_STAGE(bufoff, gbase, voff) do { _Pragma("unroll") for (int _i = 0; _i < 2; ++_i) \
;         __builtin_amdgcn_global_load_lds((const unsigned*)((const char*)(gbase) + (voff)[_i]), (LAS unsigned*)(lds + (bufoff) + ldsw + _i * 8192), 16, 0, 0); } while (0)
; #define PG8_LDA(dst, b, h) do { _Pragma("unroll") for (int m = 0; m < 4; ++m) _Pragma("unroll") for (int k = 0; k < 2; ++k) dst[m][k] = *(const LAS bf16x8*)(lds + PG8_SA(b, h) + aoff + m * 2048 + k * 1024); } while (0)
; #define PG8_MMA(ai, bj, At, Bt) do { __builtin_amdgcn_s_setprio(3); _Pragma("unroll") for (int m = 0; m < 4; ++m) _Pragma("unroll") for (int n = 0; n < 2; ++n) _Pragma("unroll") for (int k = 0; k < 2; ++k) \
;         acc[ai][bj][m][n] = __builtin_amdgcn_mfma_f32_16x16x32_bf16(Bt[n][k], At[m][k], acc[ai][bj][m][n], 0, 0, 0); __builtin_amdgcn_s_setprio(0); } while (0)
; #define PG8_WAIT_V(n) asm volatile("s_waitcnt vmcnt(" #n ")" ::: "memory")
; #define PG8_WAIT_L(n) asm volatile("s_waitcnt lgkmcnt(" #n ")" ::: "memory")
; #define PG8_BAR __builtin_amdgcn_s_barrier()
; #define PG8_SCHED __builtin_amdgcn_sched_barrier(0)
; template <class Epi, bool ALIGN_EPI>
; __device__ __forceinline__ void gemm_phase(LAS unsigned char* lds, const Gemm g, const StaticOrder& S, const Epi& E) {
;     ...
;             PG8_LDA(At, 1, 1); PG8_STAGE(PG8_SB(1, 0), b3, voffB); PG8_STAGE(PG8_SB(1, 1), b3 + hstep, voffB); PG8_STAGE(PG8_SA(1, 0), a3, voffA);
;             PG8_WAIT_V(8); PG8_WAIT_L(0); PG8_BAR; PG8_MMA(1, 0, At, B0); PG8_MMA(1, 1, At, B1); PG8_BAR; PG8_SCHED;
	s_add_i32 s8, s90, s76
	v_lshl_add_u64 v[230:231], v[230:231], 0, s[60:61]
	s_mov_b32 m0, s8
	ds_read_b128 v[182:185], v222 offset:49152
	ds_read_b128 v[186:189], v222 offset:50176
	ds_read_b128 v[190:193], v222 offset:51200
	ds_read_b128 v[194:197], v222 offset:52224
	ds_read_b128 v[198:201], v222 offset:53248
	ds_read_b128 v[202:205], v222 offset:54272
	ds_read_b128 v[206:209], v222 offset:55296
	ds_read_b128 v[226:229], v222 offset:56320
	global_load_lds_dwordx4 v[230:231], off
	s_add_i32 m0, s8, 0x2000
	s_add_u32 s6, s6, 0x40080
	v_lshl_add_u64 v[230:231], v[232:233], 0, s[60:61]
	s_addc_u32 s7, s7, 0
	s_add_i32 s8, s91, s76
	global_load_lds_dwordx4 v[230:231], off
	v_lshl_add_u64 v[230:231], s[6:7], 0, v[148:149]
	s_mov_b32 m0, s8
	s_nop 0
	global_load_lds_dwordx4 v[230:231], off
	v_lshl_add_u64 v[230:231], s[6:7], 0, v[152:153]
	s_add_i32 m0, s8, 0x2000
	s_nop 0
	global_load_lds_dwordx4 v[230:231], off
	v_lshl_add_u64 v[230:231], v[234:235], 0, s[60:61]
	s_mov_b32 m0, s65
	s_nop 0
	global_load_lds_dwordx4 v[230:231], off
	v_lshl_add_u64 v[230:231], v[236:237], 0, s[60:61]
	s_mov_b32 m0, s66
	s_nop 0
	global_load_lds_dwordx4 v[230:231], off
	s_waitcnt vmcnt(8)
	s_waitcnt lgkmcnt(0)
	s_barrier
	s_setprio 3
	s_waitcnt lgkmcnt(0)
	v_mfma_f32_16x16x32_bf16 v[62:65], v[130:133], v[182:185], v[62:65]
	v_mfma_f32_16x16x32_bf16 v[58:61], v[138:141], v[182:185], v[58:61]
	v_mfma_f32_16x16x32_bf16 v[46:49], v[130:133], v[190:193], v[46:49]
	v_mfma_f32_16x16x32_bf16 v[42:45], v[138:141], v[190:193], v[42:45]
	v_mfma_f32_16x16x32_bf16 v[30:33], v[130:133], v[198:201], v[30:33]
	v_mfma_f32_16x16x32_bf16 v[26:29], v[138:141], v[198:201], v[26:29]
	v_mfma_f32_16x16x32_bf16 v[14:17], v[130:133], v[206:209], v[14:17]
	v_mfma_f32_16x16x32_bf16 v[10:13], v[138:141], v[206:209], v[10:13]
	v_mfma_f32_16x16x32_bf16 v[62:65], v[134:137], v[186:189], v[62:65]
	v_mfma_f32_16x16x32_bf16 v[58:61], v[142:145], v[186:189], v[58:61]
	v_mfma_f32_16x16x32_bf16 v[46:49], v[134:137], v[194:197], v[46:49]
	v_mfma_f32_16x16x32_bf16 v[42:45], v[142:145], v[194:197], v[42:45]
	v_mfma_f32_16x16x32_bf16 v[30:33], v[134:137], v[202:205], v[30:33]
	v_mfma_f32_16x16x32_bf16 v[26:29], v[142:145], v[202:205], v[26:29]
	v_mfma_f32_16x16x32_bf16 v[14:17], v[134:137], v[226:229], v[14:17]
	v_mfma_f32_16x16x32_bf16 v[10:13], v[142:145], v[226:229], v[10:13]
	v_mfma_f32_16x16x32_bf16 v[54:57], v[166:169], v[182:185], v[54:57]
	v_mfma_f32_16x16x32_bf16 v[50:53], v[174:177], v[182:185], v[50:53]
	v_mfma_f32_16x16x32_bf16 v[38:41], v[166:169], v[190:193], v[38:41]
	v_mfma_f32_16x16x32_bf16 v[34:37], v[174:177], v[190:193], v[34:37]
	v_mfma_f32_16x16x32_bf16 v[22:25], v[166:169], v[198:201], v[22:25]
	v_mfma_f32_16x16x32_bf16 v[18:21], v[174:177], v[198:201], v[18:21]
	v_mfma_f32_16x16x32_bf16 v[6:9], v[166:169], v[206:209], v[6:9]
	v_mfma_f32_16x16x32_bf16 v[2:5], v[174:177], v[206:209], v[2:5]
	v_mfma_f32_16x16x32_bf16 v[54:57], v[170:173], v[186:189], v[54:57]
	v_mfma_f32_16x16x32_bf16 v[50:53], v[178:181], v[186:189], v[50:53]
	v_mfma_f32_16x16x32_bf16 v[38:41], v[170:173], v[194:197], v[38:41]
	v_mfma_f32_16x16x32_bf16 v[34:37], v[178:181], v[194:197], v[34:37]
	v_mfma_f32_16x16x32_bf16 v[22:25], v[170:173], v[202:205], v[22:25]
	v_mfma_f32_16x16x32_bf16 v[18:21], v[178:181], v[202:205], v[18:21]
	v_mfma_f32_16x16x32_bf16 v[6:9], v[170:173], v[226:229], v[6:9]
	v_mfma_f32_16x16x32_bf16 v[2:5], v[178:181], v[226:229], v[2:5]
	s_setprio 0
	s_barrier
	s_add_i32 s89, s89, 2
	s_add_u32 s4, s4, 0x100
	s_addc_u32 s5, s5, 0
	s_add_u32 s85, s85, 0x100
	s_addc_u32 s88, s88, 0

; #define PG8_STAGE(bufoff, gbase, voff) do { _Pragma("unroll") for (int _i = 0; _i < 2; ++_i) \
;         __builtin_amdgcn_global_load_lds((const unsigned*)((const char*)(gbase) + (voff)[_i]), (LAS unsigned*)(lds + (bufoff) + ldsw + _i * 8192), 16, 0, 0); } while (0)
; #define PG8_WAIT_V(n) asm volatile("s_waitcnt vmcnt(" #n ")" ::: "memory")
; #define PG8_BAR __builtin_amdgcn_s_barrier()
; template <class Epi, bool ALIGN_EPI>
; __device__ __forceinline__ void gemm_phase(LAS unsigned char* lds, const Gemm g, const StaticOrder& S, const Epi& E) {
;     ...
;     const int aoff = lds_byte(wr * 64 + fr, fq * 8), boff = lds_byte(wc * 32 + fr, fq * 8);
;     ...
;     Unit cur, nxt; int ui = 0;
;     if (!S.next(0, cur)) return;
;     f32x4 acc[2][2][4][2];
; #pragma unroll
;     for (int a = 0; a < 2; ++a)
; #pragma unroll
;         for (int b = 0; b < 2; ++b)
; #pragma unroll
;             for (int m = 0; m < 4; ++m)
; #pragma unroll
;                 for (int n = 0; n < 2; ++n) acc[a][b][m][n] = (f32x4){0.f, 0.f, 0.f, 0.f};
;     bf16x8 At[4][2], B0[2][2], B1[2][2];
;     const char* cA = (const char*)g.A + (size_t)cur.pm * tstep; const char* cB = (const char*)g.Bt + (size_t)cur.pn * tstep;
;     PG8_STAGE(PG8_SB(0, 0), cB, voffB); PG8_STAGE(PG8_SB(0, 1), cB + hstep, voffB); PG8_STAGE(PG8_SA(0, 0), cA, voffA); PG8_STAGE(PG8_SA(0, 1), cA + hstep, voffA);
;     if (wr == 1) PG8_BAR;
;     PG8_WAIT_V(2); PG8_BAR;
;     PG8_STAGE(PG8_SB(1, 0), cB + kstep, voffB); PG8_STAGE(PG8_SA(1, 0), cA + kstep, voffA); PG8_STAGE(PG8_SB(1, 1), cB + hstep + kstep, voffB);
;     PG8_WAIT_V(6); PG8_BAR;
;     for (;;) {
;         const bool has_next = S.next(ui + 1, nxt);
.LBB0_1329:
	s_lshl_b32 s1, s1, 5
	s_mov_b64 s[12:13], 0x80
	s_and_b32 s16, s1, 0x60
	s_add_i32 m0, s39, 0x18000
	v_lshl_add_u64 v[8:9], v[8:9], 0, s[12:13]
	s_lshl_b32 s15, s0, 13
	s_lshl_b32 s1, s16, 7
	s_waitcnt vmcnt(2)
	s_barrier
	global_load_lds_dwordx4 v[8:9], off
	v_lshl_add_u64 v[6:7], v[6:7], 0, s[12:13]
	s_add_i32 m0, s39, 0x1a000
	s_add_i32 s52, s39, 0x8000
	s_add_i32 s53, s39, 0xa000
	global_load_lds_dwordx4 v[6:7], off
	v_lshl_add_u64 v[2:3], v[2:3], 0, s[12:13]
	s_mov_b32 m0, s52
	s_add_u32 s4, s42, 0x40080
	global_load_lds_dwordx4 v[2:3], off
	v_lshl_add_u64 v[2:3], v[4:5], 0, s[12:13]
	s_mov_b32 m0, s53
	s_addc_u32 s5, s43, 0
	global_load_lds_dwordx4 v[2:3], off
	s_add_i32 m0, s39, 0x1c000
	v_lshl_add_u64 v[2:3], s[4:5], 0, v[156:157]
	global_load_lds_dwordx4 v[2:3], off
	v_lshl_add_u64 v[2:3], s[4:5], 0, v[160:161]
	s_add_i32 m0, s39, 0x1e000
	v_lshlrev_b32_e32 v5, 2, v190
	global_load_lds_dwordx4 v[2:3], off
	v_and_b32_e32 v2, 3, v188
	v_lshlrev_b32_e32 v3, 4, v2
	v_lshl_or_b32 v4, v190, 6, v3
	v_and_b32_e32 v5, 32, v5
	v_lshl_or_b32 v193, s0, 6, v190
	v_bitop3_b32 v4, v4, s15, v5 bitop3:0xde
	v_lshlrev_b32_e32 v5, 6, v189
	s_movk_i32 s0, 0x3c0
	v_and_or_b32 v3, v5, s0, v3
	v_and_b32_e32 v5, 32, v192
	v_bitop3_b32 v194, s1, v3, v5 bitop3:0xf6
	v_cmp_eq_u32_e64 s[0:1], 0, v2
	v_lshl_or_b32 v195, v2, 3, s16
	v_lshlrev_b32_e32 v2, 8, v189
	v_and_b32_e32 v2, 0x38000, v2
	v_lshlrev_b32_e32 v3, 11, v12
	v_or3_b32 v2, v10, v2, v3
	v_add_u32_e32 v162, v2, v11
	v_lshlrev_b32_e32 v2, 4, v13
	v_and_b32_e32 v2, 0x78000, v2
	s_waitcnt vmcnt(6)
	s_cmpk_lt_u32 s14, 0x100
	v_or3_b32 v2, v10, v2, v3
	s_cselect_b64 s[14:15], -1, 0
	v_add_u32_e32 v164, v2, v11
	s_add_i32 s56, 0, 0x10000
	s_add_i32 s57, 0, 0x14000
	v_mbcnt_lo_u32_b32 v2, -1, 0
	s_ashr_i32 s54, s3, 31
	s_ashr_i32 s55, s2, 31
	v_mov_b32_e32 v163, v157
	v_mov_b32_e32 v165, v157
	v_mov_b64_e32 v[166:167], 0x200
	v_mov_b64_e32 v[168:169], 0x1ff
	v_add_u32_e32 v196, s56, v194
	v_add_u32_e32 v197, s57, v194
	v_add_u32_e32 v198, 0, v4
	v_mbcnt_hi_u32_b32 v199, -1, v2
	s_barrier
	s_mov_b32 s98, 0
	s_branch .LBB0_1332

; #define PG8_BAR __builtin_amdgcn_s_barrier()
; template <class Epi, bool ALIGN_EPI>
; __device__ __forceinline__ void gemm_phase(LAS unsigned char* lds, const Gemm g, const StaticOrder& S, const Epi& E) {
;     ...
;         if (!has_next) break;
; #pragma unroll
;         for (int a = 0; a < 2; ++a)
; #pragma unroll
;             for (int b = 0; b < 2; ++b)
; #pragma unroll
;                 for (int m = 0; m < 4; ++m)
; #pragma unroll
;                     for (int n = 0; n < 2; ++n) acc[a][b][m][n] = (f32x4){0.f, 0.f, 0.f, 0.f};
;         cur = nxt; cA = nA; cB = nB; ++ui;
;         if constexpr (ALIGN_EPI) { if (wr == 1) PG8_BAR; }
;     }
.LBB0_1331:
	s_mov_b32 s98, 1
	s_andn2_b64 vcc, exec, s[4:5]
	s_mov_b32 s38, s16
	s_mov_b32 s36, s18
	s_mov_b64 s[42:43], s[22:23]
	s_mov_b64 s[40:41], s[20:21]
	s_cbranch_vccz .LBB0_1361

; #define PG8_STAGE(bufoff, gbase, voff) do { _Pragma("unroll") for (int _i = 0; _i < 2; ++_i) \
;         __builtin_amdgcn_global_load_lds((const unsigned*)((const char*)(gbase) + (voff)[_i]), (LAS unsigned*)(lds + (bufoff) + ldsw + _i * 8192), 16, 0, 0); } while (0)
; #define PG8_LDA(dst, b, h) do { _Pragma("unroll") for (int m = 0; m < 4; ++m) _Pragma("unroll") for (int k = 0; k < 2; ++k) dst[m][k] = *(const LAS bf16x8*)(lds + PG8_SA(b, h) + aoff + m * 2048 + k * 1024); } while (0)
; #define PG8_LDB(dst, b, h) do { _Pragma("unroll") for (int n = 0; n < 2; ++n) _Pragma("unroll") for (int k = 0; k < 2; ++k) dst[n][k] = *(const LAS bf16x8*)(lds + PG8_SB(b, h) + boff + n * 2048 + k * 1024); } while (0)
; #define PG8_MMA(ai, bj, At, Bt) do { __builtin_amdgcn_s_setprio(3); _Pragma("unroll") for (int m = 0; m < 4; ++m) _Pragma("unroll") for (int n = 0; n < 2; ++n) _Pragma("unroll") for (int k = 0; k < 2; ++k) \
;         acc[ai][bj][m][n] = __builtin_amdgcn_mfma_f32_16x16x32_bf16(Bt[n][k], At[m][k], acc[ai][bj][m][n], 0, 0, 0); __builtin_amdgcn_s_setprio(0); } while (0)
; #define PG8_WAIT_V(n) asm volatile("s_waitcnt vmcnt(" #n ")" ::: "memory")
; #define PG8_WAIT_L(n) asm volatile("s_waitcnt lgkmcnt(" #n ")" ::: "memory")
; template <class Epi, bool ALIGN_EPI>
; __device__ __forceinline__ void gemm_phase(LAS unsigned char* lds, const Gemm g, const StaticOrder& S, const Epi& E) {
;     ...
;         const bool has_next = S.next(ui + 1, nxt);
;         const char* nA = has_next ? (const char*)g.A + (size_t)nxt.pm * tstep : cA; const char* nB = has_next ? (const char*)g.Bt + (size_t)nxt.pn * tstep : cB;
;         for (int t = 0; t < nt; t += 2) {
;             const bool last = (t == nt - 2);
;             const char* a1 = cA + (size_t)(t + 1) * kstep;
;             const char* a2 = last ? nA : cA + (size_t)(t + 2) * kstep; const char* b2 = last ? nB : cB + (size_t)(t + 2) * kstep;
;             const char* a3 = a2 + kstep; const char* b3 = b2 + kstep;
;             PG8_LDB(B0, 0, 0); PG8_LDB(B1, 0, 1); PG8_SCHED; PG8_LDA(At, 0, 0); PG8_STAGE(PG8_SA(1, 1), a1 + hstep, voffA);
;             PG8_WAIT_V(8); PG8_WAIT_L(0); PG8_BAR; PG8_MMA(0, 0, At, B0); PG8_MMA(0, 1, At, B1); PG8_BAR; PG8_SCHED;
;             PG8_LDA(At, 0, 1); PG8_STAGE(PG8_SB(0, 0), b2, voffB); PG8_STAGE(PG8_SB(0, 1), b2 + hstep, voffB); PG8_STAGE(PG8_SA(0, 0), a2, voffA);
.LBB0_1338:
	s_ashr_i32 s19, s18, 31
	s_lshl_b64 s[20:21], s[18:19], 19
	s_add_u32 s20, s26, s20
	s_addc_u32 s21, s27, s21
	s_and_b64 s[22:23], s[4:5], exec
	s_cselect_b32 s19, s21, s41
	s_cselect_b32 s37, s20, s40
	s_ashr_i32 s17, s16, 31
	s_lshl_b64 s[22:23], s[16:17], 19
	s_add_u32 s22, s33, s22
	s_addc_u32 s23, s46, s23
	s_and_b64 s[44:45], s[4:5], exec
	s_cselect_b32 s17, s23, s43
	s_cselect_b32 s58, s22, s42
	s_add_u32 s40, s40, 0x40080
	s_addc_u32 s41, s41, 0
	s_add_u32 s59, s42, 0x100
	s_addc_u32 s60, s43, 0
	s_mov_b32 s61, -2
	s_waitcnt lgkmcnt(0)
	ds_read_b128 v[130:133], v196
	ds_read_b128 v[134:137], v196 offset:1024
	ds_read_b128 v[138:141], v196 offset:2048
	ds_read_b128 v[142:145], v196 offset:3072
	ds_read_b128 v[146:149], v197
	ds_read_b128 v[150:153], v197 offset:1024
	ds_read_b128 v[170:173], v197 offset:2048
	ds_read_b128 v[174:177], v197 offset:3072
	s_add_u32 s42, s40, 0xfffc0080
	s_addc_u32 s43, s41, -1
	s_cmp_eq_u32 s61, 12
	s_cselect_b32 s45, s19, s43
	s_cselect_b32 s44, s37, s42
	s_cselect_b32 s43, s17, s60
	s_cselect_b32 s42, s58, s59
	v_lshl_add_u64 v[186:187], s[40:41], 0, v[162:163]
	s_add_i32 m0, s39, 0xc000
	ds_read_b128 v[178:181], v198
	ds_read_b128 v[182:185], v198 offset:1024
	ds_read_b128 v[200:203], v198 offset:2048
	ds_read_b128 v[204:207], v198 offset:3072
	ds_read_b128 v[208:211], v198 offset:4096
	ds_read_b128 v[212:215], v198 offset:5120
	ds_read_b128 v[216:219], v198 offset:6144
	ds_read_b128 v[220:223], v198 offset:7168
	global_load_lds_dwordx4 v[186:187], off
	v_lshl_add_u64 v[186:187], s[40:41], 0, v[164:165]
	s_add_i32 m0, s39, 0xe000
	s_nop 0
	global_load_lds_dwordx4 v[186:187], off
	s_cmp_lg_u32 s98, 0
	s_cbranch_scc1 .Lmy_rw_1339_0
	s_waitcnt vmcnt(8)
.Lmy_rw_1339_0:
	s_waitcnt lgkmcnt(0)
	s_barrier
	s_setprio 3
	s_waitcnt lgkmcnt(0)
	v_mfma_f32_16x16x32_bf16 v[126:129], v[130:133], v[178:181], 0
	v_mfma_f32_16x16x32_bf16 v[122:125], v[138:141], v[178:181], 0
	v_mfma_f32_16x16x32_bf16 v[110:113], v[130:133], v[200:203], 0
	v_mfma_f32_16x16x32_bf16 v[106:109], v[138:141], v[200:203], 0
	v_mfma_f32_16x16x32_bf16 v[94:97], v[130:133], v[208:211], 0
	v_mfma_f32_16x16x32_bf16 v[90:93], v[138:141], v[208:211], 0
	v_mfma_f32_16x16x32_bf16 v[78:81], v[130:133], v[216:219], 0
	v_mfma_f32_16x16x32_bf16 v[74:77], v[138:141], v[216:219], 0
	v_mfma_f32_16x16x32_bf16 v[126:129], v[134:137], v[182:185], v[126:129]
	v_mfma_f32_16x16x32_bf16 v[122:125], v[142:145], v[182:185], v[122:125]
	v_mfma_f32_16x16x32_bf16 v[110:113], v[134:137], v[204:207], v[110:113]
	v_mfma_f32_16x16x32_bf16 v[106:109], v[142:145], v[204:207], v[106:109]
	v_mfma_f32_16x16x32_bf16 v[94:97], v[134:137], v[212:215], v[94:97]
	v_mfma_f32_16x16x32_bf16 v[90:93], v[142:145], v[212:215], v[90:93]
	v_mfma_f32_16x16x32_bf16 v[78:81], v[134:137], v[220:223], v[78:81]
	v_mfma_f32_16x16x32_bf16 v[74:77], v[142:145], v[220:223], v[74:77]
	v_mfma_f32_16x16x32_bf16 v[118:121], v[146:149], v[178:181], 0
	v_mfma_f32_16x16x32_bf16 v[114:117], v[170:173], v[178:181], 0
	v_mfma_f32_16x16x32_bf16 v[102:105], v[146:149], v[200:203], 0
	v_mfma_f32_16x16x32_bf16 v[98:101], v[170:173], v[200:203], 0
	v_mfma_f32_16x16x32_bf16 v[86:89], v[146:149], v[208:211], 0
	v_mfma_f32_16x16x32_bf16 v[82:85], v[170:173], v[208:211], 0
	v_mfma_f32_16x16x32_bf16 v[70:73], v[146:149], v[216:219], 0
	v_mfma_f32_16x16x32_bf16 v[66:69], v[170:173], v[216:219], 0
	v_mfma_f32_16x16x32_bf16 v[118:121], v[150:153], v[182:185], v[118:121]
	v_mfma_f32_16x16x32_bf16 v[114:117], v[174:177], v[182:185], v[114:117]
	v_mfma_f32_16x16x32_bf16 v[102:105], v[150:153], v[204:207], v[102:105]
	v_mfma_f32_16x16x32_bf16 v[98:101], v[174:177], v[204:207], v[98:101]
	v_mfma_f32_16x16x32_bf16 v[86:89], v[150:153], v[212:215], v[86:89]
	v_mfma_f32_16x16x32_bf16 v[82:85], v[174:177], v[212:215], v[82:85]
	v_mfma_f32_16x16x32_bf16 v[70:73], v[150:153], v[220:223], v[70:73]
	v_mfma_f32_16x16x32_bf16 v[66:69], v[174:177], v[220:223], v[66:69]
	s_setprio 0
	s_barrier
	s_add_i32 s62, s56, s47
	v_lshl_add_u64 v[186:187], s[42:43], 0, v[156:157]
	s_mov_b32 m0, s62
	ds_read_b128 v[178:181], v198 offset:16384
	ds_read_b128 v[182:185], v198 offset:17408
	ds_read_b128 v[200:203], v198 offset:18432
	ds_read_b128 v[204:207], v198 offset:19456
	ds_read_b128 v[208:211], v198 offset:20480
	ds_read_b128 v[212:215], v198 offset:21504
	ds_read_b128 v[216:219], v198 offset:22528
	ds_read_b128 v[220:223], v198 offset:23552
	global_load_lds_dwordx4 v[186:187], off
	s_add_i32 m0, s62, 0x2000
	s_add_u32 s62, s42, 0x40000
	v_lshl_add_u64 v[224:225], s[42:43], 0, v[160:161]
	s_addc_u32 s63, s43, 0
	s_add_i32 s64, s57, s47
	global_load_lds_dwordx4 v[224:225], off
	v_lshl_add_u64 v[226:227], s[62:63], 0, v[156:157]
	s_mov_b32 m0, s64
	v_lshl_add_u64 v[228:229], s[44:45], 0, v[158:159]
	global_load_lds_dwordx4 v[226:227], off
	v_lshl_add_u64 v[226:227], s[62:63], 0, v[160:161]
	s_add_i32 m0, s64, 0x2000
	s_nop 0
	global_load_lds_dwordx4 v[226:227], off
	v_lshl_add_u64 v[226:227], s[44:45], 0, v[154:155]
	s_mov_b32 m0, s39
	s_nop 0
	global_load_lds_dwordx4 v[226:227], off
	s_mov_b32 m0, s48
	s_nop 0
	global_load_lds_dwordx4 v[228:229], off
	s_cmp_lg_u32 s98, 0
	s_cbranch_scc1 .Lmy_rw_1339_1
	s_waitcnt vmcnt(8)
; #define PG8_STAGE(bufoff, gbase, voff) do { _Pragma("unroll") for (int _i = 0; _i < 2; ++_i) \
;         __builtin_amdgcn_global_load_lds((const unsigned*)((const char*)(gbase) + (voff)[_i]), (LAS unsigned*)(lds + (bufoff) + ldsw + _i * 8192), 16, 0, 0); } while (0)
; #define PG8_LDA(dst, b, h) do { _Pragma("unroll") for (int m = 0; m < 4; ++m) _Pragma("unroll") for (int k = 0; k < 2; ++k) dst[m][k] = *(const LAS bf16x8*)(lds + PG8_SA(b, h) + aoff + m * 2048 + k * 1024); } while (0)
; #define PG8_LDB(dst, b, h) do { _Pragma("unroll") for (int n = 0; n < 2; ++n) _Pragma("unroll") for (int k = 0; k < 2; ++k) dst[n][k] = *(const LAS bf16x8*)(lds + PG8_SB(b, h) + boff + n * 2048 + k * 1024); } while (0)
; #define PG8_MMA(ai, bj, At, Bt) do { __builtin_amdgcn_s_setprio(3); _Pragma("unroll") for (int m = 0; m < 4; ++m) _Pragma("unroll") for (int n = 0; n < 2; ++n) _Pragma("unroll") for (int k = 0; k < 2; ++k) \
;         acc[ai][bj][m][n] = __builtin_amdgcn_mfma_f32_16x16x32_bf16(Bt[n][k], At[m][k], acc[ai][bj][m][n], 0, 0, 0); __builtin_amdgcn_s_setprio(0); } while (0)
; #define PG8_WAIT_V(n) asm volatile("s_waitcnt vmcnt(" #n ")" ::: "memory")
; #define PG8_WAIT_L(n) asm volatile("s_waitcnt lgkmcnt(" #n ")" ::: "memory")
; #define PG8_BAR __builtin_amdgcn_s_barrier()
; #define PG8_SCHED __builtin_amdgcn_sched_barrier(0)
; template <class Epi, bool ALIGN_EPI>
; __device__ __forceinline__ void gemm_phase(LAS unsigned char* lds, const Gemm g, const StaticOrder& S, const Epi& E) {
;     ...
;             PG8_WAIT_V(8); PG8_WAIT_L(0); PG8_BAR; PG8_MMA(1, 0, At, B0); PG8_MMA(1, 1, At, B1); PG8_BAR; PG8_SCHED;
;             PG8_LDB(B0, 1, 0); PG8_LDB(B1, 1, 1); PG8_SCHED; PG8_LDA(At, 1, 0); PG8_STAGE(PG8_SA(0, 1), a2 + hstep, voffA);
;             PG8_WAIT_V(8); PG8_WAIT_L(0); PG8_BAR; PG8_MMA(0, 0, At, B0); PG8_MMA(0, 1, At, B1); PG8_BAR; PG8_SCHED;
.Lmy_rw_1339_1:
	s_waitcnt lgkmcnt(0)
	s_barrier
	s_setprio 3
	s_waitcnt lgkmcnt(0)
	v_mfma_f32_16x16x32_bf16 v[62:65], v[130:133], v[178:181], 0
	v_mfma_f32_16x16x32_bf16 v[58:61], v[138:141], v[178:181], 0
	v_mfma_f32_16x16x32_bf16 v[46:49], v[130:133], v[200:203], 0
	v_mfma_f32_16x16x32_bf16 v[42:45], v[138:141], v[200:203], 0
	v_mfma_f32_16x16x32_bf16 v[30:33], v[130:133], v[208:211], 0
	v_mfma_f32_16x16x32_bf16 v[26:29], v[138:141], v[208:211], 0
	v_mfma_f32_16x16x32_bf16 v[14:17], v[130:133], v[216:219], 0
	v_mfma_f32_16x16x32_bf16 v[10:13], v[138:141], v[216:219], 0
	v_mfma_f32_16x16x32_bf16 v[62:65], v[134:137], v[182:185], v[62:65]
	v_mfma_f32_16x16x32_bf16 v[58:61], v[142:145], v[182:185], v[58:61]
	v_mfma_f32_16x16x32_bf16 v[46:49], v[134:137], v[204:207], v[46:49]
	v_mfma_f32_16x16x32_bf16 v[42:45], v[142:145], v[204:207], v[42:45]
	v_mfma_f32_16x16x32_bf16 v[30:33], v[134:137], v[212:215], v[30:33]
	v_mfma_f32_16x16x32_bf16 v[26:29], v[142:145], v[212:215], v[26:29]
	v_mfma_f32_16x16x32_bf16 v[14:17], v[134:137], v[220:223], v[14:17]
	v_mfma_f32_16x16x32_bf16 v[10:13], v[142:145], v[220:223], v[10:13]
	v_mfma_f32_16x16x32_bf16 v[54:57], v[146:149], v[178:181], 0
	v_mfma_f32_16x16x32_bf16 v[50:53], v[170:173], v[178:181], 0
	v_mfma_f32_16x16x32_bf16 v[38:41], v[146:149], v[200:203], 0
	v_mfma_f32_16x16x32_bf16 v[34:37], v[170:173], v[200:203], 0
	v_mfma_f32_16x16x32_bf16 v[22:25], v[146:149], v[208:211], 0
	v_mfma_f32_16x16x32_bf16 v[18:21], v[170:173], v[208:211], 0
	v_mfma_f32_16x16x32_bf16 v[6:9], v[146:149], v[216:219], 0
	v_mfma_f32_16x16x32_bf16 v[2:5], v[170:173], v[216:219], 0
	v_mfma_f32_16x16x32_bf16 v[54:57], v[150:153], v[182:185], v[54:57]
	v_mfma_f32_16x16x32_bf16 v[50:53], v[174:177], v[182:185], v[50:53]
	v_mfma_f32_16x16x32_bf16 v[38:41], v[150:153], v[204:207], v[38:41]
	v_mfma_f32_16x16x32_bf16 v[34:37], v[174:177], v[204:207], v[34:37]
	v_mfma_f32_16x16x32_bf16 v[22:25], v[150:153], v[212:215], v[22:25]
	v_mfma_f32_16x16x32_bf16 v[18:21], v[174:177], v[212:215], v[18:21]
	v_mfma_f32_16x16x32_bf16 v[6:9], v[150:153], v[220:223], v[6:9]
	v_mfma_f32_16x16x32_bf16 v[2:5], v[174:177], v[220:223], v[2:5]
	s_setprio 0
	s_barrier
	s_add_i32 s62, 0, 0x18000
	s_add_i32 s63, 0, 0x1c000
	v_add_u32_e32 v142, s62, v194
	v_add_u32_e32 v174, s63, v194
	ds_read_b128 v[130:133], v142
	ds_read_b128 v[134:137], v142 offset:1024
	ds_read_b128 v[138:141], v142 offset:2048
	ds_read_b128 v[142:145], v142 offset:3072
	ds_read_b128 v[146:149], v174
	ds_read_b128 v[150:153], v174 offset:1024
	ds_read_b128 v[170:173], v174 offset:2048
	ds_read_b128 v[174:177], v174 offset:3072
	s_add_u32 s44, s44, 0x40000
	s_addc_u32 s45, s45, 0
	s_mov_b32 m0, s49
	v_lshl_add_u64 v[230:231], s[44:45], 0, v[154:155]
	ds_read_b128 v[178:181], v198 offset:32768
	ds_read_b128 v[182:185], v198 offset:33792
	ds_read_b128 v[200:203], v198 offset:34816
	ds_read_b128 v[204:207], v198 offset:35840
	ds_read_b128 v[208:211], v198 offset:36864
	ds_read_b128 v[212:215], v198 offset:37888
	ds_read_b128 v[216:219], v198 offset:38912
	ds_read_b128 v[220:223], v198 offset:39936
	global_load_lds_dwordx4 v[230:231], off
	v_lshl_add_u64 v[230:231], s[44:45], 0, v[158:159]
	s_mov_b32 m0, s50
	s_nop 0
	global_load_lds_dwordx4 v[230:231], off
	s_waitcnt vmcnt(8)
	s_waitcnt lgkmcnt(0)
	s_barrier
	s_setprio 3
	s_waitcnt lgkmcnt(0)
	v_mfma_f32_16x16x32_bf16 v[126:129], v[130:133], v[178:181], v[126:129]
	v_mfma_f32_16x16x32_bf16 v[122:125], v[138:141], v[178:181], v[122:125]
	v_mfma_f32_16x16x32_bf16 v[110:113], v[130:133], v[200:203], v[110:113]
	v_mfma_f32_16x16x32_bf16 v[106:109], v[138:141], v[200:203], v[106:109]
	v_mfma_f32_16x16x32_bf16 v[94:97], v[130:133], v[208:211], v[94:97]
	v_mfma_f32_16x16x32_bf16 v[90:93], v[138:141], v[208:211], v[90:93]
	v_mfma_f32_16x16x32_bf16 v[78:81], v[130:133], v[216:219], v[78:81]
	v_mfma_f32_16x16x32_bf16 v[74:77], v[138:141], v[216:219], v[74:77]
	v_mfma_f32_16x16x32_bf16 v[126:129], v[134:137], v[182:185], v[126:129]
	v_mfma_f32_16x16x32_bf16 v[122:125], v[142:145], v[182:185], v[122:125]
	v_mfma_f32_16x16x32_bf16 v[110:113], v[134:137], v[204:207], v[110:113]
	v_mfma_f32_16x16x32_bf16 v[106:109], v[142:145], v[204:207], v[106:109]
	v_mfma_f32_16x16x32_bf16 v[94:97], v[134:137], v[212:215], v[94:97]
	v_mfma_f32_16x16x32_bf16 v[90:93], v[142:145], v[212:215], v[90:93]
	v_mfma_f32_16x16x32_bf16 v[78:81], v[134:137], v[220:223], v[78:81]
	v_mfma_f32_16x16x32_bf16 v[74:77], v[142:145], v[220:223], v[74:77]
	v_mfma_f32_16x16x32_bf16 v[118:121], v[146:149], v[178:181], v[118:121]
	v_mfma_f32_16x16x32_bf16 v[114:117], v[170:173], v[178:181], v[114:117]
	v_mfma_f32_16x16x32_bf16 v[102:105], v[146:149], v[200:203], v[102:105]
	v_mfma_f32_16x16x32_bf16 v[98:101], v[170:173], v[200:203], v[98:101]
	v_mfma_f32_16x16x32_bf16 v[86:89], v[146:149], v[208:211], v[86:89]
	v_mfma_f32_16x16x32_bf16 v[82:85], v[170:173], v[208:211], v[82:85]
	v_mfma_f32_16x16x32_bf16 v[70:73], v[146:149], v[216:219], v[70:73]
	v_mfma_f32_16x16x32_bf16 v[66:69], v[170:173], v[216:219], v[66:69]
	v_mfma_f32_16x16x32_bf16 v[118:121], v[150:153], v[182:185], v[118:121]
	v_mfma_f32_16x16x32_bf16 v[114:117], v[174:177], v[182:185], v[114:117]
	v_mfma_f32_16x16x32_bf16 v[102:105], v[150:153], v[204:207], v[102:105]
	v_mfma_f32_16x16x32_bf16 v[98:101], v[174:177], v[204:207], v[98:101]
	v_mfma_f32_16x16x32_bf16 v[86:89], v[150:153], v[212:215], v[86:89]
	v_mfma_f32_16x16x32_bf16 v[82:85], v[174:177], v[212:215], v[82:85]
	v_mfma_f32_16x16x32_bf16 v[70:73], v[150:153], v[220:223], v[70:73]
	v_mfma_f32_16x16x32_bf16 v[66:69], v[174:177], v[220:223], v[66:69]
	s_setprio 0
	s_barrier
; #define PG8_STAGE(bufoff, gbase, voff) do { _Pragma("unroll") for (int _i = 0; _i < 2; ++_i) \
;         __builtin_amdgcn_global_load_lds((const unsigned*)((const char*)(gbase) + (voff)[_i]), (LAS unsigned*)(lds + (bufoff) + ldsw + _i * 8192), 16, 0, 0); } while (0)
; #define PG8_LDA(dst, b, h) do { _Pragma("unroll") for (int m = 0; m < 4; ++m) _Pragma("unroll") for (int k = 0; k < 2; ++k) dst[m][k] = *(const LAS bf16x8*)(lds + PG8_SA(b, h) + aoff + m * 2048 + k * 1024); } while (0)
; #define PG8_MMA(ai, bj, At, Bt) do { __builtin_amdgcn_s_setprio(3); _Pragma("unroll") for (int m = 0; m < 4; ++m) _Pragma("unroll") for (int n = 0; n < 2; ++n) _Pragma("unroll") for (int k = 0; k < 2; ++k) \
;         acc[ai][bj][m][n] = __builtin_amdgcn_mfma_f32_16x16x32_bf16(Bt[n][k], At[m][k], acc[ai][bj][m][n], 0, 0, 0); __builtin_amdgcn_s_setprio(0); } while (0)
; #define PG8_WAIT_V(n) asm volatile("s_waitcnt vmcnt(" #n ")" ::: "memory")
; #define PG8_WAIT_L(n) asm volatile("s_waitcnt lgkmcnt(" #n ")" ::: "memory")
; #define PG8_BAR __builtin_amdgcn_s_barrier()
; #define PG8_SCHED __builtin_amdgcn_sched_barrier(0)
; template <class Epi, bool ALIGN_EPI>
; __device__ __forceinline__ void gemm_phase(LAS unsigned char* lds, const Gemm g, const StaticOrder& S, const Epi& E) {
;     ...
;             PG8_LDA(At, 1, 1); PG8_STAGE(PG8_SB(1, 0), b3, voffB); PG8_STAGE(PG8_SB(1, 1), b3 + hstep, voffB); PG8_STAGE(PG8_SA(1, 0), a3, voffA);
;             PG8_WAIT_V(8); PG8_WAIT_L(0); PG8_BAR; PG8_MMA(1, 0, At, B0); PG8_MMA(1, 1, At, B1); PG8_BAR; PG8_SCHED;
	s_add_i32 s44, s62, s47
	v_lshl_add_u64 v[186:187], v[186:187], 0, s[12:13]
	s_mov_b32 m0, s44
	ds_read_b128 v[178:181], v198 offset:49152
	ds_read_b128 v[182:185], v198 offset:50176
	ds_read_b128 v[200:203], v198 offset:51200
	ds_read_b128 v[204:207], v198 offset:52224
	ds_read_b128 v[208:211], v198 offset:53248
	ds_read_b128 v[212:215], v198 offset:54272
	ds_read_b128 v[216:219], v198 offset:55296
	ds_read_b128 v[220:223], v198 offset:56320
	global_load_lds_dwordx4 v[186:187], off
	s_add_i32 m0, s44, 0x2000
	s_add_u32 s42, s42, 0x40080
	v_lshl_add_u64 v[186:187], v[224:225], 0, s[12:13]
	s_addc_u32 s43, s43, 0
	s_add_i32 s44, s63, s47
	global_load_lds_dwordx4 v[186:187], off
	v_lshl_add_u64 v[186:187], s[42:43], 0, v[156:157]
	s_mov_b32 m0, s44
	s_nop 0
	global_load_lds_dwordx4 v[186:187], off
	v_lshl_add_u64 v[186:187], s[42:43], 0, v[160:161]
	s_add_i32 m0, s44, 0x2000
	s_nop 0
	global_load_lds_dwordx4 v[186:187], off
	v_lshl_add_u64 v[186:187], v[226:227], 0, s[12:13]
	s_mov_b32 m0, s52
	s_nop 0
	global_load_lds_dwordx4 v[186:187], off
	v_lshl_add_u64 v[186:187], v[228:229], 0, s[12:13]
	s_mov_b32 m0, s53
	s_nop 0
	global_load_lds_dwordx4 v[186:187], off
	s_waitcnt vmcnt(8)
	s_waitcnt lgkmcnt(0)
	s_barrier
	s_setprio 3
	s_waitcnt lgkmcnt(0)
	v_mfma_f32_16x16x32_bf16 v[62:65], v[130:133], v[178:181], v[62:65]
	v_mfma_f32_16x16x32_bf16 v[58:61], v[138:141], v[178:181], v[58:61]
	v_mfma_f32_16x16x32_bf16 v[46:49], v[130:133], v[200:203], v[46:49]
	v_mfma_f32_16x16x32_bf16 v[42:45], v[138:141], v[200:203], v[42:45]
	v_mfma_f32_16x16x32_bf16 v[30:33], v[130:133], v[208:211], v[30:33]
	v_mfma_f32_16x16x32_bf16 v[26:29], v[138:141], v[208:211], v[26:29]
	v_mfma_f32_16x16x32_bf16 v[14:17], v[130:133], v[216:219], v[14:17]
	v_mfma_f32_16x16x32_bf16 v[10:13], v[138:141], v[216:219], v[10:13]
	v_mfma_f32_16x16x32_bf16 v[62:65], v[134:137], v[182:185], v[62:65]
	v_mfma_f32_16x16x32_bf16 v[58:61], v[142:145], v[182:185], v[58:61]
	v_mfma_f32_16x16x32_bf16 v[46:49], v[134:137], v[204:207], v[46:49]
	v_mfma_f32_16x16x32_bf16 v[42:45], v[142:145], v[204:207], v[42:45]
	v_mfma_f32_16x16x32_bf16 v[30:33], v[134:137], v[212:215], v[30:33]
	v_mfma_f32_16x16x32_bf16 v[26:29], v[142:145], v[212:215], v[26:29]
	v_mfma_f32_16x16x32_bf16 v[14:17], v[134:137], v[220:223], v[14:17]
	v_mfma_f32_16x16x32_bf16 v[10:13], v[142:145], v[220:223], v[10:13]
	v_mfma_f32_16x16x32_bf16 v[54:57], v[146:149], v[178:181], v[54:57]
	v_mfma_f32_16x16x32_bf16 v[50:53], v[170:173], v[178:181], v[50:53]
	v_mfma_f32_16x16x32_bf16 v[38:41], v[146:149], v[200:203], v[38:41]
	v_mfma_f32_16x16x32_bf16 v[34:37], v[170:173], v[200:203], v[34:37]
	v_mfma_f32_16x16x32_bf16 v[22:25], v[146:149], v[208:211], v[22:25]
	v_mfma_f32_16x16x32_bf16 v[18:21], v[170:173], v[208:211], v[18:21]
	v_mfma_f32_16x16x32_bf16 v[6:9], v[146:149], v[216:219], v[6:9]
	v_mfma_f32_16x16x32_bf16 v[2:5], v[170:173], v[216:219], v[2:5]
	v_mfma_f32_16x16x32_bf16 v[54:57], v[150:153], v[182:185], v[54:57]
	v_mfma_f32_16x16x32_bf16 v[50:53], v[174:177], v[182:185], v[50:53]
	v_mfma_f32_16x16x32_bf16 v[38:41], v[150:153], v[204:207], v[38:41]
	v_mfma_f32_16x16x32_bf16 v[34:37], v[174:177], v[204:207], v[34:37]
	v_mfma_f32_16x16x32_bf16 v[22:25], v[150:153], v[212:215], v[22:25]
	v_mfma_f32_16x16x32_bf16 v[18:21], v[174:177], v[212:215], v[18:21]
	v_mfma_f32_16x16x32_bf16 v[6:9], v[150:153], v[220:223], v[6:9]
	v_mfma_f32_16x16x32_bf16 v[2:5], v[174:177], v[220:223], v[2:5]
	s_setprio 0
	s_barrier
	s_add_i32 s61, s61, 2
	s_add_u32 s40, s40, 0x100
	s_addc_u32 s41, s41, 0
	s_add_u32 s59, s59, 0x100
	s_addc_u32 s60, s60, 0

; #define PG8_STAGE(bufoff, gbase, voff) do { _Pragma("unroll") for (int _i = 0; _i < 2; ++_i) \
;         __builtin_amdgcn_global_load_lds((const unsigned*)((const char*)(gbase) + (voff)[_i]), (LAS unsigned*)(lds + (bufoff) + ldsw + _i * 8192), 16, 0, 0); } while (0)
; #define PG8_LDA(dst, b, h) do { _Pragma("unroll") for (int m = 0; m < 4; ++m) _Pragma("unroll") for (int k = 0; k < 2; ++k) dst[m][k] = *(const LAS bf16x8*)(lds + PG8_SA(b, h) + aoff + m * 2048 + k * 1024); } while (0)
; #define PG8_LDB(dst, b, h) do { _Pragma("unroll") for (int n = 0; n < 2; ++n) _Pragma("unroll") for (int k = 0; k < 2; ++k) dst[n][k] = *(const LAS bf16x8*)(lds + PG8_SB(b, h) + boff + n * 2048 + k * 1024); } while (0)
; #define PG8_MMA(ai, bj, At, Bt) do { __builtin_amdgcn_s_setprio(3); _Pragma("unroll") for (int m = 0; m < 4; ++m) _Pragma("unroll") for (int n = 0; n < 2; ++n) _Pragma("unroll") for (int k = 0; k < 2; ++k) \
;         acc[ai][bj][m][n] = __builtin_amdgcn_mfma_f32_16x16x32_bf16(Bt[n][k], At[m][k], acc[ai][bj][m][n], 0, 0, 0); __builtin_amdgcn_s_setprio(0); } while (0)
; #define PG8_WAIT_V(n) asm volatile("s_waitcnt vmcnt(" #n ")" ::: "memory")
; #define PG8_WAIT_L(n) asm volatile("s_waitcnt lgkmcnt(" #n ")" ::: "memory")
; template <class Epi, bool ALIGN_EPI>
; __device__ __forceinline__ void gemm_phase(LAS unsigned char* lds, const Gemm g, const StaticOrder& S, const Epi& E) {
;     ...
;         const bool has_next = S.next(ui + 1, nxt);
;         const char* nA = has_next ? (const char*)g.A + (size_t)nxt.pm * tstep : cA; const char* nB = has_next ? (const char*)g.Bt + (size_t)nxt.pn * tstep : cB;
;         for (int t = 0; t < nt; t += 2) {
;             const bool last = (t == nt - 2);
;             const char* a1 = cA + (size_t)(t + 1) * kstep;
;             const char* a2 = last ? nA : cA + (size_t)(t + 2) * kstep; const char* b2 = last ? nB : cB + (size_t)(t + 2) * kstep;
;             const char* a3 = a2 + kstep; const char* b3 = b2 + kstep;
;             PG8_LDB(B0, 0, 0); PG8_LDB(B1, 0, 1); PG8_SCHED; PG8_LDA(At, 0, 0); PG8_STAGE(PG8_SA(1, 1), a1 + hstep, voffA);
;             PG8_WAIT_V(8); PG8_WAIT_L(0); PG8_BAR; PG8_MMA(0, 0, At, B0); PG8_MMA(0, 1, At, B1); PG8_BAR; PG8_SCHED;
;             PG8_LDA(At, 0, 1); PG8_STAGE(PG8_SB(0, 0), b2, voffB); PG8_STAGE(PG8_SB(0, 1), b2 + hstep, voffB); PG8_STAGE(PG8_SA(0, 0), a2, voffA);
.LBB0_1427:
	s_ashr_i32 s43, s42, 31
	s_lshl_b64 s[10:11], s[42:43], 19
	s_add_u32 s44, s34, s10
	s_addc_u32 s45, s35, s11
	s_and_b64 s[10:11], s[0:1], exec
	s_cselect_b32 s12, s45, s7
	s_cselect_b32 s13, s44, s6
	s_ashr_i32 s41, s40, 31
	s_lshl_b64 s[10:11], s[40:41], 19
	s_add_u32 s46, s22, s10
	s_addc_u32 s47, s23, s11
	s_and_b64 s[10:11], s[0:1], exec
	s_cselect_b32 s14, s47, s9
	s_cselect_b32 s15, s46, s8
	s_add_u32 s6, s6, 0x40080
	s_addc_u32 s7, s7, 0
	s_add_u32 s16, s8, 0x100
	s_addc_u32 s17, s9, 0
	s_mov_b32 s41, -2
	ds_read_b128 v[146:149], v168
	ds_read_b128 v[150:153], v168 offset:1024
	ds_read_b128 v[154:157], v168 offset:2048
	ds_read_b128 v[158:161], v168 offset:3072
	ds_read_b128 v[172:175], v169
	ds_read_b128 v[176:179], v169 offset:1024
	ds_read_b128 v[180:183], v169 offset:2048
	ds_read_b128 v[184:187], v169 offset:3072
	s_add_u32 s8, s6, 0xfffc0080
	s_addc_u32 s9, s7, -1
	s_cmp_eq_u32 s41, 12
	s_cselect_b32 s11, s12, s9
	s_cselect_b32 s10, s13, s8
	s_cselect_b32 s9, s14, s17
	s_cselect_b32 s8, s15, s16
	v_lshl_add_u64 v[220:221], s[6:7], 0, v[138:139]
	s_add_i32 m0, s50, 0xc000
	ds_read_b128 v[188:191], v170
	ds_read_b128 v[192:195], v170 offset:1024
	ds_read_b128 v[196:199], v170 offset:2048
	ds_read_b128 v[200:203], v170 offset:3072
	ds_read_b128 v[204:207], v170 offset:4096
	ds_read_b128 v[208:211], v170 offset:5120
	ds_read_b128 v[212:215], v170 offset:6144
	ds_read_b128 v[216:219], v170 offset:7168
	global_load_lds_dwordx4 v[220:221], off
	v_lshl_add_u64 v[220:221], s[6:7], 0, v[140:141]
	s_add_i32 m0, s50, 0xe000
	s_nop 0
	global_load_lds_dwordx4 v[220:221], off
	s_cmp_lg_u32 s98, 0
	s_cbranch_scc1 .Lmy_rw_1428_0
	s_waitcnt vmcnt(8)
.Lmy_rw_1428_0:
	s_waitcnt lgkmcnt(0)
	s_barrier
	s_setprio 3
	s_waitcnt lgkmcnt(0)
	v_mfma_f32_16x16x32_bf16 v[126:129], v[146:149], v[188:191], 0
	v_mfma_f32_16x16x32_bf16 v[118:121], v[154:157], v[188:191], 0
	v_mfma_f32_16x16x32_bf16 v[110:113], v[146:149], v[196:199], 0
	v_mfma_f32_16x16x32_bf16 v[102:105], v[154:157], v[196:199], 0
	v_mfma_f32_16x16x32_bf16 v[94:97], v[146:149], v[204:207], 0
	v_mfma_f32_16x16x32_bf16 v[86:89], v[154:157], v[204:207], 0
	v_mfma_f32_16x16x32_bf16 v[78:81], v[146:149], v[212:215], 0
	v_mfma_f32_16x16x32_bf16 v[70:73], v[154:157], v[212:215], 0
	v_mfma_f32_16x16x32_bf16 v[126:129], v[150:153], v[192:195], v[126:129]
	v_mfma_f32_16x16x32_bf16 v[118:121], v[158:161], v[192:195], v[118:121]
	v_mfma_f32_16x16x32_bf16 v[110:113], v[150:153], v[200:203], v[110:113]
	v_mfma_f32_16x16x32_bf16 v[102:105], v[158:161], v[200:203], v[102:105]
	v_mfma_f32_16x16x32_bf16 v[94:97], v[150:153], v[208:211], v[94:97]
	v_mfma_f32_16x16x32_bf16 v[86:89], v[158:161], v[208:211], v[86:89]
	v_mfma_f32_16x16x32_bf16 v[78:81], v[150:153], v[216:219], v[78:81]
	v_mfma_f32_16x16x32_bf16 v[70:73], v[158:161], v[216:219], v[70:73]
	v_mfma_f32_16x16x32_bf16 v[122:125], v[172:175], v[188:191], 0
	v_mfma_f32_16x16x32_bf16 v[114:117], v[180:183], v[188:191], 0
	v_mfma_f32_16x16x32_bf16 v[106:109], v[172:175], v[196:199], 0
	v_mfma_f32_16x16x32_bf16 v[98:101], v[180:183], v[196:199], 0
	v_mfma_f32_16x16x32_bf16 v[90:93], v[172:175], v[204:207], 0
	v_mfma_f32_16x16x32_bf16 v[82:85], v[180:183], v[204:207], 0
	v_mfma_f32_16x16x32_bf16 v[74:77], v[172:175], v[212:215], 0
	v_mfma_f32_16x16x32_bf16 v[66:69], v[180:183], v[212:215], 0
	v_mfma_f32_16x16x32_bf16 v[122:125], v[176:179], v[192:195], v[122:125]
	v_mfma_f32_16x16x32_bf16 v[114:117], v[184:187], v[192:195], v[114:117]
	v_mfma_f32_16x16x32_bf16 v[106:109], v[176:179], v[200:203], v[106:109]
	v_mfma_f32_16x16x32_bf16 v[98:101], v[184:187], v[200:203], v[98:101]
	v_mfma_f32_16x16x32_bf16 v[90:93], v[176:179], v[208:211], v[90:93]
	v_mfma_f32_16x16x32_bf16 v[82:85], v[184:187], v[208:211], v[82:85]
	v_mfma_f32_16x16x32_bf16 v[74:77], v[176:179], v[216:219], v[74:77]
	v_mfma_f32_16x16x32_bf16 v[66:69], v[184:187], v[216:219], v[66:69]
	s_setprio 0
	s_barrier
	s_add_i32 s43, s58, s33
	v_lshl_add_u64 v[220:221], s[8:9], 0, v[132:133]
	s_mov_b32 m0, s43
	ds_read_b128 v[188:191], v170 offset:16384
	ds_read_b128 v[192:195], v170 offset:17408
	ds_read_b128 v[196:199], v170 offset:18432
	ds_read_b128 v[200:203], v170 offset:19456
	ds_read_b128 v[204:207], v170 offset:20480
	ds_read_b128 v[208:211], v170 offset:21504
	ds_read_b128 v[212:215], v170 offset:22528
	ds_read_b128 v[216:219], v170 offset:23552
	global_load_lds_dwordx4 v[220:221], off
	s_add_i32 m0, s43, 0x2000
	s_add_u32 s62, s8, 0x40000
	v_lshl_add_u64 v[222:223], s[8:9], 0, v[136:137]
	s_addc_u32 s63, s9, 0
	s_add_i32 s43, s59, s33
	global_load_lds_dwordx4 v[222:223], off
	v_lshl_add_u64 v[224:225], s[62:63], 0, v[132:133]
	s_mov_b32 m0, s43
	v_lshl_add_u64 v[226:227], s[10:11], 0, v[134:135]
	global_load_lds_dwordx4 v[224:225], off
	v_lshl_add_u64 v[224:225], s[62:63], 0, v[136:137]
	s_add_i32 m0, s43, 0x2000
	s_nop 0
	global_load_lds_dwordx4 v[224:225], off
	v_lshl_add_u64 v[224:225], s[10:11], 0, v[130:131]
	s_mov_b32 m0, s50
	s_nop 0
	global_load_lds_dwordx4 v[224:225], off
	s_mov_b32 m0, s51
	s_nop 0
	global_load_lds_dwordx4 v[226:227], off
	s_cmp_lg_u32 s98, 0
	s_cbranch_scc1 .Lmy_rw_1428_1
	s_waitcnt vmcnt(8)
; #define PG8_STAGE(bufoff, gbase, voff) do { _Pragma("unroll") for (int _i = 0; _i < 2; ++_i) \
;         __builtin_amdgcn_global_load_lds((const unsigned*)((const char*)(gbase) + (voff)[_i]), (LAS unsigned*)(lds + (bufoff) + ldsw + _i * 8192), 16, 0, 0); } while (0)
; #define PG8_LDA(dst, b, h) do { _Pragma("unroll") for (int m = 0; m < 4; ++m) _Pragma("unroll") for (int k = 0; k < 2; ++k) dst[m][k] = *(const LAS bf16x8*)(lds + PG8_SA(b, h) + aoff + m * 2048 + k * 1024); } while (0)
; #define PG8_LDB(dst, b, h) do { _Pragma("unroll") for (int n = 0; n < 2; ++n) _Pragma("unroll") for (int k = 0; k < 2; ++k) dst[n][k] = *(const LAS bf16x8*)(lds + PG8_SB(b, h) + boff + n * 2048 + k * 1024); } while (0)
; #define PG8_MMA(ai, bj, At, Bt) do { __builtin_amdgcn_s_setprio(3); _Pragma("unroll") for (int m = 0; m < 4; ++m) _Pragma("unroll") for (int n = 0; n < 2; ++n) _Pragma("unroll") for (int k = 0; k < 2; ++k) \
;         acc[ai][bj][m][n] = __builtin_amdgcn_mfma_f32_16x16x32_bf16(Bt[n][k], At[m][k], acc[ai][bj][m][n], 0, 0, 0); __builtin_amdgcn_s_setprio(0); } while (0)
; #define PG8_WAIT_V(n) asm volatile("s_waitcnt vmcnt(" #n ")" ::: "memory")
; #define PG8_WAIT_L(n) asm volatile("s_waitcnt lgkmcnt(" #n ")" ::: "memory")
; #define PG8_BAR __builtin_amdgcn_s_barrier()
; #define PG8_SCHED __builtin_amdgcn_sched_barrier(0)
; template <class Epi, bool ALIGN_EPI>
; __device__ __forceinline__ void gemm_phase(LAS unsigned char* lds, const Gemm g, const StaticOrder& S, const Epi& E) {
;     ...
;             PG8_WAIT_V(8); PG8_WAIT_L(0); PG8_BAR; PG8_MMA(1, 0, At, B0); PG8_MMA(1, 1, At, B1); PG8_BAR; PG8_SCHED;
;             PG8_LDB(B0, 1, 0); PG8_LDB(B1, 1, 1); PG8_SCHED; PG8_LDA(At, 1, 0); PG8_STAGE(PG8_SA(0, 1), a2 + hstep, voffA);
;             PG8_WAIT_V(8); PG8_WAIT_L(0); PG8_BAR; PG8_MMA(0, 0, At, B0); PG8_MMA(0, 1, At, B1); PG8_BAR; PG8_SCHED;
.Lmy_rw_1428_1:
	s_waitcnt lgkmcnt(0)
	s_barrier
	s_setprio 3
	s_waitcnt lgkmcnt(0)
	v_mfma_f32_16x16x32_bf16 v[62:65], v[146:149], v[188:191], 0
	v_mfma_f32_16x16x32_bf16 v[54:57], v[154:157], v[188:191], 0
	v_mfma_f32_16x16x32_bf16 v[46:49], v[146:149], v[196:199], 0
	v_mfma_f32_16x16x32_bf16 v[38:41], v[154:157], v[196:199], 0
	v_mfma_f32_16x16x32_bf16 v[30:33], v[146:149], v[204:207], 0
	v_mfma_f32_16x16x32_bf16 v[22:25], v[154:157], v[204:207], 0
	v_mfma_f32_16x16x32_bf16 v[14:17], v[146:149], v[212:215], 0
	v_mfma_f32_16x16x32_bf16 v[6:9], v[154:157], v[212:215], 0
	v_mfma_f32_16x16x32_bf16 v[62:65], v[150:153], v[192:195], v[62:65]
	v_mfma_f32_16x16x32_bf16 v[54:57], v[158:161], v[192:195], v[54:57]
	v_mfma_f32_16x16x32_bf16 v[46:49], v[150:153], v[200:203], v[46:49]
	v_mfma_f32_16x16x32_bf16 v[38:41], v[158:161], v[200:203], v[38:41]
	v_mfma_f32_16x16x32_bf16 v[30:33], v[150:153], v[208:211], v[30:33]
	v_mfma_f32_16x16x32_bf16 v[22:25], v[158:161], v[208:211], v[22:25]
	v_mfma_f32_16x16x32_bf16 v[14:17], v[150:153], v[216:219], v[14:17]
	v_mfma_f32_16x16x32_bf16 v[6:9], v[158:161], v[216:219], v[6:9]
	v_mfma_f32_16x16x32_bf16 v[58:61], v[172:175], v[188:191], 0
	v_mfma_f32_16x16x32_bf16 v[50:53], v[180:183], v[188:191], 0
	v_mfma_f32_16x16x32_bf16 v[42:45], v[172:175], v[196:199], 0
	v_mfma_f32_16x16x32_bf16 v[34:37], v[180:183], v[196:199], 0
	v_mfma_f32_16x16x32_bf16 v[26:29], v[172:175], v[204:207], 0
	v_mfma_f32_16x16x32_bf16 v[18:21], v[180:183], v[204:207], 0
	v_mfma_f32_16x16x32_bf16 v[10:13], v[172:175], v[212:215], 0
	v_mfma_f32_16x16x32_bf16 v[2:5], v[180:183], v[212:215], 0
	v_mfma_f32_16x16x32_bf16 v[58:61], v[176:179], v[192:195], v[58:61]
	v_mfma_f32_16x16x32_bf16 v[50:53], v[184:187], v[192:195], v[50:53]
	v_mfma_f32_16x16x32_bf16 v[42:45], v[176:179], v[200:203], v[42:45]
	v_mfma_f32_16x16x32_bf16 v[34:37], v[184:187], v[200:203], v[34:37]
	v_mfma_f32_16x16x32_bf16 v[26:29], v[176:179], v[208:211], v[26:29]
	v_mfma_f32_16x16x32_bf16 v[18:21], v[184:187], v[208:211], v[18:21]
	v_mfma_f32_16x16x32_bf16 v[10:13], v[176:179], v[216:219], v[10:13]
	v_mfma_f32_16x16x32_bf16 v[2:5], v[184:187], v[216:219], v[2:5]
	s_setprio 0
	s_barrier
	s_add_i32 s43, 0, 0x18000
	s_add_i32 s62, 0, 0x1c000
	v_add_u32_e32 v158, s43, v166
	v_add_u32_e32 v184, s62, v166
	ds_read_b128 v[146:149], v158
	ds_read_b128 v[150:153], v158 offset:1024
	ds_read_b128 v[154:157], v158 offset:2048
	ds_read_b128 v[158:161], v158 offset:3072
	ds_read_b128 v[172:175], v184
	ds_read_b128 v[176:179], v184 offset:1024
	ds_read_b128 v[180:183], v184 offset:2048
	ds_read_b128 v[184:187], v184 offset:3072
	s_add_u32 s10, s10, 0x40000
	s_addc_u32 s11, s11, 0
	s_mov_b32 m0, s52
	v_lshl_add_u64 v[228:229], s[10:11], 0, v[130:131]
	ds_read_b128 v[188:191], v170 offset:32768
	ds_read_b128 v[192:195], v170 offset:33792
	ds_read_b128 v[196:199], v170 offset:34816
	ds_read_b128 v[200:203], v170 offset:35840
	ds_read_b128 v[204:207], v170 offset:36864
	ds_read_b128 v[208:211], v170 offset:37888
	ds_read_b128 v[212:215], v170 offset:38912
	ds_read_b128 v[216:219], v170 offset:39936
	global_load_lds_dwordx4 v[228:229], off
	v_lshl_add_u64 v[228:229], s[10:11], 0, v[134:135]
	s_mov_b32 m0, s53
	s_nop 0
	global_load_lds_dwordx4 v[228:229], off
	s_waitcnt vmcnt(8)
	s_waitcnt lgkmcnt(0)
	s_barrier
	s_setprio 3
	s_waitcnt lgkmcnt(0)
	v_mfma_f32_16x16x32_bf16 v[126:129], v[146:149], v[188:191], v[126:129]
	v_mfma_f32_16x16x32_bf16 v[118:121], v[154:157], v[188:191], v[118:121]
	v_mfma_f32_16x16x32_bf16 v[110:113], v[146:149], v[196:199], v[110:113]
	v_mfma_f32_16x16x32_bf16 v[102:105], v[154:157], v[196:199], v[102:105]
	v_mfma_f32_16x16x32_bf16 v[94:97], v[146:149], v[204:207], v[94:97]
	v_mfma_f32_16x16x32_bf16 v[86:89], v[154:157], v[204:207], v[86:89]
	v_mfma_f32_16x16x32_bf16 v[78:81], v[146:149], v[212:215], v[78:81]
	v_mfma_f32_16x16x32_bf16 v[70:73], v[154:157], v[212:215], v[70:73]
	v_mfma_f32_16x16x32_bf16 v[126:129], v[150:153], v[192:195], v[126:129]
	v_mfma_f32_16x16x32_bf16 v[118:121], v[158:161], v[192:195], v[118:121]
	v_mfma_f32_16x16x32_bf16 v[110:113], v[150:153], v[200:203], v[110:113]
	v_mfma_f32_16x16x32_bf16 v[102:105], v[158:161], v[200:203], v[102:105]
	v_mfma_f32_16x16x32_bf16 v[94:97], v[150:153], v[208:211], v[94:97]
	v_mfma_f32_16x16x32_bf16 v[86:89], v[158:161], v[208:211], v[86:89]
	v_mfma_f32_16x16x32_bf16 v[78:81], v[150:153], v[216:219], v[78:81]
	v_mfma_f32_16x16x32_bf16 v[70:73], v[158:161], v[216:219], v[70:73]
	v_mfma_f32_16x16x32_bf16 v[122:125], v[172:175], v[188:191], v[122:125]
	v_mfma_f32_16x16x32_bf16 v[114:117], v[180:183], v[188:191], v[114:117]
	v_mfma_f32_16x16x32_bf16 v[106:109], v[172:175], v[196:199], v[106:109]
	v_mfma_f32_16x16x32_bf16 v[98:101], v[180:183], v[196:199], v[98:101]
	v_mfma_f32_16x16x32_bf16 v[90:93], v[172:175], v[204:207], v[90:93]
	v_mfma_f32_16x16x32_bf16 v[82:85], v[180:183], v[204:207], v[82:85]
	v_mfma_f32_16x16x32_bf16 v[74:77], v[172:175], v[212:215], v[74:77]
	v_mfma_f32_16x16x32_bf16 v[66:69], v[180:183], v[212:215], v[66:69]
	v_mfma_f32_16x16x32_bf16 v[122:125], v[176:179], v[192:195], v[122:125]
	v_mfma_f32_16x16x32_bf16 v[114:117], v[184:187], v[192:195], v[114:117]
	v_mfma_f32_16x16x32_bf16 v[106:109], v[176:179], v[200:203], v[106:109]
	v_mfma_f32_16x16x32_bf16 v[98:101], v[184:187], v[200:203], v[98:101]
	v_mfma_f32_16x16x32_bf16 v[90:93], v[176:179], v[208:211], v[90:93]
	v_mfma_f32_16x16x32_bf16 v[82:85], v[184:187], v[208:211], v[82:85]
	v_mfma_f32_16x16x32_bf16 v[74:77], v[176:179], v[216:219], v[74:77]
	v_mfma_f32_16x16x32_bf16 v[66:69], v[184:187], v[216:219], v[66:69]
	s_setprio 0
	s_barrier
; #define PG8_STAGE(bufoff, gbase, voff) do { _Pragma("unroll") for (int _i = 0; _i < 2; ++_i) \
;         __builtin_amdgcn_global_load_lds((const unsigned*)((const char*)(gbase) + (voff)[_i]), (LAS unsigned*)(lds + (bufoff) + ldsw + _i * 8192), 16, 0, 0); } while (0)
; #define PG8_LDA(dst, b, h) do { _Pragma("unroll") for (int m = 0; m < 4; ++m) _Pragma("unroll") for (int k = 0; k < 2; ++k) dst[m][k] = *(const LAS bf16x8*)(lds + PG8_SA(b, h) + aoff + m * 2048 + k * 1024); } while (0)
; #define PG8_MMA(ai, bj, At, Bt) do { __builtin_amdgcn_s_setprio(3); _Pragma("unroll") for (int m = 0; m < 4; ++m) _Pragma("unroll") for (int n = 0; n < 2; ++n) _Pragma("unroll") for (int k = 0; k < 2; ++k) \
;         acc[ai][bj][m][n] = __builtin_amdgcn_mfma_f32_16x16x32_bf16(Bt[n][k], At[m][k], acc[ai][bj][m][n], 0, 0, 0); __builtin_amdgcn_s_setprio(0); } while (0)
; #define PG8_WAIT_V(n) asm volatile("s_waitcnt vmcnt(" #n ")" ::: "memory")
; #define PG8_WAIT_L(n) asm volatile("s_waitcnt lgkmcnt(" #n ")" ::: "memory")
; #define PG8_BAR __builtin_amdgcn_s_barrier()
; #define PG8_SCHED __builtin_amdgcn_sched_barrier(0)
; template <class Epi, bool ALIGN_EPI>
; __device__ __forceinline__ void gemm_phase(LAS unsigned char* lds, const Gemm g, const StaticOrder& S, const Epi& E) {
;     ...
;             PG8_LDA(At, 1, 1); PG8_STAGE(PG8_SB(1, 0), b3, voffB); PG8_STAGE(PG8_SB(1, 1), b3 + hstep, voffB); PG8_STAGE(PG8_SA(1, 0), a3, voffA);
;             PG8_WAIT_V(8); PG8_WAIT_L(0); PG8_BAR; PG8_MMA(1, 0, At, B0); PG8_MMA(1, 1, At, B1); PG8_BAR; PG8_SCHED;
	s_add_i32 s10, s43, s33
	v_lshl_add_u64 v[220:221], v[220:221], 0, s[36:37]
	s_mov_b32 m0, s10
	ds_read_b128 v[188:191], v170 offset:49152
	ds_read_b128 v[192:195], v170 offset:50176
	ds_read_b128 v[196:199], v170 offset:51200
	ds_read_b128 v[200:203], v170 offset:52224
	ds_read_b128 v[204:207], v170 offset:53248
	ds_read_b128 v[208:211], v170 offset:54272
	ds_read_b128 v[212:215], v170 offset:55296
	ds_read_b128 v[216:219], v170 offset:56320
	global_load_lds_dwordx4 v[220:221], off
	s_add_i32 m0, s10, 0x2000
	s_add_u32 s8, s8, 0x40080
	v_lshl_add_u64 v[220:221], v[222:223], 0, s[36:37]
	s_addc_u32 s9, s9, 0
	s_add_i32 s10, s62, s33
	global_load_lds_dwordx4 v[220:221], off
	v_lshl_add_u64 v[220:221], s[8:9], 0, v[132:133]
	s_mov_b32 m0, s10
	s_nop 0
	global_load_lds_dwordx4 v[220:221], off
	v_lshl_add_u64 v[220:221], s[8:9], 0, v[136:137]
	s_add_i32 m0, s10, 0x2000
	s_nop 0
	global_load_lds_dwordx4 v[220:221], off
	v_lshl_add_u64 v[220:221], v[224:225], 0, s[36:37]
	s_mov_b32 m0, s56
	s_nop 0
	global_load_lds_dwordx4 v[220:221], off
	v_lshl_add_u64 v[220:221], v[226:227], 0, s[36:37]
	s_mov_b32 m0, s57
	s_nop 0
	global_load_lds_dwordx4 v[220:221], off
	s_waitcnt vmcnt(8)
	s_waitcnt lgkmcnt(0)
	s_barrier
	s_setprio 3
	s_waitcnt lgkmcnt(0)
	v_mfma_f32_16x16x32_bf16 v[62:65], v[146:149], v[188:191], v[62:65]
	v_mfma_f32_16x16x32_bf16 v[54:57], v[154:157], v[188:191], v[54:57]
	v_mfma_f32_16x16x32_bf16 v[46:49], v[146:149], v[196:199], v[46:49]
	v_mfma_f32_16x16x32_bf16 v[38:41], v[154:157], v[196:199], v[38:41]
	v_mfma_f32_16x16x32_bf16 v[30:33], v[146:149], v[204:207], v[30:33]
	v_mfma_f32_16x16x32_bf16 v[22:25], v[154:157], v[204:207], v[22:25]
	v_mfma_f32_16x16x32_bf16 v[14:17], v[146:149], v[212:215], v[14:17]
	v_mfma_f32_16x16x32_bf16 v[6:9], v[154:157], v[212:215], v[6:9]
	v_mfma_f32_16x16x32_bf16 v[62:65], v[150:153], v[192:195], v[62:65]
	v_mfma_f32_16x16x32_bf16 v[54:57], v[158:161], v[192:195], v[54:57]
	v_mfma_f32_16x16x32_bf16 v[46:49], v[150:153], v[200:203], v[46:49]
	v_mfma_f32_16x16x32_bf16 v[38:41], v[158:161], v[200:203], v[38:41]
	v_mfma_f32_16x16x32_bf16 v[30:33], v[150:153], v[208:211], v[30:33]
	v_mfma_f32_16x16x32_bf16 v[22:25], v[158:161], v[208:211], v[22:25]
	v_mfma_f32_16x16x32_bf16 v[14:17], v[150:153], v[216:219], v[14:17]
	v_mfma_f32_16x16x32_bf16 v[6:9], v[158:161], v[216:219], v[6:9]
	v_mfma_f32_16x16x32_bf16 v[58:61], v[172:175], v[188:191], v[58:61]
	v_mfma_f32_16x16x32_bf16 v[50:53], v[180:183], v[188:191], v[50:53]
	v_mfma_f32_16x16x32_bf16 v[42:45], v[172:175], v[196:199], v[42:45]
	v_mfma_f32_16x16x32_bf16 v[34:37], v[180:183], v[196:199], v[34:37]
	v_mfma_f32_16x16x32_bf16 v[26:29], v[172:175], v[204:207], v[26:29]
	v_mfma_f32_16x16x32_bf16 v[18:21], v[180:183], v[204:207], v[18:21]
	v_mfma_f32_16x16x32_bf16 v[10:13], v[172:175], v[212:215], v[10:13]
	v_mfma_f32_16x16x32_bf16 v[2:5], v[180:183], v[212:215], v[2:5]
	v_mfma_f32_16x16x32_bf16 v[58:61], v[176:179], v[192:195], v[58:61]
	v_mfma_f32_16x16x32_bf16 v[50:53], v[184:187], v[192:195], v[50:53]
	v_mfma_f32_16x16x32_bf16 v[42:45], v[176:179], v[200:203], v[42:45]
	v_mfma_f32_16x16x32_bf16 v[34:37], v[184:187], v[200:203], v[34:37]
	v_mfma_f32_16x16x32_bf16 v[26:29], v[176:179], v[208:211], v[26:29]
	v_mfma_f32_16x16x32_bf16 v[18:21], v[184:187], v[208:211], v[18:21]
	v_mfma_f32_16x16x32_bf16 v[10:13], v[176:179], v[216:219], v[10:13]
	v_mfma_f32_16x16x32_bf16 v[2:5], v[184:187], v[216:219], v[2:5]
	s_setprio 0
	s_barrier
	s_add_i32 s41, s41, 2
	s_add_u32 s6, s6, 0x100
	s_addc_u32 s7, s7, 0
	s_add_u32 s16, s16, 0x100
	s_addc_u32 s17, s17, 0

; #define PG8_STAGE(bufoff, gbase, voff) do { _Pragma("unroll") for (int _i = 0; _i < 2; ++_i) \
;         __builtin_amdgcn_global_load_lds((const unsigned*)((const char*)(gbase) + (voff)[_i]), (LAS unsigned*)(lds + (bufoff) + ldsw + _i * 8192), 16, 0, 0); } while (0)
; #define PG8_WAIT_V(n) asm volatile("s_waitcnt vmcnt(" #n ")" ::: "memory")
; #define PG8_BAR __builtin_amdgcn_s_barrier()
; template <class Epi, bool ALIGN_EPI>
; __device__ __forceinline__ void gemm_phase(LAS unsigned char* lds, const Gemm g, const StaticOrder& S, const Epi& E) {
;     ...
;     const int aoff = lds_byte(wr * 64 + fr, fq * 8), boff = lds_byte(wc * 32 + fr, fq * 8);
;     ...
;     Unit cur, nxt; int ui = 0;
;     if (!S.next(0, cur)) return;
;     f32x4 acc[2][2][4][2];
; #pragma unroll
;     for (int a = 0; a < 2; ++a)
; #pragma unroll
;         for (int b = 0; b < 2; ++b)
; #pragma unroll
;             for (int m = 0; m < 4; ++m)
; #pragma unroll
;                 for (int n = 0; n < 2; ++n) acc[a][b][m][n] = (f32x4){0.f, 0.f, 0.f, 0.f};
;     bf16x8 At[4][2], B0[2][2], B1[2][2];
;     const char* cA = (const char*)g.A + (size_t)cur.pm * tstep; const char* cB = (const char*)g.Bt + (size_t)cur.pn * tstep;
;     PG8_STAGE(PG8_SB(0, 0), cB, voffB); PG8_STAGE(PG8_SB(0, 1), cB + hstep, voffB); PG8_STAGE(PG8_SA(0, 0), cA, voffA); PG8_STAGE(PG8_SA(0, 1), cA + hstep, voffA);
;     if (wr == 1) PG8_BAR;
;     PG8_WAIT_V(2); PG8_BAR;
;     PG8_STAGE(PG8_SB(1, 0), cB + kstep, voffB); PG8_STAGE(PG8_SA(1, 0), cA + kstep, voffA); PG8_STAGE(PG8_SB(1, 1), cB + hstep + kstep, voffB);
;     PG8_WAIT_V(6); PG8_BAR;
;     for (;;) {
;         const bool has_next = S.next(ui + 1, nxt);
.LBB0_1499:
	s_lshl_b32 s5, s5, 5
	s_mov_b64 s[8:9], 0x80
	s_and_b32 s5, s5, 0x60
	s_add_i32 m0, s26, 0x18000
	v_lshl_add_u64 v[6:7], v[6:7], 0, s[8:9]
	s_lshl_b32 s12, s0, 13
	s_lshl_b32 s13, s5, 7
	s_waitcnt vmcnt(2)
	s_barrier
	global_load_lds_dwordx4 v[6:7], off
	v_lshl_add_u64 v[4:5], v[4:5], 0, s[8:9]
	s_add_i32 m0, s26, 0x1a000
	s_add_i32 s31, s26, 0x8000
	s_add_i32 s33, s26, 0xa000
	global_load_lds_dwordx4 v[4:5], off
	v_lshl_add_u64 v[0:1], v[0:1], 0, s[8:9]
	s_mov_b32 m0, s31
	s_add_u32 s10, s16, 0xb0080
	global_load_lds_dwordx4 v[0:1], off
	v_lshl_add_u64 v[0:1], v[2:3], 0, s[8:9]
	s_mov_b32 m0, s33
	s_addc_u32 s11, s17, 0
	global_load_lds_dwordx4 v[0:1], off
	s_add_i32 m0, s26, 0x1c000
	v_lshl_add_u64 v[0:1], s[10:11], 0, v[130:131]
	global_load_lds_dwordx4 v[0:1], off
	v_lshl_add_u64 v[0:1], s[10:11], 0, v[134:135]
	s_add_i32 m0, s26, 0x1e000
	v_lshlrev_b32_e32 v3, 6, v153
	global_load_lds_dwordx4 v[0:1], off
	v_and_b32_e32 v0, 15, v153
	v_lshl_or_b32 v155, s0, 6, v0
	v_lshlrev_b32_e32 v1, 1, v10
	s_movk_i32 s0, 0x3c0
	v_lshl_or_b32 v0, v0, 6, v1
	v_and_b32_e32 v2, 32, v154
	v_and_or_b32 v1, v3, s0, v1
	v_bitop3_b32 v156, s13, v1, v2 bitop3:0xf6
	s_waitcnt vmcnt(6)
	s_cmpk_lt_u32 s4, 0x100
	v_add_u16_e32 v1, v8, v9
	v_bitop3_b32 v0, v0, s12, v2 bitop3:0xde
	s_cselect_b64 s[10:11], -1, 0
	v_lshrrev_b16_e32 v1, 1, v1
	s_add_i32 s37, 0, 0x10000
	s_add_i32 s38, 0, 0x14000
	s_sext_i32_i8 s42, s1
	s_ashr_i32 s36, s3, 31
	v_or_b32_e32 v157, s5, v10
	v_add_lshl_u32 v136, v11, v1, 1
	v_mov_b32_e32 v137, v131
	v_add_lshl_u32 v138, v12, v1, 1
	v_mov_b32_e32 v139, v131
	v_mov_b64_e32 v[140:141], 0x200
	v_mov_b64_e32 v[142:143], 0x1ff
	v_add_u32_e32 v158, s37, v156
	v_add_u32_e32 v159, s38, v156
	v_add_u32_e32 v160, 0, v0
	s_barrier
	s_mov_b32 s98, 0
	s_branch .LBB0_1502

; #define PG8_BAR __builtin_amdgcn_s_barrier()
; template <class Epi, bool ALIGN_EPI>
; __device__ __forceinline__ void gemm_phase(LAS unsigned char* lds, const Gemm g, const StaticOrder& S, const Epi& E) {
;     ...
;         if (!has_next) break;
; #pragma unroll
;         for (int a = 0; a < 2; ++a)
; #pragma unroll
;             for (int b = 0; b < 2; ++b)
; #pragma unroll
;                 for (int m = 0; m < 4; ++m)
; #pragma unroll
;                     for (int n = 0; n < 2; ++n) acc[a][b][m][n] = (f32x4){0.f, 0.f, 0.f, 0.f};
;         cur = nxt; cA = nA; cB = nB; ++ui;
;         if constexpr (ALIGN_EPI) { if (wr == 1) PG8_BAR; }
;     }
.LBB0_1501:
	s_mov_b32 s98, 1
	s_andn2_b64 vcc, exec, s[0:1]
	s_mov_b32 s42, s39
	s_mov_b32 s41, s40
	s_mov_b64 s[16:17], s[12:13]
	s_mov_b64 s[14:15], s[4:5]
	s_cbranch_vccz .LBB0_1519

; #define PG8_STAGE(bufoff, gbase, voff) do { _Pragma("unroll") for (int _i = 0; _i < 2; ++_i) \
;         __builtin_amdgcn_global_load_lds((const unsigned*)((const char*)(gbase) + (voff)[_i]), (LAS unsigned*)(lds + (bufoff) + ldsw + _i * 8192), 16, 0, 0); } while (0)
; #define PG8_LDA(dst, b, h) do { _Pragma("unroll") for (int m = 0; m < 4; ++m) _Pragma("unroll") for (int k = 0; k < 2; ++k) dst[m][k] = *(const LAS bf16x8*)(lds + PG8_SA(b, h) + aoff + m * 2048 + k * 1024); } while (0)
; #define PG8_LDB(dst, b, h) do { _Pragma("unroll") for (int n = 0; n < 2; ++n) _Pragma("unroll") for (int k = 0; k < 2; ++k) dst[n][k] = *(const LAS bf16x8*)(lds + PG8_SB(b, h) + boff + n * 2048 + k * 1024); } while (0)
; #define PG8_MMA(ai, bj, At, Bt) do { __builtin_amdgcn_s_setprio(3); _Pragma("unroll") for (int m = 0; m < 4; ++m) _Pragma("unroll") for (int n = 0; n < 2; ++n) _Pragma("unroll") for (int k = 0; k < 2; ++k) \
;         acc[ai][bj][m][n] = __builtin_amdgcn_mfma_f32_16x16x32_bf16(Bt[n][k], At[m][k], acc[ai][bj][m][n], 0, 0, 0); __builtin_amdgcn_s_setprio(0); } while (0)
; #define PG8_WAIT_V(n) asm volatile("s_waitcnt vmcnt(" #n ")" ::: "memory")
; #define PG8_WAIT_L(n) asm volatile("s_waitcnt lgkmcnt(" #n ")" ::: "memory")
; template <class Epi, bool ALIGN_EPI>
; __device__ __forceinline__ void gemm_phase(LAS unsigned char* lds, const Gemm g, const StaticOrder& S, const Epi& E) {
;     ...
;         const bool has_next = S.next(ui + 1, nxt);
;         const char* nA = has_next ? (const char*)g.A + (size_t)nxt.pm * tstep : cA; const char* nB = has_next ? (const char*)g.Bt + (size_t)nxt.pn * tstep : cB;
;         for (int t = 0; t < nt; t += 2) {
;             const bool last = (t == nt - 2);
;             const char* a1 = cA + (size_t)(t + 1) * kstep;
;             const char* a2 = last ? nA : cA + (size_t)(t + 2) * kstep; const char* b2 = last ? nB : cB + (size_t)(t + 2) * kstep;
;             const char* a3 = a2 + kstep; const char* b3 = b2 + kstep;
;             PG8_LDB(B0, 0, 0); PG8_LDB(B1, 0, 1); PG8_SCHED; PG8_LDA(At, 0, 0); PG8_STAGE(PG8_SA(1, 1), a1 + hstep, voffA);
;             PG8_WAIT_V(8); PG8_WAIT_L(0); PG8_BAR; PG8_MMA(0, 0, At, B0); PG8_MMA(0, 1, At, B1); PG8_BAR; PG8_SCHED;
;             PG8_LDA(At, 0, 1); PG8_STAGE(PG8_SB(0, 0), b2, voffB); PG8_STAGE(PG8_SB(0, 1), b2 + hstep, voffB); PG8_STAGE(PG8_SA(0, 0), a2, voffA);
.LBB0_1512:
	s_add_u32 s14, s14, 0xb0080
	s_addc_u32 s15, s15, 0
	s_add_u32 s43, s16, 0x100
	s_addc_u32 s44, s17, 0
	s_mov_b32 s45, -2
	ds_read_b128 v[144:147], v158
	ds_read_b128 v[148:151], v158 offset:1024
	ds_read_b128 v[162:165], v158 offset:2048
	ds_read_b128 v[166:169], v158 offset:3072
	ds_read_b128 v[170:173], v159
	ds_read_b128 v[174:177], v159 offset:1024
	ds_read_b128 v[178:181], v159 offset:2048
	ds_read_b128 v[182:185], v159 offset:3072
	s_add_u32 s16, s14, 0xfff50080
	s_addc_u32 s17, s15, -1
	s_cmp_eq_u32 s45, 40
	s_cselect_b32 s19, s5, s17
	s_cselect_b32 s18, s4, s16
	s_cselect_b32 s17, s13, s44
	s_cselect_b32 s16, s12, s43
	v_lshl_add_u64 v[218:219], s[14:15], 0, v[136:137]
	s_add_i32 m0, s26, 0xc000
	ds_read_b128 v[186:189], v160
	ds_read_b128 v[190:193], v160 offset:1024
	ds_read_b128 v[194:197], v160 offset:2048
	ds_read_b128 v[198:201], v160 offset:3072
	ds_read_b128 v[202:205], v160 offset:4096
	ds_read_b128 v[206:209], v160 offset:5120
	ds_read_b128 v[210:213], v160 offset:6144
	ds_read_b128 v[214:217], v160 offset:7168
	global_load_lds_dwordx4 v[218:219], off
	v_lshl_add_u64 v[218:219], s[14:15], 0, v[138:139]
	s_add_i32 m0, s26, 0xe000
	s_nop 0
	global_load_lds_dwordx4 v[218:219], off
	s_cmp_lg_u32 s98, 0
	s_cbranch_scc1 .Lmy_rw_1513_0
	s_waitcnt vmcnt(8)
.Lmy_rw_1513_0:
	s_waitcnt lgkmcnt(0)
	s_barrier
	s_setprio 3
	s_waitcnt lgkmcnt(0)
	v_mfma_f32_16x16x32_bf16 v[124:127], v[144:147], v[186:189], 0
	v_mfma_f32_16x16x32_bf16 v[120:123], v[162:165], v[186:189], 0
	v_mfma_f32_16x16x32_bf16 v[108:111], v[144:147], v[194:197], 0
	v_mfma_f32_16x16x32_bf16 v[104:107], v[162:165], v[194:197], 0
	v_mfma_f32_16x16x32_bf16 v[96:99], v[144:147], v[202:205], 0
	v_mfma_f32_16x16x32_bf16 v[88:91], v[162:165], v[202:205], 0
	v_mfma_f32_16x16x32_bf16 v[80:83], v[144:147], v[210:213], 0
	v_mfma_f32_16x16x32_bf16 v[72:75], v[162:165], v[210:213], 0
	v_mfma_f32_16x16x32_bf16 v[124:127], v[148:151], v[190:193], v[124:127]
	v_mfma_f32_16x16x32_bf16 v[120:123], v[166:169], v[190:193], v[120:123]
	v_mfma_f32_16x16x32_bf16 v[108:111], v[148:151], v[198:201], v[108:111]
	v_mfma_f32_16x16x32_bf16 v[104:107], v[166:169], v[198:201], v[104:107]
	v_mfma_f32_16x16x32_bf16 v[96:99], v[148:151], v[206:209], v[96:99]
	v_mfma_f32_16x16x32_bf16 v[88:91], v[166:169], v[206:209], v[88:91]
	v_mfma_f32_16x16x32_bf16 v[80:83], v[148:151], v[214:217], v[80:83]
	v_mfma_f32_16x16x32_bf16 v[72:75], v[166:169], v[214:217], v[72:75]
	v_mfma_f32_16x16x32_bf16 v[116:119], v[170:173], v[186:189], 0
	v_mfma_f32_16x16x32_bf16 v[112:115], v[178:181], v[186:189], 0
	v_mfma_f32_16x16x32_bf16 v[100:103], v[170:173], v[194:197], 0
	v_mfma_f32_16x16x32_bf16 v[92:95], v[178:181], v[194:197], 0
	v_mfma_f32_16x16x32_bf16 v[84:87], v[170:173], v[202:205], 0
	v_mfma_f32_16x16x32_bf16 v[76:79], v[178:181], v[202:205], 0
	v_mfma_f32_16x16x32_bf16 v[68:71], v[170:173], v[210:213], 0
	v_mfma_f32_16x16x32_bf16 v[64:67], v[178:181], v[210:213], 0
	v_mfma_f32_16x16x32_bf16 v[116:119], v[174:177], v[190:193], v[116:119]
	v_mfma_f32_16x16x32_bf16 v[112:115], v[182:185], v[190:193], v[112:115]
	v_mfma_f32_16x16x32_bf16 v[100:103], v[174:177], v[198:201], v[100:103]
	v_mfma_f32_16x16x32_bf16 v[92:95], v[182:185], v[198:201], v[92:95]
	v_mfma_f32_16x16x32_bf16 v[84:87], v[174:177], v[206:209], v[84:87]
	v_mfma_f32_16x16x32_bf16 v[76:79], v[182:185], v[206:209], v[76:79]
	v_mfma_f32_16x16x32_bf16 v[68:71], v[174:177], v[214:217], v[68:71]
	v_mfma_f32_16x16x32_bf16 v[64:67], v[182:185], v[214:217], v[64:67]
	s_setprio 0
	s_barrier
	s_add_i32 s46, s37, s23
	v_lshl_add_u64 v[218:219], s[16:17], 0, v[130:131]
	s_mov_b32 m0, s46
	ds_read_b128 v[186:189], v160 offset:16384
	ds_read_b128 v[190:193], v160 offset:17408
	ds_read_b128 v[194:197], v160 offset:18432
	ds_read_b128 v[198:201], v160 offset:19456
	ds_read_b128 v[202:205], v160 offset:20480
	ds_read_b128 v[206:209], v160 offset:21504
	ds_read_b128 v[210:213], v160 offset:22528
	ds_read_b128 v[214:217], v160 offset:23552
	global_load_lds_dwordx4 v[218:219], off
	s_add_i32 m0, s46, 0x2000
	s_add_u32 s46, s16, 0xb0000
	v_lshl_add_u64 v[220:221], s[16:17], 0, v[134:135]
	s_addc_u32 s47, s17, 0
	s_add_i32 s48, s38, s23
	global_load_lds_dwordx4 v[220:221], off
	v_lshl_add_u64 v[222:223], s[46:47], 0, v[130:131]
	s_mov_b32 m0, s48
	v_lshl_add_u64 v[224:225], s[18:19], 0, v[132:133]
	global_load_lds_dwordx4 v[222:223], off
	v_lshl_add_u64 v[222:223], s[46:47], 0, v[134:135]
	s_add_i32 m0, s48, 0x2000
	s_nop 0
	global_load_lds_dwordx4 v[222:223], off
	v_lshl_add_u64 v[222:223], s[18:19], 0, v[128:129]
	s_mov_b32 m0, s26
	s_nop 0
	global_load_lds_dwordx4 v[222:223], off
	s_mov_b32 m0, s27
	s_nop 0
	global_load_lds_dwordx4 v[224:225], off
	s_cmp_lg_u32 s98, 0
	s_cbranch_scc1 .Lmy_rw_1513_1
	s_waitcnt vmcnt(8)
; #define PG8_STAGE(bufoff, gbase, voff) do { _Pragma("unroll") for (int _i = 0; _i < 2; ++_i) \
;         __builtin_amdgcn_global_load_lds((const unsigned*)((const char*)(gbase) + (voff)[_i]), (LAS unsigned*)(lds + (bufoff) + ldsw + _i * 8192), 16, 0, 0); } while (0)
; #define PG8_LDA(dst, b, h) do { _Pragma("unroll") for (int m = 0; m < 4; ++m) _Pragma("unroll") for (int k = 0; k < 2; ++k) dst[m][k] = *(const LAS bf16x8*)(lds + PG8_SA(b, h) + aoff + m * 2048 + k * 1024); } while (0)
; #define PG8_LDB(dst, b, h) do { _Pragma("unroll") for (int n = 0; n < 2; ++n) _Pragma("unroll") for (int k = 0; k < 2; ++k) dst[n][k] = *(const LAS bf16x8*)(lds + PG8_SB(b, h) + boff + n * 2048 + k * 1024); } while (0)
; #define PG8_MMA(ai, bj, At, Bt) do { __builtin_amdgcn_s_setprio(3); _Pragma("unroll") for (int m = 0; m < 4; ++m) _Pragma("unroll") for (int n = 0; n < 2; ++n) _Pragma("unroll") for (int k = 0; k < 2; ++k) \
;         acc[ai][bj][m][n] = __builtin_amdgcn_mfma_f32_16x16x32_bf16(Bt[n][k], At[m][k], acc[ai][bj][m][n], 0, 0, 0); __builtin_amdgcn_s_setprio(0); } while (0)
; #define PG8_WAIT_V(n) asm volatile("s_waitcnt vmcnt(" #n ")" ::: "memory")
; #define PG8_WAIT_L(n) asm volatile("s_waitcnt lgkmcnt(" #n ")" ::: "memory")
; #define PG8_BAR __builtin_amdgcn_s_barrier()
; #define PG8_SCHED __builtin_amdgcn_sched_barrier(0)
; template <class Epi, bool ALIGN_EPI>
; __device__ __forceinline__ void gemm_phase(LAS unsigned char* lds, const Gemm g, const StaticOrder& S, const Epi& E) {
;     ...
;             PG8_WAIT_V(8); PG8_WAIT_L(0); PG8_BAR; PG8_MMA(1, 0, At, B0); PG8_MMA(1, 1, At, B1); PG8_BAR; PG8_SCHED;
;             PG8_LDB(B0, 1, 0); PG8_LDB(B1, 1, 1); PG8_SCHED; PG8_LDA(At, 1, 0); PG8_STAGE(PG8_SA(0, 1), a2 + hstep, voffA);
;             PG8_WAIT_V(8); PG8_WAIT_L(0); PG8_BAR; PG8_MMA(0, 0, At, B0); PG8_MMA(0, 1, At, B1); PG8_BAR; PG8_SCHED;
.Lmy_rw_1513_1:
	s_waitcnt lgkmcnt(0)
	s_barrier
	s_setprio 3
	s_waitcnt lgkmcnt(0)
	v_mfma_f32_16x16x32_bf16 v[60:63], v[144:147], v[186:189], 0
	v_mfma_f32_16x16x32_bf16 v[56:59], v[162:165], v[186:189], 0
	v_mfma_f32_16x16x32_bf16 v[48:51], v[144:147], v[194:197], 0
	v_mfma_f32_16x16x32_bf16 v[40:43], v[162:165], v[194:197], 0
	v_mfma_f32_16x16x32_bf16 v[32:35], v[144:147], v[202:205], 0
	v_mfma_f32_16x16x32_bf16 v[24:27], v[162:165], v[202:205], 0
	v_mfma_f32_16x16x32_bf16 v[16:19], v[144:147], v[210:213], 0
	v_mfma_f32_16x16x32_bf16 v[8:11], v[162:165], v[210:213], 0
	v_mfma_f32_16x16x32_bf16 v[60:63], v[148:151], v[190:193], v[60:63]
	v_mfma_f32_16x16x32_bf16 v[56:59], v[166:169], v[190:193], v[56:59]
	v_mfma_f32_16x16x32_bf16 v[48:51], v[148:151], v[198:201], v[48:51]
	v_mfma_f32_16x16x32_bf16 v[40:43], v[166:169], v[198:201], v[40:43]
	v_mfma_f32_16x16x32_bf16 v[32:35], v[148:151], v[206:209], v[32:35]
	v_mfma_f32_16x16x32_bf16 v[24:27], v[166:169], v[206:209], v[24:27]
	v_mfma_f32_16x16x32_bf16 v[16:19], v[148:151], v[214:217], v[16:19]
	v_mfma_f32_16x16x32_bf16 v[8:11], v[166:169], v[214:217], v[8:11]
	v_mfma_f32_16x16x32_bf16 v[52:55], v[170:173], v[186:189], 0
	v_mfma_f32_16x16x32_bf16 v[44:47], v[178:181], v[186:189], 0
	v_mfma_f32_16x16x32_bf16 v[36:39], v[170:173], v[194:197], 0
	v_mfma_f32_16x16x32_bf16 v[28:31], v[178:181], v[194:197], 0
	v_mfma_f32_16x16x32_bf16 v[20:23], v[170:173], v[202:205], 0
	v_mfma_f32_16x16x32_bf16 v[12:15], v[178:181], v[202:205], 0
	v_mfma_f32_16x16x32_bf16 v[4:7], v[170:173], v[210:213], 0
	v_mfma_f32_16x16x32_bf16 v[0:3], v[178:181], v[210:213], 0
	v_mfma_f32_16x16x32_bf16 v[52:55], v[174:177], v[190:193], v[52:55]
	v_mfma_f32_16x16x32_bf16 v[44:47], v[182:185], v[190:193], v[44:47]
	v_mfma_f32_16x16x32_bf16 v[36:39], v[174:177], v[198:201], v[36:39]
	v_mfma_f32_16x16x32_bf16 v[28:31], v[182:185], v[198:201], v[28:31]
	v_mfma_f32_16x16x32_bf16 v[20:23], v[174:177], v[206:209], v[20:23]
	v_mfma_f32_16x16x32_bf16 v[12:15], v[182:185], v[206:209], v[12:15]
	v_mfma_f32_16x16x32_bf16 v[4:7], v[174:177], v[214:217], v[4:7]
	v_mfma_f32_16x16x32_bf16 v[0:3], v[182:185], v[214:217], v[0:3]
	s_setprio 0
	s_barrier
	s_add_i32 s46, 0, 0x18000
	v_add_u32_e32 v161, s46, v156
	s_add_i32 s47, 0, 0x1c000
	ds_read_b128 v[144:147], v161
	ds_read_b128 v[148:151], v161 offset:1024
	ds_read_b128 v[162:165], v161 offset:2048
	ds_read_b128 v[166:169], v161 offset:3072
	v_add_u32_e32 v161, s47, v156
	ds_read_b128 v[170:173], v161
	ds_read_b128 v[174:177], v161 offset:1024
	ds_read_b128 v[178:181], v161 offset:2048
	ds_read_b128 v[182:185], v161 offset:3072
	s_add_u32 s18, s18, 0xb0000
	s_addc_u32 s19, s19, 0
	s_mov_b32 m0, s28
	v_lshl_add_u64 v[226:227], s[18:19], 0, v[128:129]
	ds_read_b128 v[186:189], v160 offset:32768
	ds_read_b128 v[190:193], v160 offset:33792
	ds_read_b128 v[194:197], v160 offset:34816
	ds_read_b128 v[198:201], v160 offset:35840
	ds_read_b128 v[202:205], v160 offset:36864
	ds_read_b128 v[206:209], v160 offset:37888
	ds_read_b128 v[210:213], v160 offset:38912
	ds_read_b128 v[214:217], v160 offset:39936
	global_load_lds_dwordx4 v[226:227], off
	v_lshl_add_u64 v[226:227], s[18:19], 0, v[132:133]
	s_mov_b32 m0, s29
	s_nop 0
	global_load_lds_dwordx4 v[226:227], off
	s_waitcnt vmcnt(8)
	s_waitcnt lgkmcnt(0)
	s_barrier
	s_setprio 3
	s_waitcnt lgkmcnt(0)
	v_mfma_f32_16x16x32_bf16 v[124:127], v[144:147], v[186:189], v[124:127]
	v_mfma_f32_16x16x32_bf16 v[120:123], v[162:165], v[186:189], v[120:123]
	v_mfma_f32_16x16x32_bf16 v[108:111], v[144:147], v[194:197], v[108:111]
	v_mfma_f32_16x16x32_bf16 v[104:107], v[162:165], v[194:197], v[104:107]
	v_mfma_f32_16x16x32_bf16 v[96:99], v[144:147], v[202:205], v[96:99]
	v_mfma_f32_16x16x32_bf16 v[88:91], v[162:165], v[202:205], v[88:91]
	v_mfma_f32_16x16x32_bf16 v[80:83], v[144:147], v[210:213], v[80:83]
	v_mfma_f32_16x16x32_bf16 v[72:75], v[162:165], v[210:213], v[72:75]
	v_mfma_f32_16x16x32_bf16 v[124:127], v[148:151], v[190:193], v[124:127]
	v_mfma_f32_16x16x32_bf16 v[120:123], v[166:169], v[190:193], v[120:123]
	v_mfma_f32_16x16x32_bf16 v[108:111], v[148:151], v[198:201], v[108:111]
	v_mfma_f32_16x16x32_bf16 v[104:107], v[166:169], v[198:201], v[104:107]
	v_mfma_f32_16x16x32_bf16 v[96:99], v[148:151], v[206:209], v[96:99]
	v_mfma_f32_16x16x32_bf16 v[88:91], v[166:169], v[206:209], v[88:91]
	v_mfma_f32_16x16x32_bf16 v[80:83], v[148:151], v[214:217], v[80:83]
	v_mfma_f32_16x16x32_bf16 v[72:75], v[166:169], v[214:217], v[72:75]
	v_mfma_f32_16x16x32_bf16 v[116:119], v[170:173], v[186:189], v[116:119]
	v_mfma_f32_16x16x32_bf16 v[112:115], v[178:181], v[186:189], v[112:115]
	v_mfma_f32_16x16x32_bf16 v[100:103], v[170:173], v[194:197], v[100:103]
	v_mfma_f32_16x16x32_bf16 v[92:95], v[178:181], v[194:197], v[92:95]
	v_mfma_f32_16x16x32_bf16 v[84:87], v[170:173], v[202:205], v[84:87]
	v_mfma_f32_16x16x32_bf16 v[76:79], v[178:181], v[202:205], v[76:79]
	v_mfma_f32_16x16x32_bf16 v[68:71], v[170:173], v[210:213], v[68:71]
	v_mfma_f32_16x16x32_bf16 v[64:67], v[178:181], v[210:213], v[64:67]
	v_mfma_f32_16x16x32_bf16 v[116:119], v[174:177], v[190:193], v[116:119]
	v_mfma_f32_16x16x32_bf16 v[112:115], v[182:185], v[190:193], v[112:115]
	v_mfma_f32_16x16x32_bf16 v[100:103], v[174:177], v[198:201], v[100:103]
	v_mfma_f32_16x16x32_bf16 v[92:95], v[182:185], v[198:201], v[92:95]
	v_mfma_f32_16x16x32_bf16 v[84:87], v[174:177], v[206:209], v[84:87]
	v_mfma_f32_16x16x32_bf16 v[76:79], v[182:185], v[206:209], v[76:79]
	v_mfma_f32_16x16x32_bf16 v[68:71], v[174:177], v[214:217], v[68:71]
	v_mfma_f32_16x16x32_bf16 v[64:67], v[182:185], v[214:217], v[64:67]
	s_setprio 0
	s_barrier
; #define PG8_STAGE(bufoff, gbase, voff) do { _Pragma("unroll") for (int _i = 0; _i < 2; ++_i) \
;         __builtin_amdgcn_global_load_lds((const unsigned*)((const char*)(gbase) + (voff)[_i]), (LAS unsigned*)(lds + (bufoff) + ldsw + _i * 8192), 16, 0, 0); } while (0)
; #define PG8_LDA(dst, b, h) do { _Pragma("unroll") for (int m = 0; m < 4; ++m) _Pragma("unroll") for (int k = 0; k < 2; ++k) dst[m][k] = *(const LAS bf16x8*)(lds + PG8_SA(b, h) + aoff + m * 2048 + k * 1024); } while (0)
; #define PG8_MMA(ai, bj, At, Bt) do { __builtin_amdgcn_s_setprio(3); _Pragma("unroll") for (int m = 0; m < 4; ++m) _Pragma("unroll") for (int n = 0; n < 2; ++n) _Pragma("unroll") for (int k = 0; k < 2; ++k) \
;         acc[ai][bj][m][n] = __builtin_amdgcn_mfma_f32_16x16x32_bf16(Bt[n][k], At[m][k], acc[ai][bj][m][n], 0, 0, 0); __builtin_amdgcn_s_setprio(0); } while (0)
; #define PG8_WAIT_V(n) asm volatile("s_waitcnt vmcnt(" #n ")" ::: "memory")
; #define PG8_WAIT_L(n) asm volatile("s_waitcnt lgkmcnt(" #n ")" ::: "memory")
; #define PG8_BAR __builtin_amdgcn_s_barrier()
; #define PG8_SCHED __builtin_amdgcn_sched_barrier(0)
; template <class Epi, bool ALIGN_EPI>
; __device__ __forceinline__ void gemm_phase(LAS unsigned char* lds, const Gemm g, const StaticOrder& S, const Epi& E) {
;     ...
;             PG8_LDA(At, 1, 1); PG8_STAGE(PG8_SB(1, 0), b3, voffB); PG8_STAGE(PG8_SB(1, 1), b3 + hstep, voffB); PG8_STAGE(PG8_SA(1, 0), a3, voffA);
;             PG8_WAIT_V(8); PG8_WAIT_L(0); PG8_BAR; PG8_MMA(1, 0, At, B0); PG8_MMA(1, 1, At, B1); PG8_BAR; PG8_SCHED;
	s_add_i32 s18, s46, s23
	v_lshl_add_u64 v[218:219], v[218:219], 0, s[8:9]
	s_mov_b32 m0, s18
	ds_read_b128 v[186:189], v160 offset:49152
	ds_read_b128 v[190:193], v160 offset:50176
	ds_read_b128 v[194:197], v160 offset:51200
	ds_read_b128 v[198:201], v160 offset:52224
	ds_read_b128 v[202:205], v160 offset:53248
	ds_read_b128 v[206:209], v160 offset:54272
	ds_read_b128 v[210:213], v160 offset:55296
	ds_read_b128 v[214:217], v160 offset:56320
	global_load_lds_dwordx4 v[218:219], off
	s_add_i32 m0, s18, 0x2000
	s_add_u32 s16, s16, 0xb0080
	v_lshl_add_u64 v[218:219], v[220:221], 0, s[8:9]
	s_addc_u32 s17, s17, 0
	s_add_i32 s18, s47, s23
	global_load_lds_dwordx4 v[218:219], off
	v_lshl_add_u64 v[218:219], s[16:17], 0, v[130:131]
	s_mov_b32 m0, s18
	s_nop 0
	global_load_lds_dwordx4 v[218:219], off
	v_lshl_add_u64 v[218:219], s[16:17], 0, v[134:135]
	s_add_i32 m0, s18, 0x2000
	s_nop 0
	global_load_lds_dwordx4 v[218:219], off
	v_lshl_add_u64 v[218:219], v[222:223], 0, s[8:9]
	s_mov_b32 m0, s31
	s_nop 0
	global_load_lds_dwordx4 v[218:219], off
	v_lshl_add_u64 v[218:219], v[224:225], 0, s[8:9]
	s_mov_b32 m0, s33
	s_nop 0
	global_load_lds_dwordx4 v[218:219], off
	s_waitcnt vmcnt(8)
	s_waitcnt lgkmcnt(0)
	s_barrier
	s_setprio 3
	s_waitcnt lgkmcnt(0)
	v_mfma_f32_16x16x32_bf16 v[60:63], v[144:147], v[186:189], v[60:63]
	v_mfma_f32_16x16x32_bf16 v[56:59], v[162:165], v[186:189], v[56:59]
	v_mfma_f32_16x16x32_bf16 v[48:51], v[144:147], v[194:197], v[48:51]
	v_mfma_f32_16x16x32_bf16 v[40:43], v[162:165], v[194:197], v[40:43]
	v_mfma_f32_16x16x32_bf16 v[32:35], v[144:147], v[202:205], v[32:35]
	v_mfma_f32_16x16x32_bf16 v[24:27], v[162:165], v[202:205], v[24:27]
	v_mfma_f32_16x16x32_bf16 v[16:19], v[144:147], v[210:213], v[16:19]
	v_mfma_f32_16x16x32_bf16 v[8:11], v[162:165], v[210:213], v[8:11]
	v_mfma_f32_16x16x32_bf16 v[60:63], v[148:151], v[190:193], v[60:63]
	v_mfma_f32_16x16x32_bf16 v[56:59], v[166:169], v[190:193], v[56:59]
	v_mfma_f32_16x16x32_bf16 v[48:51], v[148:151], v[198:201], v[48:51]
	v_mfma_f32_16x16x32_bf16 v[40:43], v[166:169], v[198:201], v[40:43]
	v_mfma_f32_16x16x32_bf16 v[32:35], v[148:151], v[206:209], v[32:35]
	v_mfma_f32_16x16x32_bf16 v[24:27], v[166:169], v[206:209], v[24:27]
	v_mfma_f32_16x16x32_bf16 v[16:19], v[148:151], v[214:217], v[16:19]
	v_mfma_f32_16x16x32_bf16 v[8:11], v[166:169], v[214:217], v[8:11]
	v_mfma_f32_16x16x32_bf16 v[52:55], v[170:173], v[186:189], v[52:55]
	v_mfma_f32_16x16x32_bf16 v[44:47], v[178:181], v[186:189], v[44:47]
	v_mfma_f32_16x16x32_bf16 v[36:39], v[170:173], v[194:197], v[36:39]
	v_mfma_f32_16x16x32_bf16 v[28:31], v[178:181], v[194:197], v[28:31]
	v_mfma_f32_16x16x32_bf16 v[20:23], v[170:173], v[202:205], v[20:23]
	v_mfma_f32_16x16x32_bf16 v[12:15], v[178:181], v[202:205], v[12:15]
	v_mfma_f32_16x16x32_bf16 v[4:7], v[170:173], v[210:213], v[4:7]
	v_mfma_f32_16x16x32_bf16 v[0:3], v[178:181], v[210:213], v[0:3]
	v_mfma_f32_16x16x32_bf16 v[52:55], v[174:177], v[190:193], v[52:55]
	v_mfma_f32_16x16x32_bf16 v[44:47], v[182:185], v[190:193], v[44:47]
	v_mfma_f32_16x16x32_bf16 v[36:39], v[174:177], v[198:201], v[36:39]
	v_mfma_f32_16x16x32_bf16 v[28:31], v[182:185], v[198:201], v[28:31]
	v_mfma_f32_16x16x32_bf16 v[20:23], v[174:177], v[206:209], v[20:23]
	v_mfma_f32_16x16x32_bf16 v[12:15], v[182:185], v[206:209], v[12:15]
	v_mfma_f32_16x16x32_bf16 v[4:7], v[174:177], v[214:217], v[4:7]
	v_mfma_f32_16x16x32_bf16 v[0:3], v[182:185], v[214:217], v[0:3]
	s_setprio 0
	s_barrier
	s_add_i32 s45, s45, 2
	s_add_u32 s14, s14, 0x100
	s_addc_u32 s15, s15, 0
	s_add_u32 s43, s43, 0x100
	s_addc_u32 s44, s44, 0
